# + k5: every s_setprio in the GEMM K-loops removed (probe on in-proj+SwiGLU x3: 7204 vs 7267 us, about -1.1% on those phases)
# speedup vs baseline: 1.0098x; 1.0064x over previous
; #define PG8_STAGE(bufoff, gbase, voff) do { _Pragma("unroll") for (int _i = 0; _i < 2; ++_i) \
;         __builtin_amdgcn_global_load_lds((const unsigned*)((const char*)(gbase) + (voff)[_i]), (PG8_LAS unsigned*)(lds + (bufoff) + ldsw + _i * 8192), 16, 0, 0); } while (0)
; #define PG8_LDA(dst, b, h) do { _Pragma("unroll") for (int m = 0; m < 4; ++m) _Pragma("unroll") for (int k = 0; k < 2; ++k) dst[m][k] = *(const PG8_LAS bf16x8*)(lds + PG8_SA(b, h) + aoff + m * 2048 + k * 1024); } while (0)
; #define PG8_LDB(dst, b, h) do { _Pragma("unroll") for (int n = 0; n < 2; ++n) _Pragma("unroll") for (int k = 0; k < 2; ++k) dst[n][k] = *(const PG8_LAS bf16x8*)(lds + PG8_SB(b, h) + boff + n * 2048 + k * 1024); } while (0)
; #define PG8_MMA(ai, bj, At, Bt) do { __builtin_amdgcn_s_setprio(1); _Pragma("unroll") for (int m = 0; m < 4; ++m) _Pragma("unroll") for (int n = 0; n < 2; ++n) _Pragma("unroll") for (int k = 0; k < 2; ++k) \
;         acc[ai][bj][m][n] = __builtin_amdgcn_mfma_f32_16x16x32_bf16(Bt[n][k], At[m][k], acc[ai][bj][m][n], 0, 0, 0); __builtin_amdgcn_s_setprio(0); } while (0)
; #define PG8_WAIT_V(n) asm volatile("s_waitcnt vmcnt(" #n ")" ::: "memory")
; #define PG8_WAIT_L(n) asm volatile("s_waitcnt lgkmcnt(" #n ")" ::: "memory")
; #define PG8_BAR __builtin_amdgcn_s_barrier()
; #define PG8_SCHED __builtin_amdgcn_sched_barrier(0)
; template <class Epi, class Sched, bool ALIGN_EPI = false, bool SP2 = false>
; __device__ __forceinline__ void gemm_phase(PG8_LAS unsigned char* lds, const Gemm g, const Sched& S, const Epi& E, const int tid) {
;     ...
;             PG8_LDB(B0, 0, 0); PG8_LDB(B1, 0, 1); PG8_SCHED; PG8_LDA(At, 0, 0); PG8_STAGE(PG8_SA(1, 1), a1 + hstep, voffA);
;             PG8_WAIT_V(8); PG8_WAIT_L(0); PG8_BAR; PG8_MMA(0, 0, At, B0); PG8_MMA(0, 1, At, B1); PG8_BAR; PG8_SCHED;
;             PG8_LDA(At, 0, 1); PG8_STAGE(PG8_SB(0, 0), b2, voffB); PG8_STAGE(PG8_SB(0, 1), b2 + hstep, voffB); PG8_STAGE(PG8_SA(0, 0), a2, voffA);
;             PG8_WAIT_V(8); PG8_WAIT_L(0); PG8_BAR; PG8_MMA(1, 0, At, B0); PG8_MMA(1, 1, At, B1); PG8_BAR; PG8_SCHED;
.LBB0_38:
	v_add_u32_e32 v138, 0x10000, v140
	ds_read_b128 v[142:145], v138
	ds_read_b128 v[146:149], v138 offset:1024
	ds_read_b128 v[150:153], v138 offset:2048
	ds_read_b128 v[154:157], v138 offset:3072
	v_add_u32_e32 v138, 0x14000, v140
	ds_read_b128 v[158:161], v138
	ds_read_b128 v[162:165], v138 offset:1024
	ds_read_b128 v[166:169], v138 offset:2048
	ds_read_b128 v[170:173], v138 offset:3072
	s_add_u32 s58, s44, 0xfffc0080
	s_addc_u32 s59, s45, -1
	s_add_i32 s73, 0, 0x10000
	s_cmp_eq_u32 s72, 12
	s_cselect_b32 s79, s17, s59
	s_cselect_b32 s78, s60, s58
	s_cselect_b32 s59, s15, s71
	s_cselect_b32 s58, s70, s62
	s_add_i32 s76, 0, 0x14000
	v_lshl_add_u64 v[138:139], s[44:45], 0, v[134:135]
	s_add_i32 m0, s38, 0xc000
	ds_read_b128 v[174:177], v141
	ds_read_b128 v[178:181], v141 offset:1024
	ds_read_b128 v[182:185], v141 offset:2048
	ds_read_b128 v[186:189], v141 offset:3072
	ds_read_b128 v[212:215], v141 offset:4096
	ds_read_b128 v[216:219], v141 offset:5120
	ds_read_b128 v[232:235], v141 offset:6144
	ds_read_b128 v[236:239], v141 offset:7168
	global_load_lds_dwordx4 v[138:139], off
	v_lshl_add_u64 v[138:139], s[44:45], 0, v[136:137]
	s_add_i32 m0, s38, 0xe000
	s_nop 0
	global_load_lds_dwordx4 v[138:139], off
	s_waitcnt vmcnt(8)
	s_waitcnt lgkmcnt(0)
	s_barrier
	s_waitcnt lgkmcnt(0)
	v_mfma_f32_16x16x32_bf16 v[124:127], v[142:145], v[174:177], v[124:127]
	v_mfma_f32_16x16x32_bf16 v[120:123], v[150:153], v[174:177], v[120:123]
	v_mfma_f32_16x16x32_bf16 v[108:111], v[142:145], v[182:185], v[108:111]
	v_mfma_f32_16x16x32_bf16 v[104:107], v[150:153], v[182:185], v[104:107]
	v_mfma_f32_16x16x32_bf16 v[92:95], v[142:145], v[212:215], v[92:95]
	v_mfma_f32_16x16x32_bf16 v[88:91], v[150:153], v[212:215], v[88:91]
	v_mfma_f32_16x16x32_bf16 v[76:79], v[142:145], v[232:235], v[76:79]
	v_mfma_f32_16x16x32_bf16 v[72:75], v[150:153], v[232:235], v[72:75]
	v_mfma_f32_16x16x32_bf16 v[124:127], v[146:149], v[178:181], v[124:127]
	v_mfma_f32_16x16x32_bf16 v[120:123], v[154:157], v[178:181], v[120:123]
	v_mfma_f32_16x16x32_bf16 v[108:111], v[146:149], v[186:189], v[108:111]
	v_mfma_f32_16x16x32_bf16 v[104:107], v[154:157], v[186:189], v[104:107]
	v_mfma_f32_16x16x32_bf16 v[92:95], v[146:149], v[216:219], v[92:95]
	v_mfma_f32_16x16x32_bf16 v[88:91], v[154:157], v[216:219], v[88:91]
	v_mfma_f32_16x16x32_bf16 v[76:79], v[146:149], v[236:239], v[76:79]
	v_mfma_f32_16x16x32_bf16 v[72:75], v[154:157], v[236:239], v[72:75]
	v_mfma_f32_16x16x32_bf16 v[116:119], v[158:161], v[174:177], v[116:119]
	v_mfma_f32_16x16x32_bf16 v[112:115], v[166:169], v[174:177], v[112:115]
	v_mfma_f32_16x16x32_bf16 v[100:103], v[158:161], v[182:185], v[100:103]
	v_mfma_f32_16x16x32_bf16 v[96:99], v[166:169], v[182:185], v[96:99]
	v_mfma_f32_16x16x32_bf16 v[84:87], v[158:161], v[212:215], v[84:87]
	v_mfma_f32_16x16x32_bf16 v[80:83], v[166:169], v[212:215], v[80:83]
	v_mfma_f32_16x16x32_bf16 v[68:71], v[158:161], v[232:235], v[68:71]
	v_mfma_f32_16x16x32_bf16 v[64:67], v[166:169], v[232:235], v[64:67]
	v_mfma_f32_16x16x32_bf16 v[116:119], v[162:165], v[178:181], v[116:119]
	v_mfma_f32_16x16x32_bf16 v[112:115], v[170:173], v[178:181], v[112:115]
	v_mfma_f32_16x16x32_bf16 v[100:103], v[162:165], v[186:189], v[100:103]
	v_mfma_f32_16x16x32_bf16 v[96:99], v[170:173], v[186:189], v[96:99]
	v_mfma_f32_16x16x32_bf16 v[84:87], v[162:165], v[216:219], v[84:87]
	v_mfma_f32_16x16x32_bf16 v[80:83], v[170:173], v[216:219], v[80:83]
	v_mfma_f32_16x16x32_bf16 v[68:71], v[162:165], v[236:239], v[68:71]
	v_mfma_f32_16x16x32_bf16 v[64:67], v[170:173], v[236:239], v[64:67]
	s_barrier
	s_add_i32 s73, s73, s35
	v_lshl_add_u64 v[138:139], s[58:59], 0, v[192:193]
	s_mov_b32 m0, s73
	ds_read_b128 v[174:177], v141 offset:16384
	ds_read_b128 v[178:181], v141 offset:17408
	ds_read_b128 v[182:185], v141 offset:18432
	ds_read_b128 v[186:189], v141 offset:19456
	ds_read_b128 v[212:215], v141 offset:20480
	ds_read_b128 v[216:219], v141 offset:21504
	ds_read_b128 v[232:235], v141 offset:22528
	ds_read_b128 v[236:239], v141 offset:23552
	global_load_lds_dwordx4 v[138:139], off
	s_add_i32 m0, s73, 0x2000
	s_add_u32 s74, s58, 0x40000
	v_lshl_add_u64 v[190:191], s[58:59], 0, v[132:133]
	s_addc_u32 s75, s59, 0
	s_add_i32 s73, s76, s35
	global_load_lds_dwordx4 v[190:191], off
	v_lshl_add_u64 v[194:195], s[74:75], 0, v[192:193]
	s_mov_b32 m0, s73
	v_lshl_add_u64 v[196:197], s[78:79], 0, v[130:131]
	global_load_lds_dwordx4 v[194:195], off
	v_lshl_add_u64 v[194:195], s[74:75], 0, v[132:133]
	s_add_i32 m0, s73, 0x2000
	s_nop 0
	global_load_lds_dwordx4 v[194:195], off
	v_lshl_add_u64 v[194:195], s[78:79], 0, v[128:129]
	s_mov_b32 m0, s38
	s_nop 0
	global_load_lds_dwordx4 v[194:195], off
	s_mov_b32 m0, s40
	s_nop 0
	global_load_lds_dwordx4 v[196:197], off
	s_waitcnt vmcnt(8)
	s_waitcnt lgkmcnt(0)
	s_barrier
; #define PG8_STAGE(bufoff, gbase, voff) do { _Pragma("unroll") for (int _i = 0; _i < 2; ++_i) \
;         __builtin_amdgcn_global_load_lds((const unsigned*)((const char*)(gbase) + (voff)[_i]), (PG8_LAS unsigned*)(lds + (bufoff) + ldsw + _i * 8192), 16, 0, 0); } while (0)
; #define PG8_LDA(dst, b, h) do { _Pragma("unroll") for (int m = 0; m < 4; ++m) _Pragma("unroll") for (int k = 0; k < 2; ++k) dst[m][k] = *(const PG8_LAS bf16x8*)(lds + PG8_SA(b, h) + aoff + m * 2048 + k * 1024); } while (0)
; #define PG8_LDB(dst, b, h) do { _Pragma("unroll") for (int n = 0; n < 2; ++n) _Pragma("unroll") for (int k = 0; k < 2; ++k) dst[n][k] = *(const PG8_LAS bf16x8*)(lds + PG8_SB(b, h) + boff + n * 2048 + k * 1024); } while (0)
; #define PG8_MMA(ai, bj, At, Bt) do { __builtin_amdgcn_s_setprio(1); _Pragma("unroll") for (int m = 0; m < 4; ++m) _Pragma("unroll") for (int n = 0; n < 2; ++n) _Pragma("unroll") for (int k = 0; k < 2; ++k) \
;         acc[ai][bj][m][n] = __builtin_amdgcn_mfma_f32_16x16x32_bf16(Bt[n][k], At[m][k], acc[ai][bj][m][n], 0, 0, 0); __builtin_amdgcn_s_setprio(0); } while (0)
; #define PG8_WAIT_V(n) asm volatile("s_waitcnt vmcnt(" #n ")" ::: "memory")
; #define PG8_WAIT_L(n) asm volatile("s_waitcnt lgkmcnt(" #n ")" ::: "memory")
; #define PG8_BAR __builtin_amdgcn_s_barrier()
; #define PG8_SCHED __builtin_amdgcn_sched_barrier(0)
; template <class Epi, class Sched, bool ALIGN_EPI = false, bool SP2 = false>
; __device__ __forceinline__ void gemm_phase(PG8_LAS unsigned char* lds, const Gemm g, const Sched& S, const Epi& E, const int tid) {
;     ...
;             PG8_WAIT_V(8); PG8_WAIT_L(0); PG8_BAR; PG8_MMA(1, 0, At, B0); PG8_MMA(1, 1, At, B1); PG8_BAR; PG8_SCHED;
;             PG8_LDB(B0, 1, 0); PG8_LDB(B1, 1, 1); PG8_SCHED; PG8_LDA(At, 1, 0); PG8_STAGE(PG8_SA(0, 1), a2 + hstep, voffA);
;             PG8_WAIT_V(8); PG8_WAIT_L(0); PG8_BAR; PG8_MMA(0, 0, At, B0); PG8_MMA(0, 1, At, B1); PG8_BAR; PG8_SCHED;
	s_waitcnt lgkmcnt(0)
	v_mfma_f32_16x16x32_bf16 v[60:63], v[142:145], v[174:177], v[60:63]
	v_mfma_f32_16x16x32_bf16 v[56:59], v[150:153], v[174:177], v[56:59]
	v_mfma_f32_16x16x32_bf16 v[44:47], v[142:145], v[182:185], v[44:47]
	v_mfma_f32_16x16x32_bf16 v[40:43], v[150:153], v[182:185], v[40:43]
	v_mfma_f32_16x16x32_bf16 v[28:31], v[142:145], v[212:215], v[28:31]
	v_mfma_f32_16x16x32_bf16 v[24:27], v[150:153], v[212:215], v[24:27]
	v_mfma_f32_16x16x32_bf16 v[12:15], v[142:145], v[232:235], v[12:15]
	v_mfma_f32_16x16x32_bf16 v[8:11], v[150:153], v[232:235], v[8:11]
	v_mfma_f32_16x16x32_bf16 v[60:63], v[146:149], v[178:181], v[60:63]
	v_mfma_f32_16x16x32_bf16 v[56:59], v[154:157], v[178:181], v[56:59]
	v_mfma_f32_16x16x32_bf16 v[44:47], v[146:149], v[186:189], v[44:47]
	v_mfma_f32_16x16x32_bf16 v[40:43], v[154:157], v[186:189], v[40:43]
	v_mfma_f32_16x16x32_bf16 v[28:31], v[146:149], v[216:219], v[28:31]
	v_mfma_f32_16x16x32_bf16 v[24:27], v[154:157], v[216:219], v[24:27]
	v_mfma_f32_16x16x32_bf16 v[12:15], v[146:149], v[236:239], v[12:15]
	v_mfma_f32_16x16x32_bf16 v[8:11], v[154:157], v[236:239], v[8:11]
	v_mfma_f32_16x16x32_bf16 v[52:55], v[158:161], v[174:177], v[52:55]
	v_mfma_f32_16x16x32_bf16 v[48:51], v[166:169], v[174:177], v[48:51]
	v_mfma_f32_16x16x32_bf16 v[36:39], v[158:161], v[182:185], v[36:39]
	v_mfma_f32_16x16x32_bf16 v[32:35], v[166:169], v[182:185], v[32:35]
	v_mfma_f32_16x16x32_bf16 v[20:23], v[158:161], v[212:215], v[20:23]
	v_mfma_f32_16x16x32_bf16 v[16:19], v[166:169], v[212:215], v[16:19]
	v_mfma_f32_16x16x32_bf16 v[4:7], v[158:161], v[232:235], v[4:7]
	v_mfma_f32_16x16x32_bf16 v[0:3], v[166:169], v[232:235], v[0:3]
	v_mfma_f32_16x16x32_bf16 v[52:55], v[162:165], v[178:181], v[52:55]
	v_mfma_f32_16x16x32_bf16 v[48:51], v[170:173], v[178:181], v[48:51]
	v_mfma_f32_16x16x32_bf16 v[36:39], v[162:165], v[186:189], v[36:39]
	v_mfma_f32_16x16x32_bf16 v[32:35], v[170:173], v[186:189], v[32:35]
	v_mfma_f32_16x16x32_bf16 v[20:23], v[162:165], v[216:219], v[20:23]
	v_mfma_f32_16x16x32_bf16 v[16:19], v[170:173], v[216:219], v[16:19]
	v_mfma_f32_16x16x32_bf16 v[4:7], v[162:165], v[236:239], v[4:7]
	v_mfma_f32_16x16x32_bf16 v[0:3], v[170:173], v[236:239], v[0:3]
	s_barrier
	s_add_i32 s73, 0, 0x18000
	s_add_i32 s76, 0, 0x1c000
	v_add_u32_e32 v154, s73, v140
	v_add_u32_e32 v170, s76, v140
	ds_read_b128 v[142:145], v154
	ds_read_b128 v[146:149], v154 offset:1024
	ds_read_b128 v[150:153], v154 offset:2048
	ds_read_b128 v[154:157], v154 offset:3072
	ds_read_b128 v[158:161], v170
	ds_read_b128 v[162:165], v170 offset:1024
	ds_read_b128 v[166:169], v170 offset:2048
	ds_read_b128 v[170:173], v170 offset:3072
	s_add_u32 s74, s78, 0x40000
	s_addc_u32 s75, s79, 0
	s_mov_b32 m0, s41
	v_lshl_add_u64 v[202:203], s[74:75], 0, v[128:129]
	ds_read_b128 v[174:177], v141 offset:32768
	ds_read_b128 v[178:181], v141 offset:33792
	ds_read_b128 v[182:185], v141 offset:34816
	ds_read_b128 v[186:189], v141 offset:35840
	ds_read_b128 v[212:215], v141 offset:36864
	ds_read_b128 v[216:219], v141 offset:37888
	ds_read_b128 v[232:235], v141 offset:38912
	ds_read_b128 v[236:239], v141 offset:39936
	global_load_lds_dwordx4 v[202:203], off
	v_lshl_add_u64 v[202:203], s[74:75], 0, v[130:131]
	s_mov_b32 m0, s46
	s_nop 0
	global_load_lds_dwordx4 v[202:203], off
	s_waitcnt vmcnt(8)
	s_waitcnt lgkmcnt(0)
	s_barrier
	s_waitcnt lgkmcnt(0)
	v_mfma_f32_16x16x32_bf16 v[124:127], v[142:145], v[174:177], v[124:127]
	v_mfma_f32_16x16x32_bf16 v[120:123], v[150:153], v[174:177], v[120:123]
	v_mfma_f32_16x16x32_bf16 v[108:111], v[142:145], v[182:185], v[108:111]
	v_mfma_f32_16x16x32_bf16 v[104:107], v[150:153], v[182:185], v[104:107]
	v_mfma_f32_16x16x32_bf16 v[92:95], v[142:145], v[212:215], v[92:95]
	v_mfma_f32_16x16x32_bf16 v[88:91], v[150:153], v[212:215], v[88:91]
	v_mfma_f32_16x16x32_bf16 v[76:79], v[142:145], v[232:235], v[76:79]
	v_mfma_f32_16x16x32_bf16 v[72:75], v[150:153], v[232:235], v[72:75]
	v_mfma_f32_16x16x32_bf16 v[124:127], v[146:149], v[178:181], v[124:127]
	v_mfma_f32_16x16x32_bf16 v[120:123], v[154:157], v[178:181], v[120:123]
	v_mfma_f32_16x16x32_bf16 v[108:111], v[146:149], v[186:189], v[108:111]
	v_mfma_f32_16x16x32_bf16 v[104:107], v[154:157], v[186:189], v[104:107]
	v_mfma_f32_16x16x32_bf16 v[92:95], v[146:149], v[216:219], v[92:95]
	v_mfma_f32_16x16x32_bf16 v[88:91], v[154:157], v[216:219], v[88:91]
	v_mfma_f32_16x16x32_bf16 v[76:79], v[146:149], v[236:239], v[76:79]
	v_mfma_f32_16x16x32_bf16 v[72:75], v[154:157], v[236:239], v[72:75]
	v_mfma_f32_16x16x32_bf16 v[116:119], v[158:161], v[174:177], v[116:119]
	v_mfma_f32_16x16x32_bf16 v[112:115], v[166:169], v[174:177], v[112:115]
	v_mfma_f32_16x16x32_bf16 v[100:103], v[158:161], v[182:185], v[100:103]
	v_mfma_f32_16x16x32_bf16 v[96:99], v[166:169], v[182:185], v[96:99]
	v_mfma_f32_16x16x32_bf16 v[84:87], v[158:161], v[212:215], v[84:87]
	v_mfma_f32_16x16x32_bf16 v[80:83], v[166:169], v[212:215], v[80:83]
	v_mfma_f32_16x16x32_bf16 v[68:71], v[158:161], v[232:235], v[68:71]
	v_mfma_f32_16x16x32_bf16 v[64:67], v[166:169], v[232:235], v[64:67]
	v_mfma_f32_16x16x32_bf16 v[116:119], v[162:165], v[178:181], v[116:119]
	v_mfma_f32_16x16x32_bf16 v[112:115], v[170:173], v[178:181], v[112:115]
	v_mfma_f32_16x16x32_bf16 v[100:103], v[162:165], v[186:189], v[100:103]
	v_mfma_f32_16x16x32_bf16 v[96:99], v[170:173], v[186:189], v[96:99]
	v_mfma_f32_16x16x32_bf16 v[84:87], v[162:165], v[216:219], v[84:87]
	v_mfma_f32_16x16x32_bf16 v[80:83], v[170:173], v[216:219], v[80:83]
	v_mfma_f32_16x16x32_bf16 v[68:71], v[162:165], v[236:239], v[68:71]
	v_mfma_f32_16x16x32_bf16 v[64:67], v[170:173], v[236:239], v[64:67]
	s_barrier
; #define PG8_STAGE(bufoff, gbase, voff) do { _Pragma("unroll") for (int _i = 0; _i < 2; ++_i) \
;         __builtin_amdgcn_global_load_lds((const unsigned*)((const char*)(gbase) + (voff)[_i]), (PG8_LAS unsigned*)(lds + (bufoff) + ldsw + _i * 8192), 16, 0, 0); } while (0)
; #define PG8_LDA(dst, b, h) do { _Pragma("unroll") for (int m = 0; m < 4; ++m) _Pragma("unroll") for (int k = 0; k < 2; ++k) dst[m][k] = *(const PG8_LAS bf16x8*)(lds + PG8_SA(b, h) + aoff + m * 2048 + k * 1024); } while (0)
; #define PG8_MMA(ai, bj, At, Bt) do { __builtin_amdgcn_s_setprio(1); _Pragma("unroll") for (int m = 0; m < 4; ++m) _Pragma("unroll") for (int n = 0; n < 2; ++n) _Pragma("unroll") for (int k = 0; k < 2; ++k) \
;         acc[ai][bj][m][n] = __builtin_amdgcn_mfma_f32_16x16x32_bf16(Bt[n][k], At[m][k], acc[ai][bj][m][n], 0, 0, 0); __builtin_amdgcn_s_setprio(0); } while (0)
; #define PG8_WAIT_V(n) asm volatile("s_waitcnt vmcnt(" #n ")" ::: "memory")
; #define PG8_WAIT_L(n) asm volatile("s_waitcnt lgkmcnt(" #n ")" ::: "memory")
; #define PG8_BAR __builtin_amdgcn_s_barrier()
; #define PG8_SCHED __builtin_amdgcn_sched_barrier(0)
; template <class Epi, class Sched, bool ALIGN_EPI = false, bool SP2 = false>
; __device__ __forceinline__ void gemm_phase(PG8_LAS unsigned char* lds, const Gemm g, const Sched& S, const Epi& E, const int tid) {
;     ...
;             PG8_LDA(At, 1, 1); PG8_STAGE(PG8_SB(1, 0), b3, voffB); PG8_STAGE(PG8_SB(1, 1), b3 + hstep, voffB); PG8_STAGE(PG8_SA(1, 0), a3, voffA);
;             PG8_WAIT_V(8); PG8_WAIT_L(0); PG8_BAR; PG8_MMA(1, 0, At, B0); PG8_MMA(1, 1, At, B1); PG8_BAR; PG8_SCHED;
;     ...
;         if constexpr (ALIGN_EPI) { if (wr == 0) PG8_BAR; }
	s_add_i32 s73, s73, s35
	v_lshl_add_u64 v[138:139], v[138:139], 0, s[36:37]
	s_mov_b32 m0, s73
	ds_read_b128 v[174:177], v141 offset:49152
	ds_read_b128 v[178:181], v141 offset:50176
	ds_read_b128 v[182:185], v141 offset:51200
	ds_read_b128 v[186:189], v141 offset:52224
	ds_read_b128 v[212:215], v141 offset:53248
	ds_read_b128 v[216:219], v141 offset:54272
	ds_read_b128 v[232:235], v141 offset:55296
	ds_read_b128 v[236:239], v141 offset:56320
	global_load_lds_dwordx4 v[138:139], off
	s_add_i32 m0, s73, 0x2000
	s_add_u32 s58, s58, 0x40080
	v_lshl_add_u64 v[138:139], v[190:191], 0, s[36:37]
	s_addc_u32 s59, s59, 0
	s_add_i32 s73, s76, s35
	global_load_lds_dwordx4 v[138:139], off
	v_lshl_add_u64 v[138:139], s[58:59], 0, v[192:193]
	s_mov_b32 m0, s73
	s_nop 0
	global_load_lds_dwordx4 v[138:139], off
	v_lshl_add_u64 v[138:139], s[58:59], 0, v[132:133]
	s_add_i32 m0, s73, 0x2000
	s_nop 0
	global_load_lds_dwordx4 v[138:139], off
	v_lshl_add_u64 v[138:139], v[194:195], 0, s[36:37]
	s_mov_b32 m0, s47
	s_nop 0
	global_load_lds_dwordx4 v[138:139], off
	v_lshl_add_u64 v[138:139], v[196:197], 0, s[36:37]
	s_mov_b32 m0, s53
	s_nop 0
	global_load_lds_dwordx4 v[138:139], off
	s_add_i32 s72, s72, 2
	s_add_u32 s44, s44, 0x100
	s_addc_u32 s45, s45, 0
	s_add_u32 s62, s62, 0x100
	s_addc_u32 s71, s71, 0
	s_cmp_gt_u32 s72, 13
	s_waitcnt vmcnt(8)
	s_waitcnt lgkmcnt(0)
	s_barrier
	s_waitcnt lgkmcnt(0)
	v_mfma_f32_16x16x32_bf16 v[60:63], v[142:145], v[174:177], v[60:63]
	v_mfma_f32_16x16x32_bf16 v[56:59], v[150:153], v[174:177], v[56:59]
	v_mfma_f32_16x16x32_bf16 v[44:47], v[142:145], v[182:185], v[44:47]
	v_mfma_f32_16x16x32_bf16 v[40:43], v[150:153], v[182:185], v[40:43]
	v_mfma_f32_16x16x32_bf16 v[28:31], v[142:145], v[212:215], v[28:31]
	v_mfma_f32_16x16x32_bf16 v[24:27], v[150:153], v[212:215], v[24:27]
	v_mfma_f32_16x16x32_bf16 v[12:15], v[142:145], v[232:235], v[12:15]
	v_mfma_f32_16x16x32_bf16 v[8:11], v[150:153], v[232:235], v[8:11]
	v_mfma_f32_16x16x32_bf16 v[60:63], v[146:149], v[178:181], v[60:63]
	v_mfma_f32_16x16x32_bf16 v[56:59], v[154:157], v[178:181], v[56:59]
	v_mfma_f32_16x16x32_bf16 v[44:47], v[146:149], v[186:189], v[44:47]
	v_mfma_f32_16x16x32_bf16 v[40:43], v[154:157], v[186:189], v[40:43]
	v_mfma_f32_16x16x32_bf16 v[28:31], v[146:149], v[216:219], v[28:31]
	v_mfma_f32_16x16x32_bf16 v[24:27], v[154:157], v[216:219], v[24:27]
	v_mfma_f32_16x16x32_bf16 v[12:15], v[146:149], v[236:239], v[12:15]
	v_mfma_f32_16x16x32_bf16 v[8:11], v[154:157], v[236:239], v[8:11]
	v_mfma_f32_16x16x32_bf16 v[52:55], v[158:161], v[174:177], v[52:55]
	v_mfma_f32_16x16x32_bf16 v[48:51], v[166:169], v[174:177], v[48:51]
	v_mfma_f32_16x16x32_bf16 v[36:39], v[158:161], v[182:185], v[36:39]
	v_mfma_f32_16x16x32_bf16 v[32:35], v[166:169], v[182:185], v[32:35]
	v_mfma_f32_16x16x32_bf16 v[20:23], v[158:161], v[212:215], v[20:23]
	v_mfma_f32_16x16x32_bf16 v[16:19], v[166:169], v[212:215], v[16:19]
	v_mfma_f32_16x16x32_bf16 v[4:7], v[158:161], v[232:235], v[4:7]
	v_mfma_f32_16x16x32_bf16 v[0:3], v[166:169], v[232:235], v[0:3]
	v_mfma_f32_16x16x32_bf16 v[52:55], v[162:165], v[178:181], v[52:55]
	v_mfma_f32_16x16x32_bf16 v[48:51], v[170:173], v[178:181], v[48:51]
	v_mfma_f32_16x16x32_bf16 v[36:39], v[162:165], v[186:189], v[36:39]
	v_mfma_f32_16x16x32_bf16 v[32:35], v[170:173], v[186:189], v[32:35]
	v_mfma_f32_16x16x32_bf16 v[20:23], v[162:165], v[216:219], v[20:23]
	v_mfma_f32_16x16x32_bf16 v[16:19], v[170:173], v[216:219], v[16:19]
	v_mfma_f32_16x16x32_bf16 v[4:7], v[162:165], v[236:239], v[4:7]
	v_mfma_f32_16x16x32_bf16 v[0:3], v[170:173], v[236:239], v[0:3]
	s_barrier
	s_cbranch_scc0 .LBB0_38
	s_and_b64 vcc, exec, s[10:11]
	s_mov_b64 s[72:73], 0x20000
	s_cbranch_vccz .LBB0_41
	s_barrier

; #define PG8_STAGE(bufoff, gbase, voff) do { _Pragma("unroll") for (int _i = 0; _i < 2; ++_i) \
;         __builtin_amdgcn_global_load_lds((const unsigned*)((const char*)(gbase) + (voff)[_i]), (PG8_LAS unsigned*)(lds + (bufoff) + ldsw + _i * 8192), 16, 0, 0); } while (0)
; #define PG8_LDA(dst, b, h) do { _Pragma("unroll") for (int m = 0; m < 4; ++m) _Pragma("unroll") for (int k = 0; k < 2; ++k) dst[m][k] = *(const PG8_LAS bf16x8*)(lds + PG8_SA(b, h) + aoff + m * 2048 + k * 1024); } while (0)
; #define PG8_LDB(dst, b, h) do { _Pragma("unroll") for (int n = 0; n < 2; ++n) _Pragma("unroll") for (int k = 0; k < 2; ++k) dst[n][k] = *(const PG8_LAS bf16x8*)(lds + PG8_SB(b, h) + boff + n * 2048 + k * 1024); } while (0)
; #define PG8_MMA(ai, bj, At, Bt) do { __builtin_amdgcn_s_setprio(1); _Pragma("unroll") for (int m = 0; m < 4; ++m) _Pragma("unroll") for (int n = 0; n < 2; ++n) _Pragma("unroll") for (int k = 0; k < 2; ++k) \
;         acc[ai][bj][m][n] = __builtin_amdgcn_mfma_f32_16x16x32_bf16(Bt[n][k], At[m][k], acc[ai][bj][m][n], 0, 0, 0); __builtin_amdgcn_s_setprio(0); } while (0)
; #define PG8_WAIT_V(n) asm volatile("s_waitcnt vmcnt(" #n ")" ::: "memory")
; #define PG8_WAIT_L(n) asm volatile("s_waitcnt lgkmcnt(" #n ")" ::: "memory")
; #define PG8_BAR __builtin_amdgcn_s_barrier()
; #define PG8_SCHED __builtin_amdgcn_sched_barrier(0)
; template <class Epi, class Sched, bool ALIGN_EPI = false, bool SP2 = false>
; __device__ __forceinline__ void gemm_phase(PG8_LAS unsigned char* lds, const Gemm g, const Sched& S, const Epi& E, const int tid) {
;     ...
;             PG8_LDB(B0, 0, 0); PG8_LDB(B1, 0, 1); PG8_SCHED; PG8_LDA(At, 0, 0); PG8_STAGE(PG8_SA(1, 1), a1 + hstep, voffA);
;             PG8_WAIT_V(8); PG8_WAIT_L(0); PG8_BAR; PG8_MMA(0, 0, At, B0); PG8_MMA(0, 1, At, B1); PG8_BAR; PG8_SCHED;
;             PG8_LDA(At, 0, 1); PG8_STAGE(PG8_SB(0, 0), b2, voffB); PG8_STAGE(PG8_SB(0, 1), b2 + hstep, voffB); PG8_STAGE(PG8_SA(0, 0), a2, voffA);
;             PG8_WAIT_V(8); PG8_WAIT_L(0); PG8_BAR; PG8_MMA(1, 0, At, B0); PG8_MMA(1, 1, At, B1); PG8_BAR; PG8_SCHED;
.LBB0_99:
	v_add_u32_e32 v152, 0x10000, v138
	v_add_u32_e32 v168, 0x14000, v138
	ds_read_b128 v[140:143], v152
	ds_read_b128 v[144:147], v152 offset:1024
	ds_read_b128 v[148:151], v152 offset:2048
	ds_read_b128 v[152:155], v152 offset:3072
	ds_read_b128 v[156:159], v168
	ds_read_b128 v[160:163], v168 offset:1024
	ds_read_b128 v[164:167], v168 offset:2048
	ds_read_b128 v[168:171], v168 offset:3072
	s_add_u32 s20, s18, 0x100
	s_addc_u32 s21, s19, 0
	s_add_i32 s73, 0, 0x10000
	s_cmp_eq_u32 s72, 40
	s_cselect_b32 s45, s9, s21
	s_cselect_b32 s44, s8, s20
	s_cselect_b32 s23, s17, s71
	s_cselect_b32 s22, s16, s62
	s_add_i32 s74, 0, 0x14000
	v_lshl_add_u64 v[194:195], s[18:19], 0, v[134:135]
	s_add_i32 m0, s38, 0xc000
	ds_read_b128 v[172:175], v139
	ds_read_b128 v[176:179], v139 offset:1024
	ds_read_b128 v[180:183], v139 offset:2048
	ds_read_b128 v[184:187], v139 offset:3072
	ds_read_b128 v[188:191], v139 offset:4096
	ds_read_b128 v[212:215], v139 offset:5120
	ds_read_b128 v[216:219], v139 offset:6144
	ds_read_b128 v[232:235], v139 offset:7168
	global_load_lds_dwordx4 v[194:195], off
	v_lshl_add_u64 v[194:195], s[18:19], 0, v[136:137]
	s_add_i32 m0, s38, 0xe000
	s_nop 0
	global_load_lds_dwordx4 v[194:195], off
	s_waitcnt vmcnt(8)
	s_waitcnt lgkmcnt(0)
	s_barrier
	s_waitcnt lgkmcnt(0)
	v_mfma_f32_16x16x32_bf16 v[124:127], v[140:143], v[172:175], v[124:127]
	v_mfma_f32_16x16x32_bf16 v[120:123], v[148:151], v[172:175], v[120:123]
	v_mfma_f32_16x16x32_bf16 v[116:119], v[140:143], v[180:183], v[116:119]
	v_mfma_f32_16x16x32_bf16 v[112:115], v[148:151], v[180:183], v[112:115]
	v_mfma_f32_16x16x32_bf16 v[100:103], v[140:143], v[188:191], v[100:103]
	v_mfma_f32_16x16x32_bf16 v[96:99], v[148:151], v[188:191], v[96:99]
	v_mfma_f32_16x16x32_bf16 v[84:87], v[140:143], v[216:219], v[84:87]
	v_mfma_f32_16x16x32_bf16 v[80:83], v[148:151], v[216:219], v[80:83]
	v_mfma_f32_16x16x32_bf16 v[124:127], v[144:147], v[176:179], v[124:127]
	v_mfma_f32_16x16x32_bf16 v[120:123], v[152:155], v[176:179], v[120:123]
	v_mfma_f32_16x16x32_bf16 v[116:119], v[144:147], v[184:187], v[116:119]
	v_mfma_f32_16x16x32_bf16 v[112:115], v[152:155], v[184:187], v[112:115]
	v_mfma_f32_16x16x32_bf16 v[100:103], v[144:147], v[212:215], v[100:103]
	v_mfma_f32_16x16x32_bf16 v[96:99], v[152:155], v[212:215], v[96:99]
	v_mfma_f32_16x16x32_bf16 v[84:87], v[144:147], v[232:235], v[84:87]
	v_mfma_f32_16x16x32_bf16 v[80:83], v[152:155], v[232:235], v[80:83]
	v_mfma_f32_16x16x32_bf16 v[108:111], v[156:159], v[172:175], v[108:111]
	v_mfma_f32_16x16x32_bf16 v[104:107], v[164:167], v[172:175], v[104:107]
	v_mfma_f32_16x16x32_bf16 v[92:95], v[156:159], v[180:183], v[92:95]
	v_mfma_f32_16x16x32_bf16 v[88:91], v[164:167], v[180:183], v[88:91]
	v_mfma_f32_16x16x32_bf16 v[76:79], v[156:159], v[188:191], v[76:79]
	v_mfma_f32_16x16x32_bf16 v[72:75], v[164:167], v[188:191], v[72:75]
	v_mfma_f32_16x16x32_bf16 v[68:71], v[156:159], v[216:219], v[68:71]
	v_mfma_f32_16x16x32_bf16 v[64:67], v[164:167], v[216:219], v[64:67]
	v_mfma_f32_16x16x32_bf16 v[108:111], v[160:163], v[176:179], v[108:111]
	v_mfma_f32_16x16x32_bf16 v[104:107], v[168:171], v[176:179], v[104:107]
	v_mfma_f32_16x16x32_bf16 v[92:95], v[160:163], v[184:187], v[92:95]
	v_mfma_f32_16x16x32_bf16 v[88:91], v[168:171], v[184:187], v[88:91]
	v_mfma_f32_16x16x32_bf16 v[76:79], v[160:163], v[212:215], v[76:79]
	v_mfma_f32_16x16x32_bf16 v[72:75], v[168:171], v[212:215], v[72:75]
	v_mfma_f32_16x16x32_bf16 v[68:71], v[160:163], v[232:235], v[68:71]
	v_mfma_f32_16x16x32_bf16 v[64:67], v[168:171], v[232:235], v[64:67]
	s_barrier
	s_add_i32 s18, s73, s35
	v_lshl_add_u64 v[194:195], s[22:23], 0, v[192:193]
	s_mov_b32 m0, s18
	ds_read_b128 v[172:175], v139 offset:16384
	ds_read_b128 v[176:179], v139 offset:17408
	ds_read_b128 v[180:183], v139 offset:18432
	ds_read_b128 v[184:187], v139 offset:19456
	ds_read_b128 v[188:191], v139 offset:20480
	ds_read_b128 v[212:215], v139 offset:21504
	ds_read_b128 v[216:219], v139 offset:22528
	ds_read_b128 v[232:235], v139 offset:23552
	global_load_lds_dwordx4 v[194:195], off
	s_add_i32 m0, s18, 0x2000
	s_add_u32 s18, s22, 0xb0000
	v_lshl_add_u64 v[196:197], s[22:23], 0, v[132:133]
	s_addc_u32 s19, s23, 0
	s_add_i32 s73, s74, s35
	global_load_lds_dwordx4 v[196:197], off
	v_lshl_add_u64 v[202:203], s[18:19], 0, v[192:193]
	s_mov_b32 m0, s73
	v_lshl_add_u64 v[204:205], s[44:45], 0, v[130:131]
	global_load_lds_dwordx4 v[202:203], off
	v_lshl_add_u64 v[202:203], s[18:19], 0, v[132:133]
	s_add_i32 m0, s73, 0x2000
	s_nop 0
	global_load_lds_dwordx4 v[202:203], off
	v_lshl_add_u64 v[202:203], s[44:45], 0, v[128:129]
	s_mov_b32 m0, s38
	s_nop 0
	global_load_lds_dwordx4 v[202:203], off
	s_mov_b32 m0, s40
	s_nop 0
	global_load_lds_dwordx4 v[204:205], off
	s_waitcnt vmcnt(8)
	s_waitcnt lgkmcnt(0)
	s_barrier
; #define PG8_STAGE(bufoff, gbase, voff) do { _Pragma("unroll") for (int _i = 0; _i < 2; ++_i) \
;         __builtin_amdgcn_global_load_lds((const unsigned*)((const char*)(gbase) + (voff)[_i]), (PG8_LAS unsigned*)(lds + (bufoff) + ldsw + _i * 8192), 16, 0, 0); } while (0)
; #define PG8_LDA(dst, b, h) do { _Pragma("unroll") for (int m = 0; m < 4; ++m) _Pragma("unroll") for (int k = 0; k < 2; ++k) dst[m][k] = *(const PG8_LAS bf16x8*)(lds + PG8_SA(b, h) + aoff + m * 2048 + k * 1024); } while (0)
; #define PG8_LDB(dst, b, h) do { _Pragma("unroll") for (int n = 0; n < 2; ++n) _Pragma("unroll") for (int k = 0; k < 2; ++k) dst[n][k] = *(const PG8_LAS bf16x8*)(lds + PG8_SB(b, h) + boff + n * 2048 + k * 1024); } while (0)
; #define PG8_MMA(ai, bj, At, Bt) do { __builtin_amdgcn_s_setprio(1); _Pragma("unroll") for (int m = 0; m < 4; ++m) _Pragma("unroll") for (int n = 0; n < 2; ++n) _Pragma("unroll") for (int k = 0; k < 2; ++k) \
;         acc[ai][bj][m][n] = __builtin_amdgcn_mfma_f32_16x16x32_bf16(Bt[n][k], At[m][k], acc[ai][bj][m][n], 0, 0, 0); __builtin_amdgcn_s_setprio(0); } while (0)
; #define PG8_WAIT_V(n) asm volatile("s_waitcnt vmcnt(" #n ")" ::: "memory")
; #define PG8_WAIT_L(n) asm volatile("s_waitcnt lgkmcnt(" #n ")" ::: "memory")
; #define PG8_BAR __builtin_amdgcn_s_barrier()
; #define PG8_SCHED __builtin_amdgcn_sched_barrier(0)
; template <class Epi, class Sched, bool ALIGN_EPI = false, bool SP2 = false>
; __device__ __forceinline__ void gemm_phase(PG8_LAS unsigned char* lds, const Gemm g, const Sched& S, const Epi& E, const int tid) {
;     ...
;             PG8_WAIT_V(8); PG8_WAIT_L(0); PG8_BAR; PG8_MMA(1, 0, At, B0); PG8_MMA(1, 1, At, B1); PG8_BAR; PG8_SCHED;
;             PG8_LDB(B0, 1, 0); PG8_LDB(B1, 1, 1); PG8_SCHED; PG8_LDA(At, 1, 0); PG8_STAGE(PG8_SA(0, 1), a2 + hstep, voffA);
;             PG8_WAIT_V(8); PG8_WAIT_L(0); PG8_BAR; PG8_MMA(0, 0, At, B0); PG8_MMA(0, 1, At, B1); PG8_BAR; PG8_SCHED;
	s_waitcnt lgkmcnt(0)
	v_mfma_f32_16x16x32_bf16 v[60:63], v[140:143], v[172:175], v[60:63]
	v_mfma_f32_16x16x32_bf16 v[56:59], v[148:151], v[172:175], v[56:59]
	v_mfma_f32_16x16x32_bf16 v[52:55], v[140:143], v[180:183], v[52:55]
	v_mfma_f32_16x16x32_bf16 v[48:51], v[148:151], v[180:183], v[48:51]
	v_mfma_f32_16x16x32_bf16 v[36:39], v[140:143], v[188:191], v[36:39]
	v_mfma_f32_16x16x32_bf16 v[32:35], v[148:151], v[188:191], v[32:35]
	v_mfma_f32_16x16x32_bf16 v[20:23], v[140:143], v[216:219], v[20:23]
	v_mfma_f32_16x16x32_bf16 v[16:19], v[148:151], v[216:219], v[16:19]
	v_mfma_f32_16x16x32_bf16 v[60:63], v[144:147], v[176:179], v[60:63]
	v_mfma_f32_16x16x32_bf16 v[56:59], v[152:155], v[176:179], v[56:59]
	v_mfma_f32_16x16x32_bf16 v[52:55], v[144:147], v[184:187], v[52:55]
	v_mfma_f32_16x16x32_bf16 v[48:51], v[152:155], v[184:187], v[48:51]
	v_mfma_f32_16x16x32_bf16 v[36:39], v[144:147], v[212:215], v[36:39]
	v_mfma_f32_16x16x32_bf16 v[32:35], v[152:155], v[212:215], v[32:35]
	v_mfma_f32_16x16x32_bf16 v[20:23], v[144:147], v[232:235], v[20:23]
	v_mfma_f32_16x16x32_bf16 v[16:19], v[152:155], v[232:235], v[16:19]
	v_mfma_f32_16x16x32_bf16 v[44:47], v[156:159], v[172:175], v[44:47]
	v_mfma_f32_16x16x32_bf16 v[40:43], v[164:167], v[172:175], v[40:43]
	v_mfma_f32_16x16x32_bf16 v[28:31], v[156:159], v[180:183], v[28:31]
	v_mfma_f32_16x16x32_bf16 v[24:27], v[164:167], v[180:183], v[24:27]
	v_mfma_f32_16x16x32_bf16 v[12:15], v[156:159], v[188:191], v[12:15]
	v_mfma_f32_16x16x32_bf16 v[8:11], v[164:167], v[188:191], v[8:11]
	v_mfma_f32_16x16x32_bf16 v[4:7], v[156:159], v[216:219], v[4:7]
	v_mfma_f32_16x16x32_bf16 v[0:3], v[164:167], v[216:219], v[0:3]
	v_mfma_f32_16x16x32_bf16 v[44:47], v[160:163], v[176:179], v[44:47]
	v_mfma_f32_16x16x32_bf16 v[40:43], v[168:171], v[176:179], v[40:43]
	v_mfma_f32_16x16x32_bf16 v[28:31], v[160:163], v[184:187], v[28:31]
	v_mfma_f32_16x16x32_bf16 v[24:27], v[168:171], v[184:187], v[24:27]
	v_mfma_f32_16x16x32_bf16 v[12:15], v[160:163], v[212:215], v[12:15]
	v_mfma_f32_16x16x32_bf16 v[8:11], v[168:171], v[212:215], v[8:11]
	v_mfma_f32_16x16x32_bf16 v[4:7], v[160:163], v[232:235], v[4:7]
	v_mfma_f32_16x16x32_bf16 v[0:3], v[168:171], v[232:235], v[0:3]
	s_barrier
	s_add_i32 s73, 0, 0x18000
	s_add_i32 s74, 0, 0x1c000
	v_add_u32_e32 v152, s73, v138
	v_add_u32_e32 v168, s74, v138
	ds_read_b128 v[140:143], v152
	ds_read_b128 v[144:147], v152 offset:1024
	ds_read_b128 v[148:151], v152 offset:2048
	ds_read_b128 v[152:155], v152 offset:3072
	ds_read_b128 v[156:159], v168
	ds_read_b128 v[160:163], v168 offset:1024
	ds_read_b128 v[164:167], v168 offset:2048
	ds_read_b128 v[168:171], v168 offset:3072
	s_add_u32 s18, s44, 0xb0000
	s_addc_u32 s19, s45, 0
	s_mov_b32 m0, s41
	v_lshl_add_u64 v[206:207], s[18:19], 0, v[128:129]
	ds_read_b128 v[172:175], v139 offset:32768
	ds_read_b128 v[176:179], v139 offset:33792
	ds_read_b128 v[180:183], v139 offset:34816
	ds_read_b128 v[184:187], v139 offset:35840
	ds_read_b128 v[188:191], v139 offset:36864
	ds_read_b128 v[212:215], v139 offset:37888
	ds_read_b128 v[216:219], v139 offset:38912
	ds_read_b128 v[232:235], v139 offset:39936
	global_load_lds_dwordx4 v[206:207], off
	v_lshl_add_u64 v[206:207], s[18:19], 0, v[130:131]
	s_mov_b32 m0, s46
	s_nop 0
	global_load_lds_dwordx4 v[206:207], off
	s_waitcnt vmcnt(8)
	s_waitcnt lgkmcnt(0)
	s_barrier
	s_waitcnt lgkmcnt(0)
	v_mfma_f32_16x16x32_bf16 v[124:127], v[140:143], v[172:175], v[124:127]
	v_mfma_f32_16x16x32_bf16 v[120:123], v[148:151], v[172:175], v[120:123]
	v_mfma_f32_16x16x32_bf16 v[116:119], v[140:143], v[180:183], v[116:119]
	v_mfma_f32_16x16x32_bf16 v[112:115], v[148:151], v[180:183], v[112:115]
	v_mfma_f32_16x16x32_bf16 v[100:103], v[140:143], v[188:191], v[100:103]
	v_mfma_f32_16x16x32_bf16 v[96:99], v[148:151], v[188:191], v[96:99]
	v_mfma_f32_16x16x32_bf16 v[84:87], v[140:143], v[216:219], v[84:87]
	v_mfma_f32_16x16x32_bf16 v[80:83], v[148:151], v[216:219], v[80:83]
	v_mfma_f32_16x16x32_bf16 v[124:127], v[144:147], v[176:179], v[124:127]
	v_mfma_f32_16x16x32_bf16 v[120:123], v[152:155], v[176:179], v[120:123]
	v_mfma_f32_16x16x32_bf16 v[116:119], v[144:147], v[184:187], v[116:119]
	v_mfma_f32_16x16x32_bf16 v[112:115], v[152:155], v[184:187], v[112:115]
	v_mfma_f32_16x16x32_bf16 v[100:103], v[144:147], v[212:215], v[100:103]
	v_mfma_f32_16x16x32_bf16 v[96:99], v[152:155], v[212:215], v[96:99]
	v_mfma_f32_16x16x32_bf16 v[84:87], v[144:147], v[232:235], v[84:87]
	v_mfma_f32_16x16x32_bf16 v[80:83], v[152:155], v[232:235], v[80:83]
	v_mfma_f32_16x16x32_bf16 v[108:111], v[156:159], v[172:175], v[108:111]
	v_mfma_f32_16x16x32_bf16 v[104:107], v[164:167], v[172:175], v[104:107]
	v_mfma_f32_16x16x32_bf16 v[92:95], v[156:159], v[180:183], v[92:95]
	v_mfma_f32_16x16x32_bf16 v[88:91], v[164:167], v[180:183], v[88:91]
	v_mfma_f32_16x16x32_bf16 v[76:79], v[156:159], v[188:191], v[76:79]
	v_mfma_f32_16x16x32_bf16 v[72:75], v[164:167], v[188:191], v[72:75]
	v_mfma_f32_16x16x32_bf16 v[68:71], v[156:159], v[216:219], v[68:71]
	v_mfma_f32_16x16x32_bf16 v[64:67], v[164:167], v[216:219], v[64:67]
	v_mfma_f32_16x16x32_bf16 v[108:111], v[160:163], v[176:179], v[108:111]
	v_mfma_f32_16x16x32_bf16 v[104:107], v[168:171], v[176:179], v[104:107]
	v_mfma_f32_16x16x32_bf16 v[92:95], v[160:163], v[184:187], v[92:95]
	v_mfma_f32_16x16x32_bf16 v[88:91], v[168:171], v[184:187], v[88:91]
	v_mfma_f32_16x16x32_bf16 v[76:79], v[160:163], v[212:215], v[76:79]
	v_mfma_f32_16x16x32_bf16 v[72:75], v[168:171], v[212:215], v[72:75]
	v_mfma_f32_16x16x32_bf16 v[68:71], v[160:163], v[232:235], v[68:71]
	v_mfma_f32_16x16x32_bf16 v[64:67], v[168:171], v[232:235], v[64:67]
	s_barrier
; #define PG8_STAGE(bufoff, gbase, voff) do { _Pragma("unroll") for (int _i = 0; _i < 2; ++_i) \
;         __builtin_amdgcn_global_load_lds((const unsigned*)((const char*)(gbase) + (voff)[_i]), (PG8_LAS unsigned*)(lds + (bufoff) + ldsw + _i * 8192), 16, 0, 0); } while (0)
; #define PG8_LDA(dst, b, h) do { _Pragma("unroll") for (int m = 0; m < 4; ++m) _Pragma("unroll") for (int k = 0; k < 2; ++k) dst[m][k] = *(const PG8_LAS bf16x8*)(lds + PG8_SA(b, h) + aoff + m * 2048 + k * 1024); } while (0)
; #define PG8_MMA(ai, bj, At, Bt) do { __builtin_amdgcn_s_setprio(1); _Pragma("unroll") for (int m = 0; m < 4; ++m) _Pragma("unroll") for (int n = 0; n < 2; ++n) _Pragma("unroll") for (int k = 0; k < 2; ++k) \
;         acc[ai][bj][m][n] = __builtin_amdgcn_mfma_f32_16x16x32_bf16(Bt[n][k], At[m][k], acc[ai][bj][m][n], 0, 0, 0); __builtin_amdgcn_s_setprio(0); } while (0)
; #define PG8_WAIT_V(n) asm volatile("s_waitcnt vmcnt(" #n ")" ::: "memory")
; #define PG8_WAIT_L(n) asm volatile("s_waitcnt lgkmcnt(" #n ")" ::: "memory")
; #define PG8_BAR __builtin_amdgcn_s_barrier()
; #define PG8_SCHED __builtin_amdgcn_sched_barrier(0)
; template <class Epi, class Sched, bool ALIGN_EPI = false, bool SP2 = false>
; __device__ __forceinline__ void gemm_phase(PG8_LAS unsigned char* lds, const Gemm g, const Sched& S, const Epi& E, const int tid) {
;     ...
;             PG8_LDA(At, 1, 1); PG8_STAGE(PG8_SB(1, 0), b3, voffB); PG8_STAGE(PG8_SB(1, 1), b3 + hstep, voffB); PG8_STAGE(PG8_SA(1, 0), a3, voffA);
;             PG8_WAIT_V(8); PG8_WAIT_L(0); PG8_BAR; PG8_MMA(1, 0, At, B0); PG8_MMA(1, 1, At, B1); PG8_BAR; PG8_SCHED;
;     ...
;         if constexpr (ALIGN_EPI) { if (wr == 0) PG8_BAR; }
	s_add_i32 s18, s73, s35
	v_lshl_add_u64 v[194:195], v[194:195], 0, s[36:37]
	s_mov_b32 m0, s18
	ds_read_b128 v[172:175], v139 offset:49152
	ds_read_b128 v[176:179], v139 offset:50176
	ds_read_b128 v[180:183], v139 offset:51200
	ds_read_b128 v[184:187], v139 offset:52224
	ds_read_b128 v[188:191], v139 offset:53248
	ds_read_b128 v[212:215], v139 offset:54272
	ds_read_b128 v[216:219], v139 offset:55296
	ds_read_b128 v[232:235], v139 offset:56320
	global_load_lds_dwordx4 v[194:195], off
	s_add_i32 m0, s18, 0x2000
	s_add_u32 s18, s22, 0xb0080
	v_lshl_add_u64 v[194:195], v[196:197], 0, s[36:37]
	s_addc_u32 s19, s23, 0
	s_add_i32 s22, s74, s35
	global_load_lds_dwordx4 v[194:195], off
	v_lshl_add_u64 v[194:195], s[18:19], 0, v[192:193]
	s_mov_b32 m0, s22
	s_nop 0
	global_load_lds_dwordx4 v[194:195], off
	v_lshl_add_u64 v[194:195], s[18:19], 0, v[132:133]
	s_add_i32 m0, s22, 0x2000
	s_nop 0
	global_load_lds_dwordx4 v[194:195], off
	v_lshl_add_u64 v[194:195], v[202:203], 0, s[36:37]
	s_mov_b32 m0, s47
	s_nop 0
	global_load_lds_dwordx4 v[194:195], off
	v_lshl_add_u64 v[194:195], v[204:205], 0, s[36:37]
	s_mov_b32 m0, s53
	s_nop 0
	global_load_lds_dwordx4 v[194:195], off
	s_add_i32 s72, s72, 2
	s_add_u32 s62, s62, 0x100
	s_addc_u32 s71, s71, 0
	s_cmp_gt_u32 s72, 41
	s_mov_b64 s[18:19], s[20:21]
	s_waitcnt vmcnt(8)
	s_waitcnt lgkmcnt(0)
	s_barrier
	s_waitcnt lgkmcnt(0)
	v_mfma_f32_16x16x32_bf16 v[60:63], v[140:143], v[172:175], v[60:63]
	v_mfma_f32_16x16x32_bf16 v[56:59], v[148:151], v[172:175], v[56:59]
	v_mfma_f32_16x16x32_bf16 v[52:55], v[140:143], v[180:183], v[52:55]
	v_mfma_f32_16x16x32_bf16 v[48:51], v[148:151], v[180:183], v[48:51]
	v_mfma_f32_16x16x32_bf16 v[36:39], v[140:143], v[188:191], v[36:39]
	v_mfma_f32_16x16x32_bf16 v[32:35], v[148:151], v[188:191], v[32:35]
	v_mfma_f32_16x16x32_bf16 v[20:23], v[140:143], v[216:219], v[20:23]
	v_mfma_f32_16x16x32_bf16 v[16:19], v[148:151], v[216:219], v[16:19]
	v_mfma_f32_16x16x32_bf16 v[60:63], v[144:147], v[176:179], v[60:63]
	v_mfma_f32_16x16x32_bf16 v[56:59], v[152:155], v[176:179], v[56:59]
	v_mfma_f32_16x16x32_bf16 v[52:55], v[144:147], v[184:187], v[52:55]
	v_mfma_f32_16x16x32_bf16 v[48:51], v[152:155], v[184:187], v[48:51]
	v_mfma_f32_16x16x32_bf16 v[36:39], v[144:147], v[212:215], v[36:39]
	v_mfma_f32_16x16x32_bf16 v[32:35], v[152:155], v[212:215], v[32:35]
	v_mfma_f32_16x16x32_bf16 v[20:23], v[144:147], v[232:235], v[20:23]
	v_mfma_f32_16x16x32_bf16 v[16:19], v[152:155], v[232:235], v[16:19]
	v_mfma_f32_16x16x32_bf16 v[44:47], v[156:159], v[172:175], v[44:47]
	v_mfma_f32_16x16x32_bf16 v[40:43], v[164:167], v[172:175], v[40:43]
	v_mfma_f32_16x16x32_bf16 v[28:31], v[156:159], v[180:183], v[28:31]
	v_mfma_f32_16x16x32_bf16 v[24:27], v[164:167], v[180:183], v[24:27]
	v_mfma_f32_16x16x32_bf16 v[12:15], v[156:159], v[188:191], v[12:15]
	v_mfma_f32_16x16x32_bf16 v[8:11], v[164:167], v[188:191], v[8:11]
	v_mfma_f32_16x16x32_bf16 v[4:7], v[156:159], v[216:219], v[4:7]
	v_mfma_f32_16x16x32_bf16 v[0:3], v[164:167], v[216:219], v[0:3]
	v_mfma_f32_16x16x32_bf16 v[44:47], v[160:163], v[176:179], v[44:47]
	v_mfma_f32_16x16x32_bf16 v[40:43], v[168:171], v[176:179], v[40:43]
	v_mfma_f32_16x16x32_bf16 v[28:31], v[160:163], v[184:187], v[28:31]
	v_mfma_f32_16x16x32_bf16 v[24:27], v[168:171], v[184:187], v[24:27]
	v_mfma_f32_16x16x32_bf16 v[12:15], v[160:163], v[212:215], v[12:15]
	v_mfma_f32_16x16x32_bf16 v[8:11], v[168:171], v[212:215], v[8:11]
	v_mfma_f32_16x16x32_bf16 v[4:7], v[160:163], v[232:235], v[4:7]
	v_mfma_f32_16x16x32_bf16 v[0:3], v[168:171], v[232:235], v[0:3]
	s_barrier
	s_cbranch_scc0 .LBB0_99
	s_and_b64 vcc, exec, s[14:15]
	s_cbranch_vccz .LBB0_102
	s_barrier

; #define PG8_STAGE(bufoff, gbase, voff) do { _Pragma("unroll") for (int _i = 0; _i < 2; ++_i) \
;         __builtin_amdgcn_global_load_lds((const unsigned*)((const char*)(gbase) + (voff)[_i]), (PG8_LAS unsigned*)(lds + (bufoff) + ldsw + _i * 8192), 16, 0, 0); } while (0)
; #define PG8_LDA(dst, b, h) do { _Pragma("unroll") for (int m = 0; m < 4; ++m) _Pragma("unroll") for (int k = 0; k < 2; ++k) dst[m][k] = *(const PG8_LAS bf16x8*)(lds + PG8_SA(b, h) + aoff + m * 2048 + k * 1024); } while (0)
; #define PG8_LDB(dst, b, h) do { _Pragma("unroll") for (int n = 0; n < 2; ++n) _Pragma("unroll") for (int k = 0; k < 2; ++k) dst[n][k] = *(const PG8_LAS bf16x8*)(lds + PG8_SB(b, h) + boff + n * 2048 + k * 1024); } while (0)
; #define PG8_MMA(ai, bj, At, Bt) do { __builtin_amdgcn_s_setprio(1); _Pragma("unroll") for (int m = 0; m < 4; ++m) _Pragma("unroll") for (int n = 0; n < 2; ++n) _Pragma("unroll") for (int k = 0; k < 2; ++k) \
;         acc[ai][bj][m][n] = __builtin_amdgcn_mfma_f32_16x16x32_bf16(Bt[n][k], At[m][k], acc[ai][bj][m][n], 0, 0, 0); __builtin_amdgcn_s_setprio(0); } while (0)
; #define PG8_WAIT_V(n) asm volatile("s_waitcnt vmcnt(" #n ")" ::: "memory")
; #define PG8_WAIT_L(n) asm volatile("s_waitcnt lgkmcnt(" #n ")" ::: "memory")
; #define PG8_BAR __builtin_amdgcn_s_barrier()
; #define PG8_SCHED __builtin_amdgcn_sched_barrier(0)
; template <class Epi, class Sched, bool ALIGN_EPI = false, bool SP2 = false>
; __device__ __forceinline__ void gemm_phase(PG8_LAS unsigned char* lds, const Gemm g, const Sched& S, const Epi& E, const int tid) {
;     ...
;             PG8_LDB(B0, 0, 0); PG8_LDB(B1, 0, 1); PG8_SCHED; PG8_LDA(At, 0, 0); PG8_STAGE(PG8_SA(1, 1), a1 + hstep, voffA);
;             PG8_WAIT_V(8); PG8_WAIT_L(0); PG8_BAR; PG8_MMA(0, 0, At, B0); PG8_MMA(0, 1, At, B1); PG8_BAR; PG8_SCHED;
;             PG8_LDA(At, 0, 1); PG8_STAGE(PG8_SB(0, 0), b2, voffB); PG8_STAGE(PG8_SB(0, 1), b2 + hstep, voffB); PG8_STAGE(PG8_SA(0, 0), a2, voffA);
;             PG8_WAIT_V(8); PG8_WAIT_L(0); PG8_BAR; PG8_MMA(1, 0, At, B0); PG8_MMA(1, 1, At, B1); PG8_BAR; PG8_SCHED;
.LBB0_127:
	s_waitcnt lgkmcnt(0)
	v_add_u32_e32 v156, 0x10000, v142
	v_add_u32_e32 v172, 0x14000, v142
	ds_read_b128 v[144:147], v156
	ds_read_b128 v[148:151], v156 offset:1024
	ds_read_b128 v[152:155], v156 offset:2048
	ds_read_b128 v[156:159], v156 offset:3072
	ds_read_b128 v[160:163], v172
	ds_read_b128 v[164:167], v172 offset:1024
	ds_read_b128 v[168:171], v172 offset:2048
	ds_read_b128 v[172:175], v172 offset:3072
	s_add_u32 s44, s16, s22
	s_addc_u32 s45, s17, s23
	s_add_u32 s44, s44, 0x100
	s_addc_u32 s45, s45, 0
	s_add_u32 s75, s19, s22
	s_addc_u32 s76, s62, s23
	s_add_i32 s77, 0, 0x10000
	s_cmpk_eq_i32 s22, 0x1500
	s_cselect_b32 s59, s21, s45
	s_cselect_b32 s58, s20, s44
	s_cselect_b32 s45, s11, s76
	s_cselect_b32 s44, s10, s75
	s_add_i32 s75, 0, 0x14000
	v_lshl_add_u64 v[194:195], v[138:139], 0, s[22:23]
	s_add_i32 m0, s47, 0xc000
	ds_read_b128 v[176:179], v143
	ds_read_b128 v[180:183], v143 offset:1024
	ds_read_b128 v[184:187], v143 offset:2048
	ds_read_b128 v[188:191], v143 offset:3072
	ds_read_b128 v[212:215], v143 offset:4096
	ds_read_b128 v[216:219], v143 offset:5120
	ds_read_b128 v[232:235], v143 offset:6144
	ds_read_b128 v[236:239], v143 offset:7168
	global_load_lds_dwordx4 v[194:195], off
	v_lshl_add_u64 v[194:195], v[140:141], 0, s[22:23]
	s_add_i32 m0, s47, 0xe000
	s_nop 0
	global_load_lds_dwordx4 v[194:195], off
	s_waitcnt vmcnt(8)
	s_waitcnt lgkmcnt(0)
	s_barrier
	s_waitcnt lgkmcnt(0)
	v_mfma_f32_16x16x32_bf16 v[124:127], v[144:147], v[176:179], v[124:127]
	v_mfma_f32_16x16x32_bf16 v[120:123], v[152:155], v[176:179], v[120:123]
	v_mfma_f32_16x16x32_bf16 v[108:111], v[144:147], v[184:187], v[108:111]
	v_mfma_f32_16x16x32_bf16 v[104:107], v[152:155], v[184:187], v[104:107]
	v_mfma_f32_16x16x32_bf16 v[92:95], v[144:147], v[212:215], v[92:95]
	v_mfma_f32_16x16x32_bf16 v[88:91], v[152:155], v[212:215], v[88:91]
	v_mfma_f32_16x16x32_bf16 v[76:79], v[144:147], v[232:235], v[76:79]
	v_mfma_f32_16x16x32_bf16 v[72:75], v[152:155], v[232:235], v[72:75]
	v_mfma_f32_16x16x32_bf16 v[124:127], v[148:151], v[180:183], v[124:127]
	v_mfma_f32_16x16x32_bf16 v[120:123], v[156:159], v[180:183], v[120:123]
	v_mfma_f32_16x16x32_bf16 v[108:111], v[148:151], v[188:191], v[108:111]
	v_mfma_f32_16x16x32_bf16 v[104:107], v[156:159], v[188:191], v[104:107]
	v_mfma_f32_16x16x32_bf16 v[92:95], v[148:151], v[216:219], v[92:95]
	v_mfma_f32_16x16x32_bf16 v[88:91], v[156:159], v[216:219], v[88:91]
	v_mfma_f32_16x16x32_bf16 v[76:79], v[148:151], v[236:239], v[76:79]
	v_mfma_f32_16x16x32_bf16 v[72:75], v[156:159], v[236:239], v[72:75]
	v_mfma_f32_16x16x32_bf16 v[116:119], v[160:163], v[176:179], v[116:119]
	v_mfma_f32_16x16x32_bf16 v[112:115], v[168:171], v[176:179], v[112:115]
	v_mfma_f32_16x16x32_bf16 v[100:103], v[160:163], v[184:187], v[100:103]
	v_mfma_f32_16x16x32_bf16 v[96:99], v[168:171], v[184:187], v[96:99]
	v_mfma_f32_16x16x32_bf16 v[84:87], v[160:163], v[212:215], v[84:87]
	v_mfma_f32_16x16x32_bf16 v[80:83], v[168:171], v[212:215], v[80:83]
	v_mfma_f32_16x16x32_bf16 v[68:71], v[160:163], v[232:235], v[68:71]
	v_mfma_f32_16x16x32_bf16 v[64:67], v[168:171], v[232:235], v[64:67]
	v_mfma_f32_16x16x32_bf16 v[116:119], v[164:167], v[180:183], v[116:119]
	v_mfma_f32_16x16x32_bf16 v[112:115], v[172:175], v[180:183], v[112:115]
	v_mfma_f32_16x16x32_bf16 v[100:103], v[164:167], v[188:191], v[100:103]
	v_mfma_f32_16x16x32_bf16 v[96:99], v[172:175], v[188:191], v[96:99]
	v_mfma_f32_16x16x32_bf16 v[84:87], v[164:167], v[216:219], v[84:87]
	v_mfma_f32_16x16x32_bf16 v[80:83], v[172:175], v[216:219], v[80:83]
	v_mfma_f32_16x16x32_bf16 v[68:71], v[164:167], v[236:239], v[68:71]
	v_mfma_f32_16x16x32_bf16 v[64:67], v[172:175], v[236:239], v[64:67]
	s_barrier
	s_add_i32 s76, s77, s46
	v_lshl_add_u64 v[194:195], s[44:45], 0, v[192:193]
	s_mov_b32 m0, s76
	ds_read_b128 v[176:179], v143 offset:16384
	ds_read_b128 v[180:183], v143 offset:17408
	ds_read_b128 v[184:187], v143 offset:18432
	ds_read_b128 v[188:191], v143 offset:19456
	ds_read_b128 v[212:215], v143 offset:20480
	ds_read_b128 v[216:219], v143 offset:21504
	ds_read_b128 v[232:235], v143 offset:22528
	ds_read_b128 v[236:239], v143 offset:23552
	global_load_lds_dwordx4 v[194:195], off
	s_add_i32 m0, s76, 0x2000
	s_add_u32 s76, s44, 0xb0000
	v_lshl_add_u64 v[196:197], s[44:45], 0, v[132:133]
	s_addc_u32 s77, s45, 0
	s_add_i32 s75, s75, s46
	global_load_lds_dwordx4 v[196:197], off
	v_lshl_add_u64 v[202:203], s[76:77], 0, v[192:193]
	s_mov_b32 m0, s75
	v_lshl_add_u64 v[204:205], s[58:59], 0, v[130:131]
	global_load_lds_dwordx4 v[202:203], off
	v_lshl_add_u64 v[202:203], s[76:77], 0, v[132:133]
	s_add_i32 m0, s75, 0x2000
	s_nop 0
	global_load_lds_dwordx4 v[202:203], off
	v_lshl_add_u64 v[202:203], s[58:59], 0, v[128:129]
	s_mov_b32 m0, s47
	s_nop 0
	global_load_lds_dwordx4 v[202:203], off
	s_mov_b32 m0, s53
	s_nop 0
	global_load_lds_dwordx4 v[204:205], off
	s_waitcnt vmcnt(8)
	s_waitcnt lgkmcnt(0)
	s_barrier
; #define PG8_STAGE(bufoff, gbase, voff) do { _Pragma("unroll") for (int _i = 0; _i < 2; ++_i) \
;         __builtin_amdgcn_global_load_lds((const unsigned*)((const char*)(gbase) + (voff)[_i]), (PG8_LAS unsigned*)(lds + (bufoff) + ldsw + _i * 8192), 16, 0, 0); } while (0)
; #define PG8_LDA(dst, b, h) do { _Pragma("unroll") for (int m = 0; m < 4; ++m) _Pragma("unroll") for (int k = 0; k < 2; ++k) dst[m][k] = *(const PG8_LAS bf16x8*)(lds + PG8_SA(b, h) + aoff + m * 2048 + k * 1024); } while (0)
; #define PG8_LDB(dst, b, h) do { _Pragma("unroll") for (int n = 0; n < 2; ++n) _Pragma("unroll") for (int k = 0; k < 2; ++k) dst[n][k] = *(const PG8_LAS bf16x8*)(lds + PG8_SB(b, h) + boff + n * 2048 + k * 1024); } while (0)
; #define PG8_MMA(ai, bj, At, Bt) do { __builtin_amdgcn_s_setprio(1); _Pragma("unroll") for (int m = 0; m < 4; ++m) _Pragma("unroll") for (int n = 0; n < 2; ++n) _Pragma("unroll") for (int k = 0; k < 2; ++k) \
;         acc[ai][bj][m][n] = __builtin_amdgcn_mfma_f32_16x16x32_bf16(Bt[n][k], At[m][k], acc[ai][bj][m][n], 0, 0, 0); __builtin_amdgcn_s_setprio(0); } while (0)
; #define PG8_WAIT_V(n) asm volatile("s_waitcnt vmcnt(" #n ")" ::: "memory")
; #define PG8_WAIT_L(n) asm volatile("s_waitcnt lgkmcnt(" #n ")" ::: "memory")
; #define PG8_BAR __builtin_amdgcn_s_barrier()
; #define PG8_SCHED __builtin_amdgcn_sched_barrier(0)
; template <class Epi, class Sched, bool ALIGN_EPI = false, bool SP2 = false>
; __device__ __forceinline__ void gemm_phase(PG8_LAS unsigned char* lds, const Gemm g, const Sched& S, const Epi& E, const int tid) {
;     ...
;             PG8_WAIT_V(8); PG8_WAIT_L(0); PG8_BAR; PG8_MMA(1, 0, At, B0); PG8_MMA(1, 1, At, B1); PG8_BAR; PG8_SCHED;
;             PG8_LDB(B0, 1, 0); PG8_LDB(B1, 1, 1); PG8_SCHED; PG8_LDA(At, 1, 0); PG8_STAGE(PG8_SA(0, 1), a2 + hstep, voffA);
;             PG8_WAIT_V(8); PG8_WAIT_L(0); PG8_BAR; PG8_MMA(0, 0, At, B0); PG8_MMA(0, 1, At, B1); PG8_BAR; PG8_SCHED;
	s_waitcnt lgkmcnt(0)
	v_mfma_f32_16x16x32_bf16 v[60:63], v[144:147], v[176:179], v[60:63]
	v_mfma_f32_16x16x32_bf16 v[56:59], v[152:155], v[176:179], v[56:59]
	v_mfma_f32_16x16x32_bf16 v[44:47], v[144:147], v[184:187], v[44:47]
	v_mfma_f32_16x16x32_bf16 v[40:43], v[152:155], v[184:187], v[40:43]
	v_mfma_f32_16x16x32_bf16 v[28:31], v[144:147], v[212:215], v[28:31]
	v_mfma_f32_16x16x32_bf16 v[24:27], v[152:155], v[212:215], v[24:27]
	v_mfma_f32_16x16x32_bf16 v[12:15], v[144:147], v[232:235], v[12:15]
	v_mfma_f32_16x16x32_bf16 v[8:11], v[152:155], v[232:235], v[8:11]
	v_mfma_f32_16x16x32_bf16 v[60:63], v[148:151], v[180:183], v[60:63]
	v_mfma_f32_16x16x32_bf16 v[56:59], v[156:159], v[180:183], v[56:59]
	v_mfma_f32_16x16x32_bf16 v[44:47], v[148:151], v[188:191], v[44:47]
	v_mfma_f32_16x16x32_bf16 v[40:43], v[156:159], v[188:191], v[40:43]
	v_mfma_f32_16x16x32_bf16 v[28:31], v[148:151], v[216:219], v[28:31]
	v_mfma_f32_16x16x32_bf16 v[24:27], v[156:159], v[216:219], v[24:27]
	v_mfma_f32_16x16x32_bf16 v[12:15], v[148:151], v[236:239], v[12:15]
	v_mfma_f32_16x16x32_bf16 v[8:11], v[156:159], v[236:239], v[8:11]
	v_mfma_f32_16x16x32_bf16 v[52:55], v[160:163], v[176:179], v[52:55]
	v_mfma_f32_16x16x32_bf16 v[48:51], v[168:171], v[176:179], v[48:51]
	v_mfma_f32_16x16x32_bf16 v[36:39], v[160:163], v[184:187], v[36:39]
	v_mfma_f32_16x16x32_bf16 v[32:35], v[168:171], v[184:187], v[32:35]
	v_mfma_f32_16x16x32_bf16 v[20:23], v[160:163], v[212:215], v[20:23]
	v_mfma_f32_16x16x32_bf16 v[16:19], v[168:171], v[212:215], v[16:19]
	v_mfma_f32_16x16x32_bf16 v[4:7], v[160:163], v[232:235], v[4:7]
	v_mfma_f32_16x16x32_bf16 v[0:3], v[168:171], v[232:235], v[0:3]
	v_mfma_f32_16x16x32_bf16 v[52:55], v[164:167], v[180:183], v[52:55]
	v_mfma_f32_16x16x32_bf16 v[48:51], v[172:175], v[180:183], v[48:51]
	v_mfma_f32_16x16x32_bf16 v[36:39], v[164:167], v[188:191], v[36:39]
	v_mfma_f32_16x16x32_bf16 v[32:35], v[172:175], v[188:191], v[32:35]
	v_mfma_f32_16x16x32_bf16 v[20:23], v[164:167], v[216:219], v[20:23]
	v_mfma_f32_16x16x32_bf16 v[16:19], v[172:175], v[216:219], v[16:19]
	v_mfma_f32_16x16x32_bf16 v[4:7], v[164:167], v[236:239], v[4:7]
	v_mfma_f32_16x16x32_bf16 v[0:3], v[172:175], v[236:239], v[0:3]
	s_barrier
	s_add_i32 s75, 0, 0x18000
	s_add_i32 s76, 0, 0x1c000
	v_add_u32_e32 v156, s75, v142
	v_add_u32_e32 v172, s76, v142
	ds_read_b128 v[144:147], v156
	ds_read_b128 v[148:151], v156 offset:1024
	ds_read_b128 v[152:155], v156 offset:2048
	ds_read_b128 v[156:159], v156 offset:3072
	ds_read_b128 v[160:163], v172
	ds_read_b128 v[164:167], v172 offset:1024
	ds_read_b128 v[168:171], v172 offset:2048
	ds_read_b128 v[172:175], v172 offset:3072
	s_add_u32 s58, s58, 0xb0000
	s_addc_u32 s59, s59, 0
	s_mov_b32 m0, s54
	v_lshl_add_u64 v[206:207], s[58:59], 0, v[128:129]
	ds_read_b128 v[176:179], v143 offset:32768
	ds_read_b128 v[180:183], v143 offset:33792
	ds_read_b128 v[184:187], v143 offset:34816
	ds_read_b128 v[188:191], v143 offset:35840
	ds_read_b128 v[212:215], v143 offset:36864
	ds_read_b128 v[216:219], v143 offset:37888
	ds_read_b128 v[232:235], v143 offset:38912
	ds_read_b128 v[236:239], v143 offset:39936
	global_load_lds_dwordx4 v[206:207], off
	v_lshl_add_u64 v[206:207], s[58:59], 0, v[130:131]
	s_mov_b32 m0, s55
	s_nop 0
	global_load_lds_dwordx4 v[206:207], off
	s_waitcnt vmcnt(8)
	s_waitcnt lgkmcnt(0)
	s_barrier
	s_waitcnt lgkmcnt(0)
	v_mfma_f32_16x16x32_bf16 v[124:127], v[144:147], v[176:179], v[124:127]
	v_mfma_f32_16x16x32_bf16 v[120:123], v[152:155], v[176:179], v[120:123]
	v_mfma_f32_16x16x32_bf16 v[108:111], v[144:147], v[184:187], v[108:111]
	v_mfma_f32_16x16x32_bf16 v[104:107], v[152:155], v[184:187], v[104:107]
	v_mfma_f32_16x16x32_bf16 v[92:95], v[144:147], v[212:215], v[92:95]
	v_mfma_f32_16x16x32_bf16 v[88:91], v[152:155], v[212:215], v[88:91]
	v_mfma_f32_16x16x32_bf16 v[76:79], v[144:147], v[232:235], v[76:79]
	v_mfma_f32_16x16x32_bf16 v[72:75], v[152:155], v[232:235], v[72:75]
	v_mfma_f32_16x16x32_bf16 v[124:127], v[148:151], v[180:183], v[124:127]
	v_mfma_f32_16x16x32_bf16 v[120:123], v[156:159], v[180:183], v[120:123]
	v_mfma_f32_16x16x32_bf16 v[108:111], v[148:151], v[188:191], v[108:111]
	v_mfma_f32_16x16x32_bf16 v[104:107], v[156:159], v[188:191], v[104:107]
	v_mfma_f32_16x16x32_bf16 v[92:95], v[148:151], v[216:219], v[92:95]
	v_mfma_f32_16x16x32_bf16 v[88:91], v[156:159], v[216:219], v[88:91]
	v_mfma_f32_16x16x32_bf16 v[76:79], v[148:151], v[236:239], v[76:79]
	v_mfma_f32_16x16x32_bf16 v[72:75], v[156:159], v[236:239], v[72:75]
	v_mfma_f32_16x16x32_bf16 v[116:119], v[160:163], v[176:179], v[116:119]
	v_mfma_f32_16x16x32_bf16 v[112:115], v[168:171], v[176:179], v[112:115]
	v_mfma_f32_16x16x32_bf16 v[100:103], v[160:163], v[184:187], v[100:103]
	v_mfma_f32_16x16x32_bf16 v[96:99], v[168:171], v[184:187], v[96:99]
	v_mfma_f32_16x16x32_bf16 v[84:87], v[160:163], v[212:215], v[84:87]
	v_mfma_f32_16x16x32_bf16 v[80:83], v[168:171], v[212:215], v[80:83]
	v_mfma_f32_16x16x32_bf16 v[68:71], v[160:163], v[232:235], v[68:71]
	v_mfma_f32_16x16x32_bf16 v[64:67], v[168:171], v[232:235], v[64:67]
	v_mfma_f32_16x16x32_bf16 v[116:119], v[164:167], v[180:183], v[116:119]
	v_mfma_f32_16x16x32_bf16 v[112:115], v[172:175], v[180:183], v[112:115]
	v_mfma_f32_16x16x32_bf16 v[100:103], v[164:167], v[188:191], v[100:103]
	v_mfma_f32_16x16x32_bf16 v[96:99], v[172:175], v[188:191], v[96:99]
	v_mfma_f32_16x16x32_bf16 v[84:87], v[164:167], v[216:219], v[84:87]
	v_mfma_f32_16x16x32_bf16 v[80:83], v[172:175], v[216:219], v[80:83]
	v_mfma_f32_16x16x32_bf16 v[68:71], v[164:167], v[236:239], v[68:71]
	v_mfma_f32_16x16x32_bf16 v[64:67], v[172:175], v[236:239], v[64:67]
	s_barrier
; #define PG8_STAGE(bufoff, gbase, voff) do { _Pragma("unroll") for (int _i = 0; _i < 2; ++_i) \
;         __builtin_amdgcn_global_load_lds((const unsigned*)((const char*)(gbase) + (voff)[_i]), (PG8_LAS unsigned*)(lds + (bufoff) + ldsw + _i * 8192), 16, 0, 0); } while (0)
; #define PG8_LDA(dst, b, h) do { _Pragma("unroll") for (int m = 0; m < 4; ++m) _Pragma("unroll") for (int k = 0; k < 2; ++k) dst[m][k] = *(const PG8_LAS bf16x8*)(lds + PG8_SA(b, h) + aoff + m * 2048 + k * 1024); } while (0)
; #define PG8_MMA(ai, bj, At, Bt) do { __builtin_amdgcn_s_setprio(1); _Pragma("unroll") for (int m = 0; m < 4; ++m) _Pragma("unroll") for (int n = 0; n < 2; ++n) _Pragma("unroll") for (int k = 0; k < 2; ++k) \
;         acc[ai][bj][m][n] = __builtin_amdgcn_mfma_f32_16x16x32_bf16(Bt[n][k], At[m][k], acc[ai][bj][m][n], 0, 0, 0); __builtin_amdgcn_s_setprio(0); } while (0)
; #define PG8_WAIT_V(n) asm volatile("s_waitcnt vmcnt(" #n ")" ::: "memory")
; #define PG8_WAIT_L(n) asm volatile("s_waitcnt lgkmcnt(" #n ")" ::: "memory")
; #define PG8_BAR __builtin_amdgcn_s_barrier()
; #define PG8_SCHED __builtin_amdgcn_sched_barrier(0)
; template <class Epi, class Sched, bool ALIGN_EPI = false, bool SP2 = false>
; __device__ __forceinline__ void gemm_phase(PG8_LAS unsigned char* lds, const Gemm g, const Sched& S, const Epi& E, const int tid) {
;     ...
;             PG8_LDA(At, 1, 1); PG8_STAGE(PG8_SB(1, 0), b3, voffB); PG8_STAGE(PG8_SB(1, 1), b3 + hstep, voffB); PG8_STAGE(PG8_SA(1, 0), a3, voffA);
;             PG8_WAIT_V(8); PG8_WAIT_L(0); PG8_BAR; PG8_MMA(1, 0, At, B0); PG8_MMA(1, 1, At, B1); PG8_BAR; PG8_SCHED;
;     ...
;         if (!has_next) break;
; #pragma unroll
;         for (int a = 0; a < 2; ++a)
; #pragma unroll
;             for (int b = 0; b < 2; ++b)
; #pragma unroll
;                 for (int m = 0; m < 4; ++m)
; #pragma unroll
;                     for (int n = 0; n < 2; ++n) acc[a][b][m][n] = (f32x4){0.f, 0.f, 0.f, 0.f};
	s_add_i32 s58, s75, s46
	v_lshl_add_u64 v[194:195], v[194:195], 0, s[36:37]
	s_mov_b32 m0, s58
	ds_read_b128 v[176:179], v143 offset:49152
	ds_read_b128 v[180:183], v143 offset:50176
	ds_read_b128 v[184:187], v143 offset:51200
	ds_read_b128 v[188:191], v143 offset:52224
	ds_read_b128 v[212:215], v143 offset:53248
	ds_read_b128 v[216:219], v143 offset:54272
	ds_read_b128 v[232:235], v143 offset:55296
	ds_read_b128 v[236:239], v143 offset:56320
	global_load_lds_dwordx4 v[194:195], off
	s_add_i32 m0, s58, 0x2000
	s_add_u32 s44, s44, 0xb0080
	v_lshl_add_u64 v[194:195], v[196:197], 0, s[36:37]
	s_addc_u32 s45, s45, 0
	s_add_i32 s58, s76, s46
	global_load_lds_dwordx4 v[194:195], off
	v_lshl_add_u64 v[194:195], s[44:45], 0, v[192:193]
	s_mov_b32 m0, s58
	s_nop 0
	global_load_lds_dwordx4 v[194:195], off
	v_lshl_add_u64 v[194:195], s[44:45], 0, v[132:133]
	s_add_i32 m0, s58, 0x2000
	s_nop 0
	global_load_lds_dwordx4 v[194:195], off
	v_lshl_add_u64 v[194:195], v[202:203], 0, s[36:37]
	s_mov_b32 m0, s60
	s_nop 0
	global_load_lds_dwordx4 v[194:195], off
	v_lshl_add_u64 v[194:195], v[204:205], 0, s[36:37]
	s_mov_b32 m0, s70
	s_nop 0
	global_load_lds_dwordx4 v[194:195], off
	s_add_i32 s74, s74, 2
	s_add_u32 s22, s22, 0x100
	s_addc_u32 s23, s23, 0
	s_cmp_gt_u32 s74, 41
	s_waitcnt vmcnt(8)
	s_waitcnt lgkmcnt(0)
	s_barrier
	s_waitcnt lgkmcnt(0)
	v_mfma_f32_16x16x32_bf16 v[60:63], v[144:147], v[176:179], v[60:63]
	v_mfma_f32_16x16x32_bf16 v[56:59], v[152:155], v[176:179], v[56:59]
	v_mfma_f32_16x16x32_bf16 v[44:47], v[144:147], v[184:187], v[44:47]
	v_mfma_f32_16x16x32_bf16 v[40:43], v[152:155], v[184:187], v[40:43]
	v_mfma_f32_16x16x32_bf16 v[28:31], v[144:147], v[212:215], v[28:31]
	v_mfma_f32_16x16x32_bf16 v[24:27], v[152:155], v[212:215], v[24:27]
	v_mfma_f32_16x16x32_bf16 v[12:15], v[144:147], v[232:235], v[12:15]
	v_mfma_f32_16x16x32_bf16 v[8:11], v[152:155], v[232:235], v[8:11]
	v_mfma_f32_16x16x32_bf16 v[60:63], v[148:151], v[180:183], v[60:63]
	v_mfma_f32_16x16x32_bf16 v[56:59], v[156:159], v[180:183], v[56:59]
	v_mfma_f32_16x16x32_bf16 v[44:47], v[148:151], v[188:191], v[44:47]
	v_mfma_f32_16x16x32_bf16 v[40:43], v[156:159], v[188:191], v[40:43]
	v_mfma_f32_16x16x32_bf16 v[28:31], v[148:151], v[216:219], v[28:31]
	v_mfma_f32_16x16x32_bf16 v[24:27], v[156:159], v[216:219], v[24:27]
	v_mfma_f32_16x16x32_bf16 v[12:15], v[148:151], v[236:239], v[12:15]
	v_mfma_f32_16x16x32_bf16 v[8:11], v[156:159], v[236:239], v[8:11]
	v_mfma_f32_16x16x32_bf16 v[52:55], v[160:163], v[176:179], v[52:55]
	v_mfma_f32_16x16x32_bf16 v[48:51], v[168:171], v[176:179], v[48:51]
	v_mfma_f32_16x16x32_bf16 v[36:39], v[160:163], v[184:187], v[36:39]
	v_mfma_f32_16x16x32_bf16 v[32:35], v[168:171], v[184:187], v[32:35]
	v_mfma_f32_16x16x32_bf16 v[20:23], v[160:163], v[212:215], v[20:23]
	v_mfma_f32_16x16x32_bf16 v[16:19], v[168:171], v[212:215], v[16:19]
	v_mfma_f32_16x16x32_bf16 v[4:7], v[160:163], v[232:235], v[4:7]
	v_mfma_f32_16x16x32_bf16 v[0:3], v[168:171], v[232:235], v[0:3]
	v_mfma_f32_16x16x32_bf16 v[52:55], v[164:167], v[180:183], v[52:55]
	v_mfma_f32_16x16x32_bf16 v[48:51], v[172:175], v[180:183], v[48:51]
	v_mfma_f32_16x16x32_bf16 v[36:39], v[164:167], v[188:191], v[36:39]
	v_mfma_f32_16x16x32_bf16 v[32:35], v[172:175], v[188:191], v[32:35]
	v_mfma_f32_16x16x32_bf16 v[20:23], v[164:167], v[216:219], v[20:23]
	v_mfma_f32_16x16x32_bf16 v[16:19], v[172:175], v[216:219], v[16:19]
	v_mfma_f32_16x16x32_bf16 v[4:7], v[164:167], v[236:239], v[4:7]
	v_mfma_f32_16x16x32_bf16 v[0:3], v[172:175], v[236:239], v[0:3]
	s_barrier
	s_cbranch_scc0 .LBB0_127
	s_add_u32 s22, s19, 0xffffff00
	s_addc_u32 s23, s62, -1
	s_and_b64 vcc, exec, s[8:9]
	s_cbranch_vccnz .LBB0_130
	v_mov_b32_e32 v0, 0
	s_mov_b32 s14, s72
	s_mov_b32 s1, s73
	s_mov_b64 s[16:17], s[20:21]
	s_mov_b32 s71, s18
	v_mov_b32_e32 v1, v0
	v_mov_b32_e32 v2, v0
	v_mov_b32_e32 v3, v0
	v_mov_b32_e32 v4, v0
	v_mov_b32_e32 v5, v0
	v_mov_b32_e32 v6, v0
	v_mov_b32_e32 v7, v0
	v_mov_b32_e32 v16, v0
	v_mov_b32_e32 v17, v0
	v_mov_b32_e32 v18, v0
	v_mov_b32_e32 v19, v0
	v_mov_b32_e32 v20, v0
	v_mov_b32_e32 v21, v0
	v_mov_b32_e32 v22, v0
	v_mov_b32_e32 v23, v0
	v_mov_b32_e32 v32, v0
	v_mov_b32_e32 v33, v0
	v_mov_b32_e32 v34, v0
	v_mov_b32_e32 v35, v0
	v_mov_b32_e32 v36, v0
	v_mov_b32_e32 v37, v0
	v_mov_b32_e32 v38, v0
	v_mov_b32_e32 v39, v0
	v_mov_b32_e32 v48, v0
	v_mov_b32_e32 v49, v0
	v_mov_b32_e32 v50, v0
	v_mov_b32_e32 v51, v0
	v_mov_b32_e32 v52, v0
	v_mov_b32_e32 v53, v0
	v_mov_b32_e32 v54, v0
	v_mov_b32_e32 v55, v0
	v_mov_b32_e32 v8, v0
	v_mov_b32_e32 v9, v0
	v_mov_b32_e32 v10, v0
	v_mov_b32_e32 v11, v0
	v_mov_b32_e32 v12, v0
	v_mov_b32_e32 v13, v0
	v_mov_b32_e32 v14, v0
	v_mov_b32_e32 v15, v0
	v_mov_b32_e32 v24, v0
	v_mov_b32_e32 v25, v0
	v_mov_b32_e32 v26, v0
	v_mov_b32_e32 v27, v0
	v_mov_b32_e32 v28, v0
	v_mov_b32_e32 v29, v0
	v_mov_b32_e32 v30, v0
	v_mov_b32_e32 v31, v0
	v_mov_b32_e32 v40, v0
	v_mov_b32_e32 v41, v0
	v_mov_b32_e32 v42, v0
	v_mov_b32_e32 v43, v0
	v_mov_b32_e32 v44, v0
	v_mov_b32_e32 v45, v0
	v_mov_b32_e32 v46, v0
	v_mov_b32_e32 v47, v0
	v_mov_b32_e32 v56, v0
	v_mov_b32_e32 v57, v0
	v_mov_b32_e32 v58, v0
	v_mov_b32_e32 v59, v0
	v_mov_b32_e32 v60, v0
	v_mov_b32_e32 v61, v0
	v_mov_b32_e32 v62, v0
	v_mov_b32_e32 v63, v0
	v_mov_b32_e32 v64, v0
	v_mov_b32_e32 v65, v0
	v_mov_b32_e32 v66, v0
	v_mov_b32_e32 v67, v0
	v_mov_b32_e32 v68, v0
	v_mov_b32_e32 v69, v0
	v_mov_b32_e32 v70, v0
	v_mov_b32_e32 v71, v0
	v_mov_b32_e32 v80, v0
	v_mov_b32_e32 v81, v0
	v_mov_b32_e32 v82, v0
	v_mov_b32_e32 v83, v0
	v_mov_b32_e32 v84, v0
	v_mov_b32_e32 v85, v0
	v_mov_b32_e32 v86, v0
	v_mov_b32_e32 v87, v0
	v_mov_b32_e32 v96, v0
	v_mov_b32_e32 v97, v0
	v_mov_b32_e32 v98, v0
	v_mov_b32_e32 v99, v0
	v_mov_b32_e32 v100, v0
	v_mov_b32_e32 v101, v0
	v_mov_b32_e32 v102, v0
	v_mov_b32_e32 v103, v0
	v_mov_b32_e32 v112, v0
	v_mov_b32_e32 v113, v0
	v_mov_b32_e32 v114, v0
	v_mov_b32_e32 v115, v0
	v_mov_b32_e32 v116, v0
	v_mov_b32_e32 v117, v0
	v_mov_b32_e32 v118, v0
	v_mov_b32_e32 v119, v0
	v_mov_b32_e32 v72, v0
	v_mov_b32_e32 v73, v0
	v_mov_b32_e32 v74, v0
	v_mov_b32_e32 v75, v0
	v_mov_b32_e32 v76, v0
	v_mov_b32_e32 v77, v0
	v_mov_b32_e32 v78, v0
	v_mov_b32_e32 v79, v0
	v_mov_b32_e32 v88, v0
	v_mov_b32_e32 v89, v0
	v_mov_b32_e32 v90, v0
	v_mov_b32_e32 v91, v0
	v_mov_b32_e32 v92, v0
	v_mov_b32_e32 v93, v0
	v_mov_b32_e32 v94, v0
	v_mov_b32_e32 v95, v0
	v_mov_b32_e32 v104, v0
	v_mov_b32_e32 v105, v0
	v_mov_b32_e32 v106, v0
	v_mov_b32_e32 v107, v0
	v_mov_b32_e32 v108, v0
	v_mov_b32_e32 v109, v0
	v_mov_b32_e32 v110, v0
	v_mov_b32_e32 v111, v0
	v_mov_b32_e32 v120, v0
	v_mov_b32_e32 v121, v0
	v_mov_b32_e32 v122, v0
	v_mov_b32_e32 v123, v0
	v_mov_b32_e32 v124, v0
	v_mov_b32_e32 v125, v0
	v_mov_b32_e32 v126, v0
	v_mov_b32_e32 v127, v0
	s_load_dword s75, s[96:97], 0x0
	s_andn2_b64 vcc, exec, s[6:7]
	s_cbranch_vccnz .LBB0_131
	s_branch .LBB0_189

; #define PG8_STAGE(bufoff, gbase, voff) do { _Pragma("unroll") for (int _i = 0; _i < 2; ++_i) \
;         __builtin_amdgcn_global_load_lds((const unsigned*)((const char*)(gbase) + (voff)[_i]), (PG8_LAS unsigned*)(lds + (bufoff) + ldsw + _i * 8192), 16, 0, 0); } while (0)
; #define PG8_LDA(dst, b, h) do { _Pragma("unroll") for (int m = 0; m < 4; ++m) _Pragma("unroll") for (int k = 0; k < 2; ++k) dst[m][k] = *(const PG8_LAS bf16x8*)(lds + PG8_SA(b, h) + aoff + m * 2048 + k * 1024); } while (0)
; #define PG8_LDB(dst, b, h) do { _Pragma("unroll") for (int n = 0; n < 2; ++n) _Pragma("unroll") for (int k = 0; k < 2; ++k) dst[n][k] = *(const PG8_LAS bf16x8*)(lds + PG8_SB(b, h) + boff + n * 2048 + k * 1024); } while (0)
; #define PG8_MMA(ai, bj, At, Bt) do { __builtin_amdgcn_s_setprio(1); _Pragma("unroll") for (int m = 0; m < 4; ++m) _Pragma("unroll") for (int n = 0; n < 2; ++n) _Pragma("unroll") for (int k = 0; k < 2; ++k) \
;         acc[ai][bj][m][n] = __builtin_amdgcn_mfma_f32_16x16x32_bf16(Bt[n][k], At[m][k], acc[ai][bj][m][n], 0, 0, 0); __builtin_amdgcn_s_setprio(0); } while (0)
; #define PG8_WAIT_V(n) asm volatile("s_waitcnt vmcnt(" #n ")" ::: "memory")
; #define PG8_WAIT_L(n) asm volatile("s_waitcnt lgkmcnt(" #n ")" ::: "memory")
; #define PG8_BAR __builtin_amdgcn_s_barrier()
; #define PG8_SCHED __builtin_amdgcn_sched_barrier(0)
; template <class Epi, class Sched, bool ALIGN_EPI = false, bool SP2 = false>
; __device__ __forceinline__ void gemm_phase(PG8_LAS unsigned char* lds, const Gemm g, const Sched& S, const Epi& E, const int tid) {
;     ...
;             PG8_LDB(B0, 0, 0); PG8_LDB(B1, 0, 1); PG8_SCHED; PG8_LDA(At, 0, 0); PG8_STAGE(PG8_SA(1, 1), a1 + hstep, voffA);
;             PG8_WAIT_V(8); PG8_WAIT_L(0); PG8_BAR; PG8_MMA(0, 0, At, B0); PG8_MMA(0, 1, At, B1); PG8_BAR; PG8_SCHED;
;             PG8_LDA(At, 0, 1); PG8_STAGE(PG8_SB(0, 0), b2, voffB); PG8_STAGE(PG8_SB(0, 1), b2 + hstep, voffB); PG8_STAGE(PG8_SA(0, 0), a2, voffA);
;             PG8_WAIT_V(8); PG8_WAIT_L(0); PG8_BAR; PG8_MMA(1, 0, At, B0); PG8_MMA(1, 1, At, B1); PG8_BAR; PG8_SCHED;
.LBB0_143:
	v_add_u32_e32 v138, 0x10000, v140
	ds_read_b128 v[142:145], v138
	ds_read_b128 v[146:149], v138 offset:1024
	ds_read_b128 v[150:153], v138 offset:2048
	ds_read_b128 v[154:157], v138 offset:3072
	v_add_u32_e32 v138, 0x14000, v140
	ds_read_b128 v[158:161], v138
	ds_read_b128 v[162:165], v138 offset:1024
	ds_read_b128 v[166:169], v138 offset:2048
	ds_read_b128 v[170:173], v138 offset:3072
	s_add_u32 s58, s44, 0xfffc0080
	s_addc_u32 s59, s45, -1
	s_add_i32 s72, 0, 0x10000
	s_cmp_eq_u32 s71, 12
	s_cselect_b32 s79, s17, s59
	s_cselect_b32 s78, s55, s58
	s_cselect_b32 s59, s15, s70
	s_cselect_b32 s58, s60, s62
	s_add_i32 s74, 0, 0x14000
	v_lshl_add_u64 v[138:139], s[44:45], 0, v[134:135]
	s_add_i32 m0, s38, 0xc000
	ds_read_b128 v[174:177], v141
	ds_read_b128 v[178:181], v141 offset:1024
	ds_read_b128 v[182:185], v141 offset:2048
	ds_read_b128 v[186:189], v141 offset:3072
	ds_read_b128 v[212:215], v141 offset:4096
	ds_read_b128 v[216:219], v141 offset:5120
	ds_read_b128 v[232:235], v141 offset:6144
	ds_read_b128 v[236:239], v141 offset:7168
	global_load_lds_dwordx4 v[138:139], off
	v_lshl_add_u64 v[138:139], s[44:45], 0, v[136:137]
	s_add_i32 m0, s38, 0xe000
	s_nop 0
	global_load_lds_dwordx4 v[138:139], off
	s_waitcnt vmcnt(8)
	s_waitcnt lgkmcnt(0)
	s_barrier
	s_waitcnt lgkmcnt(0)
	v_mfma_f32_16x16x32_bf16 v[124:127], v[142:145], v[174:177], v[124:127]
	v_mfma_f32_16x16x32_bf16 v[116:119], v[150:153], v[174:177], v[116:119]
	v_mfma_f32_16x16x32_bf16 v[108:111], v[142:145], v[182:185], v[108:111]
	v_mfma_f32_16x16x32_bf16 v[100:103], v[150:153], v[182:185], v[100:103]
	v_mfma_f32_16x16x32_bf16 v[92:95], v[142:145], v[212:215], v[92:95]
	v_mfma_f32_16x16x32_bf16 v[84:87], v[150:153], v[212:215], v[84:87]
	v_mfma_f32_16x16x32_bf16 v[76:79], v[142:145], v[232:235], v[76:79]
	v_mfma_f32_16x16x32_bf16 v[68:71], v[150:153], v[232:235], v[68:71]
	v_mfma_f32_16x16x32_bf16 v[124:127], v[146:149], v[178:181], v[124:127]
	v_mfma_f32_16x16x32_bf16 v[116:119], v[154:157], v[178:181], v[116:119]
	v_mfma_f32_16x16x32_bf16 v[108:111], v[146:149], v[186:189], v[108:111]
	v_mfma_f32_16x16x32_bf16 v[100:103], v[154:157], v[186:189], v[100:103]
	v_mfma_f32_16x16x32_bf16 v[92:95], v[146:149], v[216:219], v[92:95]
	v_mfma_f32_16x16x32_bf16 v[84:87], v[154:157], v[216:219], v[84:87]
	v_mfma_f32_16x16x32_bf16 v[76:79], v[146:149], v[236:239], v[76:79]
	v_mfma_f32_16x16x32_bf16 v[68:71], v[154:157], v[236:239], v[68:71]
	v_mfma_f32_16x16x32_bf16 v[120:123], v[158:161], v[174:177], v[120:123]
	v_mfma_f32_16x16x32_bf16 v[112:115], v[166:169], v[174:177], v[112:115]
	v_mfma_f32_16x16x32_bf16 v[104:107], v[158:161], v[182:185], v[104:107]
	v_mfma_f32_16x16x32_bf16 v[96:99], v[166:169], v[182:185], v[96:99]
	v_mfma_f32_16x16x32_bf16 v[88:91], v[158:161], v[212:215], v[88:91]
	v_mfma_f32_16x16x32_bf16 v[80:83], v[166:169], v[212:215], v[80:83]
	v_mfma_f32_16x16x32_bf16 v[72:75], v[158:161], v[232:235], v[72:75]
	v_mfma_f32_16x16x32_bf16 v[64:67], v[166:169], v[232:235], v[64:67]
	v_mfma_f32_16x16x32_bf16 v[120:123], v[162:165], v[178:181], v[120:123]
	v_mfma_f32_16x16x32_bf16 v[112:115], v[170:173], v[178:181], v[112:115]
	v_mfma_f32_16x16x32_bf16 v[104:107], v[162:165], v[186:189], v[104:107]
	v_mfma_f32_16x16x32_bf16 v[96:99], v[170:173], v[186:189], v[96:99]
	v_mfma_f32_16x16x32_bf16 v[88:91], v[162:165], v[216:219], v[88:91]
	v_mfma_f32_16x16x32_bf16 v[80:83], v[170:173], v[216:219], v[80:83]
	v_mfma_f32_16x16x32_bf16 v[72:75], v[162:165], v[236:239], v[72:75]
	v_mfma_f32_16x16x32_bf16 v[64:67], v[170:173], v[236:239], v[64:67]
	s_barrier
	s_add_i32 s72, s72, s34
	v_lshl_add_u64 v[138:139], s[58:59], 0, v[192:193]
	s_mov_b32 m0, s72
	ds_read_b128 v[174:177], v141 offset:16384
	ds_read_b128 v[178:181], v141 offset:17408
	ds_read_b128 v[182:185], v141 offset:18432
	ds_read_b128 v[186:189], v141 offset:19456
	ds_read_b128 v[212:215], v141 offset:20480
	ds_read_b128 v[216:219], v141 offset:21504
	ds_read_b128 v[232:235], v141 offset:22528
	ds_read_b128 v[236:239], v141 offset:23552
	global_load_lds_dwordx4 v[138:139], off
	s_add_i32 m0, s72, 0x2000
	s_add_u32 s72, s58, 0x40000
	v_lshl_add_u64 v[190:191], s[58:59], 0, v[128:129]
	s_addc_u32 s73, s59, 0
	s_add_i32 s74, s74, s34
	global_load_lds_dwordx4 v[190:191], off
	v_lshl_add_u64 v[194:195], s[72:73], 0, v[192:193]
	s_mov_b32 m0, s74
	v_lshl_add_u64 v[196:197], s[78:79], 0, v[130:131]
	global_load_lds_dwordx4 v[194:195], off
	v_lshl_add_u64 v[194:195], s[72:73], 0, v[128:129]
	s_add_i32 m0, s74, 0x2000
	s_nop 0
	global_load_lds_dwordx4 v[194:195], off
	v_lshl_add_u64 v[194:195], s[78:79], 0, v[132:133]
	s_mov_b32 m0, s38
	s_nop 0
	global_load_lds_dwordx4 v[194:195], off
	s_mov_b32 m0, s40
	s_nop 0
	global_load_lds_dwordx4 v[196:197], off
	s_waitcnt vmcnt(8)
	s_waitcnt lgkmcnt(0)
	s_barrier
; #define PG8_STAGE(bufoff, gbase, voff) do { _Pragma("unroll") for (int _i = 0; _i < 2; ++_i) \
;         __builtin_amdgcn_global_load_lds((const unsigned*)((const char*)(gbase) + (voff)[_i]), (PG8_LAS unsigned*)(lds + (bufoff) + ldsw + _i * 8192), 16, 0, 0); } while (0)
; #define PG8_LDA(dst, b, h) do { _Pragma("unroll") for (int m = 0; m < 4; ++m) _Pragma("unroll") for (int k = 0; k < 2; ++k) dst[m][k] = *(const PG8_LAS bf16x8*)(lds + PG8_SA(b, h) + aoff + m * 2048 + k * 1024); } while (0)
; #define PG8_LDB(dst, b, h) do { _Pragma("unroll") for (int n = 0; n < 2; ++n) _Pragma("unroll") for (int k = 0; k < 2; ++k) dst[n][k] = *(const PG8_LAS bf16x8*)(lds + PG8_SB(b, h) + boff + n * 2048 + k * 1024); } while (0)
; #define PG8_MMA(ai, bj, At, Bt) do { __builtin_amdgcn_s_setprio(1); _Pragma("unroll") for (int m = 0; m < 4; ++m) _Pragma("unroll") for (int n = 0; n < 2; ++n) _Pragma("unroll") for (int k = 0; k < 2; ++k) \
;         acc[ai][bj][m][n] = __builtin_amdgcn_mfma_f32_16x16x32_bf16(Bt[n][k], At[m][k], acc[ai][bj][m][n], 0, 0, 0); __builtin_amdgcn_s_setprio(0); } while (0)
; #define PG8_WAIT_V(n) asm volatile("s_waitcnt vmcnt(" #n ")" ::: "memory")
; #define PG8_WAIT_L(n) asm volatile("s_waitcnt lgkmcnt(" #n ")" ::: "memory")
; #define PG8_BAR __builtin_amdgcn_s_barrier()
; #define PG8_SCHED __builtin_amdgcn_sched_barrier(0)
; template <class Epi, class Sched, bool ALIGN_EPI = false, bool SP2 = false>
; __device__ __forceinline__ void gemm_phase(PG8_LAS unsigned char* lds, const Gemm g, const Sched& S, const Epi& E, const int tid) {
;     ...
;             PG8_WAIT_V(8); PG8_WAIT_L(0); PG8_BAR; PG8_MMA(1, 0, At, B0); PG8_MMA(1, 1, At, B1); PG8_BAR; PG8_SCHED;
;             PG8_LDB(B0, 1, 0); PG8_LDB(B1, 1, 1); PG8_SCHED; PG8_LDA(At, 1, 0); PG8_STAGE(PG8_SA(0, 1), a2 + hstep, voffA);
;             PG8_WAIT_V(8); PG8_WAIT_L(0); PG8_BAR; PG8_MMA(0, 0, At, B0); PG8_MMA(0, 1, At, B1); PG8_BAR; PG8_SCHED;
	s_waitcnt lgkmcnt(0)
	v_mfma_f32_16x16x32_bf16 v[60:63], v[142:145], v[174:177], v[60:63]
	v_mfma_f32_16x16x32_bf16 v[52:55], v[150:153], v[174:177], v[52:55]
	v_mfma_f32_16x16x32_bf16 v[44:47], v[142:145], v[182:185], v[44:47]
	v_mfma_f32_16x16x32_bf16 v[36:39], v[150:153], v[182:185], v[36:39]
	v_mfma_f32_16x16x32_bf16 v[28:31], v[142:145], v[212:215], v[28:31]
	v_mfma_f32_16x16x32_bf16 v[20:23], v[150:153], v[212:215], v[20:23]
	v_mfma_f32_16x16x32_bf16 v[12:15], v[142:145], v[232:235], v[12:15]
	v_mfma_f32_16x16x32_bf16 v[4:7], v[150:153], v[232:235], v[4:7]
	v_mfma_f32_16x16x32_bf16 v[60:63], v[146:149], v[178:181], v[60:63]
	v_mfma_f32_16x16x32_bf16 v[52:55], v[154:157], v[178:181], v[52:55]
	v_mfma_f32_16x16x32_bf16 v[44:47], v[146:149], v[186:189], v[44:47]
	v_mfma_f32_16x16x32_bf16 v[36:39], v[154:157], v[186:189], v[36:39]
	v_mfma_f32_16x16x32_bf16 v[28:31], v[146:149], v[216:219], v[28:31]
	v_mfma_f32_16x16x32_bf16 v[20:23], v[154:157], v[216:219], v[20:23]
	v_mfma_f32_16x16x32_bf16 v[12:15], v[146:149], v[236:239], v[12:15]
	v_mfma_f32_16x16x32_bf16 v[4:7], v[154:157], v[236:239], v[4:7]
	v_mfma_f32_16x16x32_bf16 v[56:59], v[158:161], v[174:177], v[56:59]
	v_mfma_f32_16x16x32_bf16 v[48:51], v[166:169], v[174:177], v[48:51]
	v_mfma_f32_16x16x32_bf16 v[40:43], v[158:161], v[182:185], v[40:43]
	v_mfma_f32_16x16x32_bf16 v[32:35], v[166:169], v[182:185], v[32:35]
	v_mfma_f32_16x16x32_bf16 v[24:27], v[158:161], v[212:215], v[24:27]
	v_mfma_f32_16x16x32_bf16 v[16:19], v[166:169], v[212:215], v[16:19]
	v_mfma_f32_16x16x32_bf16 v[8:11], v[158:161], v[232:235], v[8:11]
	v_mfma_f32_16x16x32_bf16 v[0:3], v[166:169], v[232:235], v[0:3]
	v_mfma_f32_16x16x32_bf16 v[56:59], v[162:165], v[178:181], v[56:59]
	v_mfma_f32_16x16x32_bf16 v[48:51], v[170:173], v[178:181], v[48:51]
	v_mfma_f32_16x16x32_bf16 v[40:43], v[162:165], v[186:189], v[40:43]
	v_mfma_f32_16x16x32_bf16 v[32:35], v[170:173], v[186:189], v[32:35]
	v_mfma_f32_16x16x32_bf16 v[24:27], v[162:165], v[216:219], v[24:27]
	v_mfma_f32_16x16x32_bf16 v[16:19], v[170:173], v[216:219], v[16:19]
	v_mfma_f32_16x16x32_bf16 v[8:11], v[162:165], v[236:239], v[8:11]
	v_mfma_f32_16x16x32_bf16 v[0:3], v[170:173], v[236:239], v[0:3]
	s_barrier
	s_add_i32 s74, 0, 0x18000
	s_add_i32 s75, 0, 0x1c000
	v_add_u32_e32 v154, s74, v140
	v_add_u32_e32 v170, s75, v140
	ds_read_b128 v[142:145], v154
	ds_read_b128 v[146:149], v154 offset:1024
	ds_read_b128 v[150:153], v154 offset:2048
	ds_read_b128 v[154:157], v154 offset:3072
	ds_read_b128 v[158:161], v170
	ds_read_b128 v[162:165], v170 offset:1024
	ds_read_b128 v[166:169], v170 offset:2048
	ds_read_b128 v[170:173], v170 offset:3072
	s_add_u32 s72, s78, 0x40000
	s_addc_u32 s73, s79, 0
	s_mov_b32 m0, s41
	v_lshl_add_u64 v[202:203], s[72:73], 0, v[132:133]
	ds_read_b128 v[174:177], v141 offset:32768
	ds_read_b128 v[178:181], v141 offset:33792
	ds_read_b128 v[182:185], v141 offset:34816
	ds_read_b128 v[186:189], v141 offset:35840
	ds_read_b128 v[212:215], v141 offset:36864
	ds_read_b128 v[216:219], v141 offset:37888
	ds_read_b128 v[232:235], v141 offset:38912
	ds_read_b128 v[236:239], v141 offset:39936
	global_load_lds_dwordx4 v[202:203], off
	v_lshl_add_u64 v[202:203], s[72:73], 0, v[130:131]
	s_mov_b32 m0, s46
	s_nop 0
	global_load_lds_dwordx4 v[202:203], off
	s_waitcnt vmcnt(8)
	s_waitcnt lgkmcnt(0)
	s_barrier
	s_waitcnt lgkmcnt(0)
	v_mfma_f32_16x16x32_bf16 v[124:127], v[142:145], v[174:177], v[124:127]
	v_mfma_f32_16x16x32_bf16 v[116:119], v[150:153], v[174:177], v[116:119]
	v_mfma_f32_16x16x32_bf16 v[108:111], v[142:145], v[182:185], v[108:111]
	v_mfma_f32_16x16x32_bf16 v[100:103], v[150:153], v[182:185], v[100:103]
	v_mfma_f32_16x16x32_bf16 v[92:95], v[142:145], v[212:215], v[92:95]
	v_mfma_f32_16x16x32_bf16 v[84:87], v[150:153], v[212:215], v[84:87]
	v_mfma_f32_16x16x32_bf16 v[76:79], v[142:145], v[232:235], v[76:79]
	v_mfma_f32_16x16x32_bf16 v[68:71], v[150:153], v[232:235], v[68:71]
	v_mfma_f32_16x16x32_bf16 v[124:127], v[146:149], v[178:181], v[124:127]
	v_mfma_f32_16x16x32_bf16 v[116:119], v[154:157], v[178:181], v[116:119]
	v_mfma_f32_16x16x32_bf16 v[108:111], v[146:149], v[186:189], v[108:111]
	v_mfma_f32_16x16x32_bf16 v[100:103], v[154:157], v[186:189], v[100:103]
	v_mfma_f32_16x16x32_bf16 v[92:95], v[146:149], v[216:219], v[92:95]
	v_mfma_f32_16x16x32_bf16 v[84:87], v[154:157], v[216:219], v[84:87]
	v_mfma_f32_16x16x32_bf16 v[76:79], v[146:149], v[236:239], v[76:79]
	v_mfma_f32_16x16x32_bf16 v[68:71], v[154:157], v[236:239], v[68:71]
	v_mfma_f32_16x16x32_bf16 v[120:123], v[158:161], v[174:177], v[120:123]
	v_mfma_f32_16x16x32_bf16 v[112:115], v[166:169], v[174:177], v[112:115]
	v_mfma_f32_16x16x32_bf16 v[104:107], v[158:161], v[182:185], v[104:107]
	v_mfma_f32_16x16x32_bf16 v[96:99], v[166:169], v[182:185], v[96:99]
	v_mfma_f32_16x16x32_bf16 v[88:91], v[158:161], v[212:215], v[88:91]
	v_mfma_f32_16x16x32_bf16 v[80:83], v[166:169], v[212:215], v[80:83]
	v_mfma_f32_16x16x32_bf16 v[72:75], v[158:161], v[232:235], v[72:75]
	v_mfma_f32_16x16x32_bf16 v[64:67], v[166:169], v[232:235], v[64:67]
	v_mfma_f32_16x16x32_bf16 v[120:123], v[162:165], v[178:181], v[120:123]
	v_mfma_f32_16x16x32_bf16 v[112:115], v[170:173], v[178:181], v[112:115]
	v_mfma_f32_16x16x32_bf16 v[104:107], v[162:165], v[186:189], v[104:107]
	v_mfma_f32_16x16x32_bf16 v[96:99], v[170:173], v[186:189], v[96:99]
	v_mfma_f32_16x16x32_bf16 v[88:91], v[162:165], v[216:219], v[88:91]
	v_mfma_f32_16x16x32_bf16 v[80:83], v[170:173], v[216:219], v[80:83]
	v_mfma_f32_16x16x32_bf16 v[72:75], v[162:165], v[236:239], v[72:75]
	v_mfma_f32_16x16x32_bf16 v[64:67], v[170:173], v[236:239], v[64:67]
	s_barrier
; #define PG8_STAGE(bufoff, gbase, voff) do { _Pragma("unroll") for (int _i = 0; _i < 2; ++_i) \
;         __builtin_amdgcn_global_load_lds((const unsigned*)((const char*)(gbase) + (voff)[_i]), (PG8_LAS unsigned*)(lds + (bufoff) + ldsw + _i * 8192), 16, 0, 0); } while (0)
; #define PG8_LDA(dst, b, h) do { _Pragma("unroll") for (int m = 0; m < 4; ++m) _Pragma("unroll") for (int k = 0; k < 2; ++k) dst[m][k] = *(const PG8_LAS bf16x8*)(lds + PG8_SA(b, h) + aoff + m * 2048 + k * 1024); } while (0)
; #define PG8_MMA(ai, bj, At, Bt) do { __builtin_amdgcn_s_setprio(1); _Pragma("unroll") for (int m = 0; m < 4; ++m) _Pragma("unroll") for (int n = 0; n < 2; ++n) _Pragma("unroll") for (int k = 0; k < 2; ++k) \
;         acc[ai][bj][m][n] = __builtin_amdgcn_mfma_f32_16x16x32_bf16(Bt[n][k], At[m][k], acc[ai][bj][m][n], 0, 0, 0); __builtin_amdgcn_s_setprio(0); } while (0)
; #define PG8_WAIT_V(n) asm volatile("s_waitcnt vmcnt(" #n ")" ::: "memory")
; #define PG8_WAIT_L(n) asm volatile("s_waitcnt lgkmcnt(" #n ")" ::: "memory")
; #define PG8_BAR __builtin_amdgcn_s_barrier()
; #define PG8_SCHED __builtin_amdgcn_sched_barrier(0)
; template <class Epi, class Sched, bool ALIGN_EPI = false, bool SP2 = false>
; __device__ __forceinline__ void gemm_phase(PG8_LAS unsigned char* lds, const Gemm g, const Sched& S, const Epi& E, const int tid) {
;     ...
;             PG8_LDA(At, 1, 1); PG8_STAGE(PG8_SB(1, 0), b3, voffB); PG8_STAGE(PG8_SB(1, 1), b3 + hstep, voffB); PG8_STAGE(PG8_SA(1, 0), a3, voffA);
;             PG8_WAIT_V(8); PG8_WAIT_L(0); PG8_BAR; PG8_MMA(1, 0, At, B0); PG8_MMA(1, 1, At, B1); PG8_BAR; PG8_SCHED;
;     ...
;         if constexpr (ALIGN_EPI) { if (wr == 0) PG8_BAR; }
	s_add_i32 s72, s74, s34
	v_lshl_add_u64 v[138:139], v[138:139], 0, s[36:37]
	s_mov_b32 m0, s72
	ds_read_b128 v[174:177], v141 offset:49152
	ds_read_b128 v[178:181], v141 offset:50176
	ds_read_b128 v[182:185], v141 offset:51200
	ds_read_b128 v[186:189], v141 offset:52224
	ds_read_b128 v[212:215], v141 offset:53248
	ds_read_b128 v[216:219], v141 offset:54272
	ds_read_b128 v[232:235], v141 offset:55296
	ds_read_b128 v[236:239], v141 offset:56320
	global_load_lds_dwordx4 v[138:139], off
	s_add_i32 m0, s72, 0x2000
	s_add_u32 s58, s58, 0x40080
	v_lshl_add_u64 v[138:139], v[190:191], 0, s[36:37]
	s_addc_u32 s59, s59, 0
	s_add_i32 s72, s75, s34
	global_load_lds_dwordx4 v[138:139], off
	v_lshl_add_u64 v[138:139], s[58:59], 0, v[192:193]
	s_mov_b32 m0, s72
	s_nop 0
	global_load_lds_dwordx4 v[138:139], off
	v_lshl_add_u64 v[138:139], s[58:59], 0, v[128:129]
	s_add_i32 m0, s72, 0x2000
	s_nop 0
	global_load_lds_dwordx4 v[138:139], off
	v_lshl_add_u64 v[138:139], v[194:195], 0, s[36:37]
	s_mov_b32 m0, s47
	s_nop 0
	global_load_lds_dwordx4 v[138:139], off
	v_lshl_add_u64 v[138:139], v[196:197], 0, s[36:37]
	s_mov_b32 m0, s52
	s_nop 0
	global_load_lds_dwordx4 v[138:139], off
	s_add_i32 s71, s71, 2
	s_add_u32 s44, s44, 0x100
	s_addc_u32 s45, s45, 0
	s_add_u32 s62, s62, 0x100
	s_addc_u32 s70, s70, 0
	s_cmp_gt_u32 s71, 13
	s_waitcnt vmcnt(8)
	s_waitcnt lgkmcnt(0)
	s_barrier
	s_waitcnt lgkmcnt(0)
	v_mfma_f32_16x16x32_bf16 v[60:63], v[142:145], v[174:177], v[60:63]
	v_mfma_f32_16x16x32_bf16 v[52:55], v[150:153], v[174:177], v[52:55]
	v_mfma_f32_16x16x32_bf16 v[44:47], v[142:145], v[182:185], v[44:47]
	v_mfma_f32_16x16x32_bf16 v[36:39], v[150:153], v[182:185], v[36:39]
	v_mfma_f32_16x16x32_bf16 v[28:31], v[142:145], v[212:215], v[28:31]
	v_mfma_f32_16x16x32_bf16 v[20:23], v[150:153], v[212:215], v[20:23]
	v_mfma_f32_16x16x32_bf16 v[12:15], v[142:145], v[232:235], v[12:15]
	v_mfma_f32_16x16x32_bf16 v[4:7], v[150:153], v[232:235], v[4:7]
	v_mfma_f32_16x16x32_bf16 v[60:63], v[146:149], v[178:181], v[60:63]
	v_mfma_f32_16x16x32_bf16 v[52:55], v[154:157], v[178:181], v[52:55]
	v_mfma_f32_16x16x32_bf16 v[44:47], v[146:149], v[186:189], v[44:47]
	v_mfma_f32_16x16x32_bf16 v[36:39], v[154:157], v[186:189], v[36:39]
	v_mfma_f32_16x16x32_bf16 v[28:31], v[146:149], v[216:219], v[28:31]
	v_mfma_f32_16x16x32_bf16 v[20:23], v[154:157], v[216:219], v[20:23]
	v_mfma_f32_16x16x32_bf16 v[12:15], v[146:149], v[236:239], v[12:15]
	v_mfma_f32_16x16x32_bf16 v[4:7], v[154:157], v[236:239], v[4:7]
	v_mfma_f32_16x16x32_bf16 v[56:59], v[158:161], v[174:177], v[56:59]
	v_mfma_f32_16x16x32_bf16 v[48:51], v[166:169], v[174:177], v[48:51]
	v_mfma_f32_16x16x32_bf16 v[40:43], v[158:161], v[182:185], v[40:43]
	v_mfma_f32_16x16x32_bf16 v[32:35], v[166:169], v[182:185], v[32:35]
	v_mfma_f32_16x16x32_bf16 v[24:27], v[158:161], v[212:215], v[24:27]
	v_mfma_f32_16x16x32_bf16 v[16:19], v[166:169], v[212:215], v[16:19]
	v_mfma_f32_16x16x32_bf16 v[8:11], v[158:161], v[232:235], v[8:11]
	v_mfma_f32_16x16x32_bf16 v[0:3], v[166:169], v[232:235], v[0:3]
	v_mfma_f32_16x16x32_bf16 v[56:59], v[162:165], v[178:181], v[56:59]
	v_mfma_f32_16x16x32_bf16 v[48:51], v[170:173], v[178:181], v[48:51]
	v_mfma_f32_16x16x32_bf16 v[40:43], v[162:165], v[186:189], v[40:43]
	v_mfma_f32_16x16x32_bf16 v[32:35], v[170:173], v[186:189], v[32:35]
	v_mfma_f32_16x16x32_bf16 v[24:27], v[162:165], v[216:219], v[24:27]
	v_mfma_f32_16x16x32_bf16 v[16:19], v[170:173], v[216:219], v[16:19]
	v_mfma_f32_16x16x32_bf16 v[8:11], v[162:165], v[236:239], v[8:11]
	v_mfma_f32_16x16x32_bf16 v[0:3], v[170:173], v[236:239], v[0:3]
	s_barrier
	s_cbranch_scc0 .LBB0_143
	s_and_b64 vcc, exec, s[10:11]
	s_cbranch_vccz .LBB0_146
	s_barrier

; #define PG8_STAGE(bufoff, gbase, voff) do { _Pragma("unroll") for (int _i = 0; _i < 2; ++_i) \
;         __builtin_amdgcn_global_load_lds((const unsigned*)((const char*)(gbase) + (voff)[_i]), (PG8_LAS unsigned*)(lds + (bufoff) + ldsw + _i * 8192), 16, 0, 0); } while (0)
; #define PG8_LDA(dst, b, h) do { _Pragma("unroll") for (int m = 0; m < 4; ++m) _Pragma("unroll") for (int k = 0; k < 2; ++k) dst[m][k] = *(const PG8_LAS bf16x8*)(lds + PG8_SA(b, h) + aoff + m * 2048 + k * 1024); } while (0)
; #define PG8_LDB(dst, b, h) do { _Pragma("unroll") for (int n = 0; n < 2; ++n) _Pragma("unroll") for (int k = 0; k < 2; ++k) dst[n][k] = *(const PG8_LAS bf16x8*)(lds + PG8_SB(b, h) + boff + n * 2048 + k * 1024); } while (0)
; #define PG8_MMA(ai, bj, At, Bt) do { __builtin_amdgcn_s_setprio(1); _Pragma("unroll") for (int m = 0; m < 4; ++m) _Pragma("unroll") for (int n = 0; n < 2; ++n) _Pragma("unroll") for (int k = 0; k < 2; ++k) \
;         acc[ai][bj][m][n] = __builtin_amdgcn_mfma_f32_16x16x32_bf16(Bt[n][k], At[m][k], acc[ai][bj][m][n], 0, 0, 0); __builtin_amdgcn_s_setprio(0); } while (0)
; #define PG8_WAIT_V(n) asm volatile("s_waitcnt vmcnt(" #n ")" ::: "memory")
; #define PG8_WAIT_L(n) asm volatile("s_waitcnt lgkmcnt(" #n ")" ::: "memory")
; #define PG8_BAR __builtin_amdgcn_s_barrier()
; #define PG8_SCHED __builtin_amdgcn_sched_barrier(0)
; template <class Epi, class Sched, bool ALIGN_EPI = false, bool SP2 = false>
; __device__ __forceinline__ void gemm_phase(PG8_LAS unsigned char* lds, const Gemm g, const Sched& S, const Epi& E, const int tid) {
;     ...
;             PG8_LDB(B0, 0, 0); PG8_LDB(B1, 0, 1); PG8_SCHED; PG8_LDA(At, 0, 0); PG8_STAGE(PG8_SA(1, 1), a1 + hstep, voffA);
;             PG8_WAIT_V(8); PG8_WAIT_L(0); PG8_BAR; PG8_MMA(0, 0, At, B0); PG8_MMA(0, 1, At, B1); PG8_BAR; PG8_SCHED;
;             PG8_LDA(At, 0, 1); PG8_STAGE(PG8_SB(0, 0), b2, voffB); PG8_STAGE(PG8_SB(0, 1), b2 + hstep, voffB); PG8_STAGE(PG8_SA(0, 0), a2, voffA);
;             PG8_WAIT_V(8); PG8_WAIT_L(0); PG8_BAR; PG8_MMA(1, 0, At, B0); PG8_MMA(1, 1, At, B1); PG8_BAR; PG8_SCHED;
.LBB0_183:
	v_add_u32_e32 v154, 0x10000, v140
	v_add_u32_e32 v170, 0x14000, v140
	ds_read_b128 v[142:145], v154
	ds_read_b128 v[146:149], v154 offset:1024
	ds_read_b128 v[150:153], v154 offset:2048
	ds_read_b128 v[154:157], v154 offset:3072
	ds_read_b128 v[158:161], v170
	ds_read_b128 v[162:165], v170 offset:1024
	ds_read_b128 v[166:169], v170 offset:2048
	ds_read_b128 v[170:173], v170 offset:3072
	s_add_u32 s28, s22, 0xfffc0080
	s_addc_u32 s29, s23, -1
	s_add_i32 s71, 0, 0x10000
	s_cmp_eq_u32 s70, 12
	s_cselect_b32 s45, s17, s29
	s_cselect_b32 s44, s58, s28
	s_cselect_b32 s29, s13, s62
	s_cselect_b32 s28, s59, s60
	s_add_i32 s74, 0, 0x14000
	v_lshl_add_u64 v[190:191], s[22:23], 0, v[136:137]
	s_add_i32 m0, s15, 0xc000
	ds_read_b128 v[174:177], v141
	ds_read_b128 v[178:181], v141 offset:1024
	ds_read_b128 v[182:185], v141 offset:2048
	ds_read_b128 v[186:189], v141 offset:3072
	ds_read_b128 v[212:215], v141 offset:4096
	ds_read_b128 v[216:219], v141 offset:5120
	ds_read_b128 v[232:235], v141 offset:6144
	ds_read_b128 v[236:239], v141 offset:7168
	global_load_lds_dwordx4 v[190:191], off
	v_lshl_add_u64 v[190:191], s[22:23], 0, v[138:139]
	s_add_i32 m0, s15, 0xe000
	s_nop 0
	global_load_lds_dwordx4 v[190:191], off
	s_waitcnt vmcnt(8)
	s_waitcnt lgkmcnt(0)
	s_barrier
	s_waitcnt lgkmcnt(0)
	v_mfma_f32_16x16x32_bf16 v[124:127], v[142:145], v[174:177], v[124:127]
	v_mfma_f32_16x16x32_bf16 v[120:123], v[150:153], v[174:177], v[120:123]
	v_mfma_f32_16x16x32_bf16 v[116:119], v[142:145], v[182:185], v[116:119]
	v_mfma_f32_16x16x32_bf16 v[112:115], v[150:153], v[182:185], v[112:115]
	v_mfma_f32_16x16x32_bf16 v[100:103], v[142:145], v[212:215], v[100:103]
	v_mfma_f32_16x16x32_bf16 v[96:99], v[150:153], v[212:215], v[96:99]
	v_mfma_f32_16x16x32_bf16 v[84:87], v[142:145], v[232:235], v[84:87]
	v_mfma_f32_16x16x32_bf16 v[80:83], v[150:153], v[232:235], v[80:83]
	v_mfma_f32_16x16x32_bf16 v[124:127], v[146:149], v[178:181], v[124:127]
	v_mfma_f32_16x16x32_bf16 v[120:123], v[154:157], v[178:181], v[120:123]
	v_mfma_f32_16x16x32_bf16 v[116:119], v[146:149], v[186:189], v[116:119]
	v_mfma_f32_16x16x32_bf16 v[112:115], v[154:157], v[186:189], v[112:115]
	v_mfma_f32_16x16x32_bf16 v[100:103], v[146:149], v[216:219], v[100:103]
	v_mfma_f32_16x16x32_bf16 v[96:99], v[154:157], v[216:219], v[96:99]
	v_mfma_f32_16x16x32_bf16 v[84:87], v[146:149], v[236:239], v[84:87]
	v_mfma_f32_16x16x32_bf16 v[80:83], v[154:157], v[236:239], v[80:83]
	v_mfma_f32_16x16x32_bf16 v[108:111], v[158:161], v[174:177], v[108:111]
	v_mfma_f32_16x16x32_bf16 v[104:107], v[166:169], v[174:177], v[104:107]
	v_mfma_f32_16x16x32_bf16 v[92:95], v[158:161], v[182:185], v[92:95]
	v_mfma_f32_16x16x32_bf16 v[88:91], v[166:169], v[182:185], v[88:91]
	v_mfma_f32_16x16x32_bf16 v[76:79], v[158:161], v[212:215], v[76:79]
	v_mfma_f32_16x16x32_bf16 v[72:75], v[166:169], v[212:215], v[72:75]
	v_mfma_f32_16x16x32_bf16 v[68:71], v[158:161], v[232:235], v[68:71]
	v_mfma_f32_16x16x32_bf16 v[64:67], v[166:169], v[232:235], v[64:67]
	v_mfma_f32_16x16x32_bf16 v[108:111], v[162:165], v[178:181], v[108:111]
	v_mfma_f32_16x16x32_bf16 v[104:107], v[170:173], v[178:181], v[104:107]
	v_mfma_f32_16x16x32_bf16 v[92:95], v[162:165], v[186:189], v[92:95]
	v_mfma_f32_16x16x32_bf16 v[88:91], v[170:173], v[186:189], v[88:91]
	v_mfma_f32_16x16x32_bf16 v[76:79], v[162:165], v[216:219], v[76:79]
	v_mfma_f32_16x16x32_bf16 v[72:75], v[170:173], v[216:219], v[72:75]
	v_mfma_f32_16x16x32_bf16 v[68:71], v[162:165], v[236:239], v[68:71]
	v_mfma_f32_16x16x32_bf16 v[64:67], v[170:173], v[236:239], v[64:67]
	s_barrier
	s_add_i32 s71, s71, s38
	v_lshl_add_u64 v[190:191], s[28:29], 0, v[192:193]
	s_mov_b32 m0, s71
	ds_read_b128 v[174:177], v141 offset:16384
	ds_read_b128 v[178:181], v141 offset:17408
	ds_read_b128 v[182:185], v141 offset:18432
	ds_read_b128 v[186:189], v141 offset:19456
	ds_read_b128 v[212:215], v141 offset:20480
	ds_read_b128 v[216:219], v141 offset:21504
	ds_read_b128 v[232:235], v141 offset:22528
	ds_read_b128 v[236:239], v141 offset:23552
	global_load_lds_dwordx4 v[190:191], off
	s_add_i32 m0, s71, 0x2000
	s_add_u32 s72, s28, 0x40000
	v_lshl_add_u64 v[194:195], s[28:29], 0, v[132:133]
	s_addc_u32 s73, s29, 0
	s_add_i32 s71, s74, s38
	global_load_lds_dwordx4 v[194:195], off
	v_lshl_add_u64 v[196:197], s[72:73], 0, v[192:193]
	s_mov_b32 m0, s71
	v_lshl_add_u64 v[202:203], s[44:45], 0, v[130:131]
	global_load_lds_dwordx4 v[196:197], off
	v_lshl_add_u64 v[196:197], s[72:73], 0, v[132:133]
	s_add_i32 m0, s71, 0x2000
	s_nop 0
	global_load_lds_dwordx4 v[196:197], off
	v_lshl_add_u64 v[196:197], s[44:45], 0, v[128:129]
	s_mov_b32 m0, s15
	s_nop 0
	global_load_lds_dwordx4 v[196:197], off
	s_mov_b32 m0, s40
	s_nop 0
	global_load_lds_dwordx4 v[202:203], off
	s_waitcnt vmcnt(8)
	s_waitcnt lgkmcnt(0)
	s_barrier
; #define PG8_STAGE(bufoff, gbase, voff) do { _Pragma("unroll") for (int _i = 0; _i < 2; ++_i) \
;         __builtin_amdgcn_global_load_lds((const unsigned*)((const char*)(gbase) + (voff)[_i]), (PG8_LAS unsigned*)(lds + (bufoff) + ldsw + _i * 8192), 16, 0, 0); } while (0)
; #define PG8_LDA(dst, b, h) do { _Pragma("unroll") for (int m = 0; m < 4; ++m) _Pragma("unroll") for (int k = 0; k < 2; ++k) dst[m][k] = *(const PG8_LAS bf16x8*)(lds + PG8_SA(b, h) + aoff + m * 2048 + k * 1024); } while (0)
; #define PG8_LDB(dst, b, h) do { _Pragma("unroll") for (int n = 0; n < 2; ++n) _Pragma("unroll") for (int k = 0; k < 2; ++k) dst[n][k] = *(const PG8_LAS bf16x8*)(lds + PG8_SB(b, h) + boff + n * 2048 + k * 1024); } while (0)
; #define PG8_MMA(ai, bj, At, Bt) do { __builtin_amdgcn_s_setprio(1); _Pragma("unroll") for (int m = 0; m < 4; ++m) _Pragma("unroll") for (int n = 0; n < 2; ++n) _Pragma("unroll") for (int k = 0; k < 2; ++k) \
;         acc[ai][bj][m][n] = __builtin_amdgcn_mfma_f32_16x16x32_bf16(Bt[n][k], At[m][k], acc[ai][bj][m][n], 0, 0, 0); __builtin_amdgcn_s_setprio(0); } while (0)
; #define PG8_WAIT_V(n) asm volatile("s_waitcnt vmcnt(" #n ")" ::: "memory")
; #define PG8_WAIT_L(n) asm volatile("s_waitcnt lgkmcnt(" #n ")" ::: "memory")
; #define PG8_BAR __builtin_amdgcn_s_barrier()
; #define PG8_SCHED __builtin_amdgcn_sched_barrier(0)
; template <class Epi, class Sched, bool ALIGN_EPI = false, bool SP2 = false>
; __device__ __forceinline__ void gemm_phase(PG8_LAS unsigned char* lds, const Gemm g, const Sched& S, const Epi& E, const int tid) {
;     ...
;             PG8_WAIT_V(8); PG8_WAIT_L(0); PG8_BAR; PG8_MMA(1, 0, At, B0); PG8_MMA(1, 1, At, B1); PG8_BAR; PG8_SCHED;
;             PG8_LDB(B0, 1, 0); PG8_LDB(B1, 1, 1); PG8_SCHED; PG8_LDA(At, 1, 0); PG8_STAGE(PG8_SA(0, 1), a2 + hstep, voffA);
;             PG8_WAIT_V(8); PG8_WAIT_L(0); PG8_BAR; PG8_MMA(0, 0, At, B0); PG8_MMA(0, 1, At, B1); PG8_BAR; PG8_SCHED;
	s_waitcnt lgkmcnt(0)
	v_mfma_f32_16x16x32_bf16 v[60:63], v[142:145], v[174:177], v[60:63]
	v_mfma_f32_16x16x32_bf16 v[56:59], v[150:153], v[174:177], v[56:59]
	v_mfma_f32_16x16x32_bf16 v[52:55], v[142:145], v[182:185], v[52:55]
	v_mfma_f32_16x16x32_bf16 v[48:51], v[150:153], v[182:185], v[48:51]
	v_mfma_f32_16x16x32_bf16 v[36:39], v[142:145], v[212:215], v[36:39]
	v_mfma_f32_16x16x32_bf16 v[32:35], v[150:153], v[212:215], v[32:35]
	v_mfma_f32_16x16x32_bf16 v[20:23], v[142:145], v[232:235], v[20:23]
	v_mfma_f32_16x16x32_bf16 v[16:19], v[150:153], v[232:235], v[16:19]
	v_mfma_f32_16x16x32_bf16 v[60:63], v[146:149], v[178:181], v[60:63]
	v_mfma_f32_16x16x32_bf16 v[56:59], v[154:157], v[178:181], v[56:59]
	v_mfma_f32_16x16x32_bf16 v[52:55], v[146:149], v[186:189], v[52:55]
	v_mfma_f32_16x16x32_bf16 v[48:51], v[154:157], v[186:189], v[48:51]
	v_mfma_f32_16x16x32_bf16 v[36:39], v[146:149], v[216:219], v[36:39]
	v_mfma_f32_16x16x32_bf16 v[32:35], v[154:157], v[216:219], v[32:35]
	v_mfma_f32_16x16x32_bf16 v[20:23], v[146:149], v[236:239], v[20:23]
	v_mfma_f32_16x16x32_bf16 v[16:19], v[154:157], v[236:239], v[16:19]
	v_mfma_f32_16x16x32_bf16 v[44:47], v[158:161], v[174:177], v[44:47]
	v_mfma_f32_16x16x32_bf16 v[40:43], v[166:169], v[174:177], v[40:43]
	v_mfma_f32_16x16x32_bf16 v[28:31], v[158:161], v[182:185], v[28:31]
	v_mfma_f32_16x16x32_bf16 v[24:27], v[166:169], v[182:185], v[24:27]
	v_mfma_f32_16x16x32_bf16 v[12:15], v[158:161], v[212:215], v[12:15]
	v_mfma_f32_16x16x32_bf16 v[8:11], v[166:169], v[212:215], v[8:11]
	v_mfma_f32_16x16x32_bf16 v[4:7], v[158:161], v[232:235], v[4:7]
	v_mfma_f32_16x16x32_bf16 v[0:3], v[166:169], v[232:235], v[0:3]
	v_mfma_f32_16x16x32_bf16 v[44:47], v[162:165], v[178:181], v[44:47]
	v_mfma_f32_16x16x32_bf16 v[40:43], v[170:173], v[178:181], v[40:43]
	v_mfma_f32_16x16x32_bf16 v[28:31], v[162:165], v[186:189], v[28:31]
	v_mfma_f32_16x16x32_bf16 v[24:27], v[170:173], v[186:189], v[24:27]
	v_mfma_f32_16x16x32_bf16 v[12:15], v[162:165], v[216:219], v[12:15]
	v_mfma_f32_16x16x32_bf16 v[8:11], v[170:173], v[216:219], v[8:11]
	v_mfma_f32_16x16x32_bf16 v[4:7], v[162:165], v[236:239], v[4:7]
	v_mfma_f32_16x16x32_bf16 v[0:3], v[170:173], v[236:239], v[0:3]
	s_barrier
	s_add_i32 s71, 0, 0x18000
	s_add_i32 s72, 0, 0x1c000
	v_add_u32_e32 v154, s71, v140
	v_add_u32_e32 v170, s72, v140
	ds_read_b128 v[142:145], v154
	ds_read_b128 v[146:149], v154 offset:1024
	ds_read_b128 v[150:153], v154 offset:2048
	ds_read_b128 v[154:157], v154 offset:3072
	ds_read_b128 v[158:161], v170
	ds_read_b128 v[162:165], v170 offset:1024
	ds_read_b128 v[166:169], v170 offset:2048
	ds_read_b128 v[170:173], v170 offset:3072
	s_add_u32 s44, s44, 0x40000
	s_addc_u32 s45, s45, 0
	s_mov_b32 m0, s41
	v_lshl_add_u64 v[204:205], s[44:45], 0, v[128:129]
	ds_read_b128 v[174:177], v141 offset:32768
	ds_read_b128 v[178:181], v141 offset:33792
	ds_read_b128 v[182:185], v141 offset:34816
	ds_read_b128 v[186:189], v141 offset:35840
	ds_read_b128 v[212:215], v141 offset:36864
	ds_read_b128 v[216:219], v141 offset:37888
	ds_read_b128 v[232:235], v141 offset:38912
	ds_read_b128 v[236:239], v141 offset:39936
	global_load_lds_dwordx4 v[204:205], off
	v_lshl_add_u64 v[204:205], s[44:45], 0, v[130:131]
	s_mov_b32 m0, s46
	s_nop 0
	global_load_lds_dwordx4 v[204:205], off
	s_waitcnt vmcnt(8)
	s_waitcnt lgkmcnt(0)
	s_barrier
	s_waitcnt lgkmcnt(0)
	v_mfma_f32_16x16x32_bf16 v[124:127], v[142:145], v[174:177], v[124:127]
	v_mfma_f32_16x16x32_bf16 v[120:123], v[150:153], v[174:177], v[120:123]
	v_mfma_f32_16x16x32_bf16 v[116:119], v[142:145], v[182:185], v[116:119]
	v_mfma_f32_16x16x32_bf16 v[112:115], v[150:153], v[182:185], v[112:115]
	v_mfma_f32_16x16x32_bf16 v[100:103], v[142:145], v[212:215], v[100:103]
	v_mfma_f32_16x16x32_bf16 v[96:99], v[150:153], v[212:215], v[96:99]
	v_mfma_f32_16x16x32_bf16 v[84:87], v[142:145], v[232:235], v[84:87]
	v_mfma_f32_16x16x32_bf16 v[80:83], v[150:153], v[232:235], v[80:83]
	v_mfma_f32_16x16x32_bf16 v[124:127], v[146:149], v[178:181], v[124:127]
	v_mfma_f32_16x16x32_bf16 v[120:123], v[154:157], v[178:181], v[120:123]
	v_mfma_f32_16x16x32_bf16 v[116:119], v[146:149], v[186:189], v[116:119]
	v_mfma_f32_16x16x32_bf16 v[112:115], v[154:157], v[186:189], v[112:115]
	v_mfma_f32_16x16x32_bf16 v[100:103], v[146:149], v[216:219], v[100:103]
	v_mfma_f32_16x16x32_bf16 v[96:99], v[154:157], v[216:219], v[96:99]
	v_mfma_f32_16x16x32_bf16 v[84:87], v[146:149], v[236:239], v[84:87]
	v_mfma_f32_16x16x32_bf16 v[80:83], v[154:157], v[236:239], v[80:83]
	v_mfma_f32_16x16x32_bf16 v[108:111], v[158:161], v[174:177], v[108:111]
	v_mfma_f32_16x16x32_bf16 v[104:107], v[166:169], v[174:177], v[104:107]
	v_mfma_f32_16x16x32_bf16 v[92:95], v[158:161], v[182:185], v[92:95]
	v_mfma_f32_16x16x32_bf16 v[88:91], v[166:169], v[182:185], v[88:91]
	v_mfma_f32_16x16x32_bf16 v[76:79], v[158:161], v[212:215], v[76:79]
	v_mfma_f32_16x16x32_bf16 v[72:75], v[166:169], v[212:215], v[72:75]
	v_mfma_f32_16x16x32_bf16 v[68:71], v[158:161], v[232:235], v[68:71]
	v_mfma_f32_16x16x32_bf16 v[64:67], v[166:169], v[232:235], v[64:67]
	v_mfma_f32_16x16x32_bf16 v[108:111], v[162:165], v[178:181], v[108:111]
	v_mfma_f32_16x16x32_bf16 v[104:107], v[170:173], v[178:181], v[104:107]
	v_mfma_f32_16x16x32_bf16 v[92:95], v[162:165], v[186:189], v[92:95]
	v_mfma_f32_16x16x32_bf16 v[88:91], v[170:173], v[186:189], v[88:91]
	v_mfma_f32_16x16x32_bf16 v[76:79], v[162:165], v[216:219], v[76:79]
	v_mfma_f32_16x16x32_bf16 v[72:75], v[170:173], v[216:219], v[72:75]
	v_mfma_f32_16x16x32_bf16 v[68:71], v[162:165], v[236:239], v[68:71]
	v_mfma_f32_16x16x32_bf16 v[64:67], v[170:173], v[236:239], v[64:67]
	s_barrier
; #define PG8_STAGE(bufoff, gbase, voff) do { _Pragma("unroll") for (int _i = 0; _i < 2; ++_i) \
;         __builtin_amdgcn_global_load_lds((const unsigned*)((const char*)(gbase) + (voff)[_i]), (PG8_LAS unsigned*)(lds + (bufoff) + ldsw + _i * 8192), 16, 0, 0); } while (0)
; #define PG8_LDA(dst, b, h) do { _Pragma("unroll") for (int m = 0; m < 4; ++m) _Pragma("unroll") for (int k = 0; k < 2; ++k) dst[m][k] = *(const PG8_LAS bf16x8*)(lds + PG8_SA(b, h) + aoff + m * 2048 + k * 1024); } while (0)
; #define PG8_MMA(ai, bj, At, Bt) do { __builtin_amdgcn_s_setprio(1); _Pragma("unroll") for (int m = 0; m < 4; ++m) _Pragma("unroll") for (int n = 0; n < 2; ++n) _Pragma("unroll") for (int k = 0; k < 2; ++k) \
;         acc[ai][bj][m][n] = __builtin_amdgcn_mfma_f32_16x16x32_bf16(Bt[n][k], At[m][k], acc[ai][bj][m][n], 0, 0, 0); __builtin_amdgcn_s_setprio(0); } while (0)
; #define PG8_WAIT_V(n) asm volatile("s_waitcnt vmcnt(" #n ")" ::: "memory")
; #define PG8_WAIT_L(n) asm volatile("s_waitcnt lgkmcnt(" #n ")" ::: "memory")
; #define PG8_BAR __builtin_amdgcn_s_barrier()
; #define PG8_SCHED __builtin_amdgcn_sched_barrier(0)
; template <class Epi, class Sched, bool ALIGN_EPI = false, bool SP2 = false>
; __device__ __forceinline__ void gemm_phase(PG8_LAS unsigned char* lds, const Gemm g, const Sched& S, const Epi& E, const int tid) {
;     ...
;             PG8_LDA(At, 1, 1); PG8_STAGE(PG8_SB(1, 0), b3, voffB); PG8_STAGE(PG8_SB(1, 1), b3 + hstep, voffB); PG8_STAGE(PG8_SA(1, 0), a3, voffA);
;             PG8_WAIT_V(8); PG8_WAIT_L(0); PG8_BAR; PG8_MMA(1, 0, At, B0); PG8_MMA(1, 1, At, B1); PG8_BAR; PG8_SCHED;
;     ...
;         if constexpr (ALIGN_EPI) { if (wr == 0) PG8_BAR; }
	s_add_i32 s44, s71, s38
	v_lshl_add_u64 v[190:191], v[190:191], 0, s[36:37]
	s_mov_b32 m0, s44
	ds_read_b128 v[174:177], v141 offset:49152
	ds_read_b128 v[178:181], v141 offset:50176
	ds_read_b128 v[182:185], v141 offset:51200
	ds_read_b128 v[186:189], v141 offset:52224
	ds_read_b128 v[212:215], v141 offset:53248
	ds_read_b128 v[216:219], v141 offset:54272
	ds_read_b128 v[232:235], v141 offset:55296
	ds_read_b128 v[236:239], v141 offset:56320
	global_load_lds_dwordx4 v[190:191], off
	s_add_i32 m0, s44, 0x2000
	s_add_u32 s28, s28, 0x40080
	v_lshl_add_u64 v[190:191], v[194:195], 0, s[36:37]
	s_addc_u32 s29, s29, 0
	s_add_i32 s44, s72, s38
	global_load_lds_dwordx4 v[190:191], off
	v_lshl_add_u64 v[190:191], s[28:29], 0, v[192:193]
	s_mov_b32 m0, s44
	s_nop 0
	global_load_lds_dwordx4 v[190:191], off
	v_lshl_add_u64 v[190:191], s[28:29], 0, v[132:133]
	s_add_i32 m0, s44, 0x2000
	s_nop 0
	global_load_lds_dwordx4 v[190:191], off
	v_lshl_add_u64 v[190:191], v[196:197], 0, s[36:37]
	s_mov_b32 m0, s47
	s_nop 0
	global_load_lds_dwordx4 v[190:191], off
	v_lshl_add_u64 v[190:191], v[202:203], 0, s[36:37]
	s_mov_b32 m0, s52
	s_nop 0
	global_load_lds_dwordx4 v[190:191], off
	s_add_i32 s70, s70, 2
	s_add_u32 s22, s22, 0x100
	s_addc_u32 s23, s23, 0
	s_add_u32 s60, s60, 0x100
	s_addc_u32 s62, s62, 0
	s_cmp_gt_u32 s70, 13
	s_waitcnt vmcnt(8)
	s_waitcnt lgkmcnt(0)
	s_barrier
	s_waitcnt lgkmcnt(0)
	v_mfma_f32_16x16x32_bf16 v[60:63], v[142:145], v[174:177], v[60:63]
	v_mfma_f32_16x16x32_bf16 v[56:59], v[150:153], v[174:177], v[56:59]
	v_mfma_f32_16x16x32_bf16 v[52:55], v[142:145], v[182:185], v[52:55]
	v_mfma_f32_16x16x32_bf16 v[48:51], v[150:153], v[182:185], v[48:51]
	v_mfma_f32_16x16x32_bf16 v[36:39], v[142:145], v[212:215], v[36:39]
	v_mfma_f32_16x16x32_bf16 v[32:35], v[150:153], v[212:215], v[32:35]
	v_mfma_f32_16x16x32_bf16 v[20:23], v[142:145], v[232:235], v[20:23]
	v_mfma_f32_16x16x32_bf16 v[16:19], v[150:153], v[232:235], v[16:19]
	v_mfma_f32_16x16x32_bf16 v[60:63], v[146:149], v[178:181], v[60:63]
	v_mfma_f32_16x16x32_bf16 v[56:59], v[154:157], v[178:181], v[56:59]
	v_mfma_f32_16x16x32_bf16 v[52:55], v[146:149], v[186:189], v[52:55]
	v_mfma_f32_16x16x32_bf16 v[48:51], v[154:157], v[186:189], v[48:51]
	v_mfma_f32_16x16x32_bf16 v[36:39], v[146:149], v[216:219], v[36:39]
	v_mfma_f32_16x16x32_bf16 v[32:35], v[154:157], v[216:219], v[32:35]
	v_mfma_f32_16x16x32_bf16 v[20:23], v[146:149], v[236:239], v[20:23]
	v_mfma_f32_16x16x32_bf16 v[16:19], v[154:157], v[236:239], v[16:19]
	v_mfma_f32_16x16x32_bf16 v[44:47], v[158:161], v[174:177], v[44:47]
	v_mfma_f32_16x16x32_bf16 v[40:43], v[166:169], v[174:177], v[40:43]
	v_mfma_f32_16x16x32_bf16 v[28:31], v[158:161], v[182:185], v[28:31]
	v_mfma_f32_16x16x32_bf16 v[24:27], v[166:169], v[182:185], v[24:27]
	v_mfma_f32_16x16x32_bf16 v[12:15], v[158:161], v[212:215], v[12:15]
	v_mfma_f32_16x16x32_bf16 v[8:11], v[166:169], v[212:215], v[8:11]
	v_mfma_f32_16x16x32_bf16 v[4:7], v[158:161], v[232:235], v[4:7]
	v_mfma_f32_16x16x32_bf16 v[0:3], v[166:169], v[232:235], v[0:3]
	v_mfma_f32_16x16x32_bf16 v[44:47], v[162:165], v[178:181], v[44:47]
	v_mfma_f32_16x16x32_bf16 v[40:43], v[170:173], v[178:181], v[40:43]
	v_mfma_f32_16x16x32_bf16 v[28:31], v[162:165], v[186:189], v[28:31]
	v_mfma_f32_16x16x32_bf16 v[24:27], v[170:173], v[186:189], v[24:27]
	v_mfma_f32_16x16x32_bf16 v[12:15], v[162:165], v[216:219], v[12:15]
	v_mfma_f32_16x16x32_bf16 v[8:11], v[170:173], v[216:219], v[8:11]
	v_mfma_f32_16x16x32_bf16 v[4:7], v[162:165], v[236:239], v[4:7]
	v_mfma_f32_16x16x32_bf16 v[0:3], v[170:173], v[236:239], v[0:3]
	s_barrier
	s_cbranch_scc0 .LBB0_183
	s_and_b64 vcc, exec, s[10:11]
	s_cbranch_vccz .LBB0_186
	s_barrier

; #define PG8_STAGE(bufoff, gbase, voff) do { _Pragma("unroll") for (int _i = 0; _i < 2; ++_i) \
;         __builtin_amdgcn_global_load_lds((const unsigned*)((const char*)(gbase) + (voff)[_i]), (PG8_LAS unsigned*)(lds + (bufoff) + ldsw + _i * 8192), 16, 0, 0); } while (0)
; #define PG8_LDA(dst, b, h) do { _Pragma("unroll") for (int m = 0; m < 4; ++m) _Pragma("unroll") for (int k = 0; k < 2; ++k) dst[m][k] = *(const PG8_LAS bf16x8*)(lds + PG8_SA(b, h) + aoff + m * 2048 + k * 1024); } while (0)
; #define PG8_LDB(dst, b, h) do { _Pragma("unroll") for (int n = 0; n < 2; ++n) _Pragma("unroll") for (int k = 0; k < 2; ++k) dst[n][k] = *(const PG8_LAS bf16x8*)(lds + PG8_SB(b, h) + boff + n * 2048 + k * 1024); } while (0)
; #define PG8_MMA(ai, bj, At, Bt) do { __builtin_amdgcn_s_setprio(1); _Pragma("unroll") for (int m = 0; m < 4; ++m) _Pragma("unroll") for (int n = 0; n < 2; ++n) _Pragma("unroll") for (int k = 0; k < 2; ++k) \
;         acc[ai][bj][m][n] = __builtin_amdgcn_mfma_f32_16x16x32_bf16(Bt[n][k], At[m][k], acc[ai][bj][m][n], 0, 0, 0); __builtin_amdgcn_s_setprio(0); } while (0)
; #define PG8_WAIT_V(n) asm volatile("s_waitcnt vmcnt(" #n ")" ::: "memory")
; #define PG8_WAIT_L(n) asm volatile("s_waitcnt lgkmcnt(" #n ")" ::: "memory")
; #define PG8_BAR __builtin_amdgcn_s_barrier()
; #define PG8_SCHED __builtin_amdgcn_sched_barrier(0)
; template <class Epi, class Sched, bool ALIGN_EPI = false, bool SP2 = false>
; __device__ __forceinline__ void gemm_phase(PG8_LAS unsigned char* lds, const Gemm g, const Sched& S, const Epi& E, const int tid) {
;     ...
;             PG8_LDB(B0, 0, 0); PG8_LDB(B1, 0, 1); PG8_SCHED; PG8_LDA(At, 0, 0); PG8_STAGE(PG8_SA(1, 1), a1 + hstep, voffA);
;             PG8_WAIT_V(8); PG8_WAIT_L(0); PG8_BAR; PG8_MMA(0, 0, At, B0); PG8_MMA(0, 1, At, B1); PG8_BAR; PG8_SCHED;
;             PG8_LDA(At, 0, 1); PG8_STAGE(PG8_SB(0, 0), b2, voffB); PG8_STAGE(PG8_SB(0, 1), b2 + hstep, voffB); PG8_STAGE(PG8_SA(0, 0), a2, voffA);
;             PG8_WAIT_V(8); PG8_WAIT_L(0); PG8_BAR; PG8_MMA(1, 0, At, B0); PG8_MMA(1, 1, At, B1); PG8_BAR; PG8_SCHED;
.LBB0_239:
	s_waitcnt lgkmcnt(0)
	v_add_u32_e32 v156, 0x10000, v142
	v_add_u32_e32 v172, 0x14000, v142
	ds_read_b128 v[144:147], v156
	ds_read_b128 v[148:151], v156 offset:1024
	ds_read_b128 v[152:155], v156 offset:2048
	ds_read_b128 v[156:159], v156 offset:3072
	ds_read_b128 v[160:163], v172
	ds_read_b128 v[164:167], v172 offset:1024
	ds_read_b128 v[168:171], v172 offset:2048
	ds_read_b128 v[172:175], v172 offset:3072
	s_add_u32 s58, s10, s44
	s_addc_u32 s59, s11, s45
	s_add_u32 s58, s58, 0x100
	s_addc_u32 s59, s59, 0
	s_add_u32 s73, s19, s44
	s_addc_u32 s74, s62, s45
	s_add_i32 s75, 0, 0x10000
	s_cmpk_eq_i32 s44, 0x700
	s_cselect_b32 s79, s15, s59
	s_cselect_b32 s78, s70, s58
	s_cselect_b32 s59, s13, s74
	s_cselect_b32 s58, s71, s73
	s_add_i32 s73, 0, 0x14000
	v_lshl_add_u64 v[194:195], v[138:139], 0, s[44:45]
	s_add_i32 m0, s46, 0xc000
	ds_read_b128 v[176:179], v143
	ds_read_b128 v[180:183], v143 offset:1024
	ds_read_b128 v[184:187], v143 offset:2048
	ds_read_b128 v[188:191], v143 offset:3072
	ds_read_b128 v[212:215], v143 offset:4096
	ds_read_b128 v[216:219], v143 offset:5120
	ds_read_b128 v[234:237], v143 offset:6144
	ds_read_b128 v[238:241], v143 offset:7168
	global_load_lds_dwordx4 v[194:195], off
	v_lshl_add_u64 v[194:195], v[140:141], 0, s[44:45]
	s_add_i32 m0, s46, 0xe000
	s_nop 0
	global_load_lds_dwordx4 v[194:195], off
	s_waitcnt vmcnt(8)
	s_waitcnt lgkmcnt(0)
	s_barrier
	s_waitcnt lgkmcnt(0)
	v_mfma_f32_16x16x32_bf16 v[76:79], v[144:147], v[176:179], v[76:79]
	v_mfma_f32_16x16x32_bf16 v[72:75], v[152:155], v[176:179], v[72:75]
	v_mfma_f32_16x16x32_bf16 v[100:103], v[144:147], v[184:187], v[100:103]
	v_mfma_f32_16x16x32_bf16 v[96:99], v[152:155], v[184:187], v[96:99]
	v_mfma_f32_16x16x32_bf16 v[124:127], v[144:147], v[212:215], v[124:127]
	v_mfma_f32_16x16x32_bf16 v[120:123], v[152:155], v[212:215], v[120:123]
	v_mfma_f32_16x16x32_bf16 v[92:95], v[144:147], v[234:237], v[92:95]
	v_mfma_f32_16x16x32_bf16 v[84:87], v[152:155], v[234:237], v[84:87]
	v_mfma_f32_16x16x32_bf16 v[76:79], v[148:151], v[180:183], v[76:79]
	v_mfma_f32_16x16x32_bf16 v[72:75], v[156:159], v[180:183], v[72:75]
	v_mfma_f32_16x16x32_bf16 v[100:103], v[148:151], v[188:191], v[100:103]
	v_mfma_f32_16x16x32_bf16 v[96:99], v[156:159], v[188:191], v[96:99]
	v_mfma_f32_16x16x32_bf16 v[124:127], v[148:151], v[216:219], v[124:127]
	v_mfma_f32_16x16x32_bf16 v[120:123], v[156:159], v[216:219], v[120:123]
	v_mfma_f32_16x16x32_bf16 v[92:95], v[148:151], v[238:241], v[92:95]
	v_mfma_f32_16x16x32_bf16 v[84:87], v[156:159], v[238:241], v[84:87]
	v_mfma_f32_16x16x32_bf16 v[80:83], v[160:163], v[176:179], v[80:83]
	v_mfma_f32_16x16x32_bf16 v[88:91], v[168:171], v[176:179], v[88:91]
	v_mfma_f32_16x16x32_bf16 v[108:111], v[160:163], v[184:187], v[108:111]
	v_mfma_f32_16x16x32_bf16 v[116:119], v[168:171], v[184:187], v[116:119]
	v_mfma_f32_16x16x32_bf16 v[112:115], v[160:163], v[212:215], v[112:115]
	v_mfma_f32_16x16x32_bf16 v[104:107], v[168:171], v[212:215], v[104:107]
	v_mfma_f32_16x16x32_bf16 v[68:71], v[160:163], v[234:237], v[68:71]
	v_mfma_f32_16x16x32_bf16 v[64:67], v[168:171], v[234:237], v[64:67]
	v_mfma_f32_16x16x32_bf16 v[80:83], v[164:167], v[180:183], v[80:83]
	v_mfma_f32_16x16x32_bf16 v[88:91], v[172:175], v[180:183], v[88:91]
	v_mfma_f32_16x16x32_bf16 v[108:111], v[164:167], v[188:191], v[108:111]
	v_mfma_f32_16x16x32_bf16 v[116:119], v[172:175], v[188:191], v[116:119]
	v_mfma_f32_16x16x32_bf16 v[112:115], v[164:167], v[216:219], v[112:115]
	v_mfma_f32_16x16x32_bf16 v[104:107], v[172:175], v[216:219], v[104:107]
	v_mfma_f32_16x16x32_bf16 v[68:71], v[164:167], v[238:241], v[68:71]
	v_mfma_f32_16x16x32_bf16 v[64:67], v[172:175], v[238:241], v[64:67]
	s_barrier
	s_add_i32 s74, s75, s41
	v_lshl_add_u64 v[194:195], s[58:59], 0, v[192:193]
	s_mov_b32 m0, s74
	ds_read_b128 v[176:179], v143 offset:16384
	ds_read_b128 v[180:183], v143 offset:17408
	ds_read_b128 v[184:187], v143 offset:18432
	ds_read_b128 v[188:191], v143 offset:19456
	ds_read_b128 v[212:215], v143 offset:20480
	ds_read_b128 v[216:219], v143 offset:21504
	ds_read_b128 v[234:237], v143 offset:22528
	ds_read_b128 v[238:241], v143 offset:23552
	global_load_lds_dwordx4 v[194:195], off
	s_add_i32 m0, s74, 0x2000
	s_add_u32 s74, s58, 0x40000
	v_lshl_add_u64 v[196:197], s[58:59], 0, v[132:133]
	s_addc_u32 s75, s59, 0
	s_add_i32 s73, s73, s41
	global_load_lds_dwordx4 v[196:197], off
	v_lshl_add_u64 v[202:203], s[74:75], 0, v[192:193]
	s_mov_b32 m0, s73
	v_lshl_add_u64 v[204:205], s[78:79], 0, v[130:131]
	global_load_lds_dwordx4 v[202:203], off
	v_lshl_add_u64 v[202:203], s[74:75], 0, v[132:133]
	s_add_i32 m0, s73, 0x2000
	s_nop 0
	global_load_lds_dwordx4 v[202:203], off
	v_lshl_add_u64 v[202:203], s[78:79], 0, v[128:129]
	s_mov_b32 m0, s46
	s_nop 0
	global_load_lds_dwordx4 v[202:203], off
	s_mov_b32 m0, s47
	s_nop 0
	global_load_lds_dwordx4 v[204:205], off
	s_waitcnt vmcnt(8)
	s_waitcnt lgkmcnt(0)
	s_barrier
; #define PG8_STAGE(bufoff, gbase, voff) do { _Pragma("unroll") for (int _i = 0; _i < 2; ++_i) \
;         __builtin_amdgcn_global_load_lds((const unsigned*)((const char*)(gbase) + (voff)[_i]), (PG8_LAS unsigned*)(lds + (bufoff) + ldsw + _i * 8192), 16, 0, 0); } while (0)
; #define PG8_LDA(dst, b, h) do { _Pragma("unroll") for (int m = 0; m < 4; ++m) _Pragma("unroll") for (int k = 0; k < 2; ++k) dst[m][k] = *(const PG8_LAS bf16x8*)(lds + PG8_SA(b, h) + aoff + m * 2048 + k * 1024); } while (0)
; #define PG8_LDB(dst, b, h) do { _Pragma("unroll") for (int n = 0; n < 2; ++n) _Pragma("unroll") for (int k = 0; k < 2; ++k) dst[n][k] = *(const PG8_LAS bf16x8*)(lds + PG8_SB(b, h) + boff + n * 2048 + k * 1024); } while (0)
; #define PG8_MMA(ai, bj, At, Bt) do { __builtin_amdgcn_s_setprio(1); _Pragma("unroll") for (int m = 0; m < 4; ++m) _Pragma("unroll") for (int n = 0; n < 2; ++n) _Pragma("unroll") for (int k = 0; k < 2; ++k) \
;         acc[ai][bj][m][n] = __builtin_amdgcn_mfma_f32_16x16x32_bf16(Bt[n][k], At[m][k], acc[ai][bj][m][n], 0, 0, 0); __builtin_amdgcn_s_setprio(0); } while (0)
; #define PG8_WAIT_V(n) asm volatile("s_waitcnt vmcnt(" #n ")" ::: "memory")
; #define PG8_WAIT_L(n) asm volatile("s_waitcnt lgkmcnt(" #n ")" ::: "memory")
; #define PG8_BAR __builtin_amdgcn_s_barrier()
; #define PG8_SCHED __builtin_amdgcn_sched_barrier(0)
; template <class Epi, class Sched, bool ALIGN_EPI = false, bool SP2 = false>
; __device__ __forceinline__ void gemm_phase(PG8_LAS unsigned char* lds, const Gemm g, const Sched& S, const Epi& E, const int tid) {
;     ...
;             PG8_WAIT_V(8); PG8_WAIT_L(0); PG8_BAR; PG8_MMA(1, 0, At, B0); PG8_MMA(1, 1, At, B1); PG8_BAR; PG8_SCHED;
;             PG8_LDB(B0, 1, 0); PG8_LDB(B1, 1, 1); PG8_SCHED; PG8_LDA(At, 1, 0); PG8_STAGE(PG8_SA(0, 1), a2 + hstep, voffA);
;             PG8_WAIT_V(8); PG8_WAIT_L(0); PG8_BAR; PG8_MMA(0, 0, At, B0); PG8_MMA(0, 1, At, B1); PG8_BAR; PG8_SCHED;
	s_waitcnt lgkmcnt(0)
	v_mfma_f32_16x16x32_bf16 v[60:63], v[144:147], v[176:179], v[60:63]
	v_mfma_f32_16x16x32_bf16 v[56:59], v[152:155], v[176:179], v[56:59]
	v_mfma_f32_16x16x32_bf16 v[44:47], v[144:147], v[184:187], v[44:47]
	v_mfma_f32_16x16x32_bf16 v[40:43], v[152:155], v[184:187], v[40:43]
	v_mfma_f32_16x16x32_bf16 v[28:31], v[144:147], v[212:215], v[28:31]
	v_mfma_f32_16x16x32_bf16 v[24:27], v[152:155], v[212:215], v[24:27]
	v_mfma_f32_16x16x32_bf16 v[12:15], v[144:147], v[234:237], v[12:15]
	v_mfma_f32_16x16x32_bf16 v[8:11], v[152:155], v[234:237], v[8:11]
	v_mfma_f32_16x16x32_bf16 v[60:63], v[148:151], v[180:183], v[60:63]
	v_mfma_f32_16x16x32_bf16 v[56:59], v[156:159], v[180:183], v[56:59]
	v_mfma_f32_16x16x32_bf16 v[44:47], v[148:151], v[188:191], v[44:47]
	v_mfma_f32_16x16x32_bf16 v[40:43], v[156:159], v[188:191], v[40:43]
	v_mfma_f32_16x16x32_bf16 v[28:31], v[148:151], v[216:219], v[28:31]
	v_mfma_f32_16x16x32_bf16 v[24:27], v[156:159], v[216:219], v[24:27]
	v_mfma_f32_16x16x32_bf16 v[12:15], v[148:151], v[238:241], v[12:15]
	v_mfma_f32_16x16x32_bf16 v[8:11], v[156:159], v[238:241], v[8:11]
	v_mfma_f32_16x16x32_bf16 v[52:55], v[160:163], v[176:179], v[52:55]
	v_mfma_f32_16x16x32_bf16 v[48:51], v[168:171], v[176:179], v[48:51]
	v_mfma_f32_16x16x32_bf16 v[36:39], v[160:163], v[184:187], v[36:39]
	v_mfma_f32_16x16x32_bf16 v[32:35], v[168:171], v[184:187], v[32:35]
	v_mfma_f32_16x16x32_bf16 v[20:23], v[160:163], v[212:215], v[20:23]
	v_mfma_f32_16x16x32_bf16 v[16:19], v[168:171], v[212:215], v[16:19]
	v_mfma_f32_16x16x32_bf16 v[4:7], v[160:163], v[234:237], v[4:7]
	v_mfma_f32_16x16x32_bf16 v[0:3], v[168:171], v[234:237], v[0:3]
	v_mfma_f32_16x16x32_bf16 v[52:55], v[164:167], v[180:183], v[52:55]
	v_mfma_f32_16x16x32_bf16 v[48:51], v[172:175], v[180:183], v[48:51]
	v_mfma_f32_16x16x32_bf16 v[36:39], v[164:167], v[188:191], v[36:39]
	v_mfma_f32_16x16x32_bf16 v[32:35], v[172:175], v[188:191], v[32:35]
	v_mfma_f32_16x16x32_bf16 v[20:23], v[164:167], v[216:219], v[20:23]
	v_mfma_f32_16x16x32_bf16 v[16:19], v[172:175], v[216:219], v[16:19]
	v_mfma_f32_16x16x32_bf16 v[4:7], v[164:167], v[238:241], v[4:7]
	v_mfma_f32_16x16x32_bf16 v[0:3], v[172:175], v[238:241], v[0:3]
	s_barrier
	s_add_i32 s73, 0, 0x18000
	s_add_i32 s76, 0, 0x1c000
	v_add_u32_e32 v156, s73, v142
	v_add_u32_e32 v172, s76, v142
	ds_read_b128 v[144:147], v156
	ds_read_b128 v[148:151], v156 offset:1024
	ds_read_b128 v[152:155], v156 offset:2048
	ds_read_b128 v[156:159], v156 offset:3072
	ds_read_b128 v[160:163], v172
	ds_read_b128 v[164:167], v172 offset:1024
	ds_read_b128 v[168:171], v172 offset:2048
	ds_read_b128 v[172:175], v172 offset:3072
	s_add_u32 s74, s78, 0x40000
	s_addc_u32 s75, s79, 0
	s_mov_b32 m0, s52
	v_lshl_add_u64 v[206:207], s[74:75], 0, v[128:129]
	ds_read_b128 v[176:179], v143 offset:32768
	ds_read_b128 v[180:183], v143 offset:33792
	ds_read_b128 v[184:187], v143 offset:34816
	ds_read_b128 v[188:191], v143 offset:35840
	ds_read_b128 v[212:215], v143 offset:36864
	ds_read_b128 v[216:219], v143 offset:37888
	ds_read_b128 v[234:237], v143 offset:38912
	ds_read_b128 v[238:241], v143 offset:39936
	global_load_lds_dwordx4 v[206:207], off
	v_lshl_add_u64 v[206:207], s[74:75], 0, v[130:131]
	s_mov_b32 m0, s53
	s_nop 0
	global_load_lds_dwordx4 v[206:207], off
	s_waitcnt vmcnt(8)
	s_waitcnt lgkmcnt(0)
	s_barrier
	s_waitcnt lgkmcnt(0)
	v_mfma_f32_16x16x32_bf16 v[76:79], v[144:147], v[176:179], v[76:79]
	v_mfma_f32_16x16x32_bf16 v[72:75], v[152:155], v[176:179], v[72:75]
	v_mfma_f32_16x16x32_bf16 v[100:103], v[144:147], v[184:187], v[100:103]
	v_mfma_f32_16x16x32_bf16 v[96:99], v[152:155], v[184:187], v[96:99]
	v_mfma_f32_16x16x32_bf16 v[124:127], v[144:147], v[212:215], v[124:127]
	v_mfma_f32_16x16x32_bf16 v[120:123], v[152:155], v[212:215], v[120:123]
	v_mfma_f32_16x16x32_bf16 v[92:95], v[144:147], v[234:237], v[92:95]
	v_mfma_f32_16x16x32_bf16 v[84:87], v[152:155], v[234:237], v[84:87]
	v_mfma_f32_16x16x32_bf16 v[76:79], v[148:151], v[180:183], v[76:79]
	v_mfma_f32_16x16x32_bf16 v[72:75], v[156:159], v[180:183], v[72:75]
	v_mfma_f32_16x16x32_bf16 v[100:103], v[148:151], v[188:191], v[100:103]
	v_mfma_f32_16x16x32_bf16 v[96:99], v[156:159], v[188:191], v[96:99]
	v_mfma_f32_16x16x32_bf16 v[124:127], v[148:151], v[216:219], v[124:127]
	v_mfma_f32_16x16x32_bf16 v[120:123], v[156:159], v[216:219], v[120:123]
	v_mfma_f32_16x16x32_bf16 v[92:95], v[148:151], v[238:241], v[92:95]
	v_mfma_f32_16x16x32_bf16 v[84:87], v[156:159], v[238:241], v[84:87]
	v_mfma_f32_16x16x32_bf16 v[80:83], v[160:163], v[176:179], v[80:83]
	v_mfma_f32_16x16x32_bf16 v[88:91], v[168:171], v[176:179], v[88:91]
	v_mfma_f32_16x16x32_bf16 v[108:111], v[160:163], v[184:187], v[108:111]
	v_mfma_f32_16x16x32_bf16 v[116:119], v[168:171], v[184:187], v[116:119]
	v_mfma_f32_16x16x32_bf16 v[112:115], v[160:163], v[212:215], v[112:115]
	v_mfma_f32_16x16x32_bf16 v[104:107], v[168:171], v[212:215], v[104:107]
	v_mfma_f32_16x16x32_bf16 v[68:71], v[160:163], v[234:237], v[68:71]
	v_mfma_f32_16x16x32_bf16 v[64:67], v[168:171], v[234:237], v[64:67]
	v_mfma_f32_16x16x32_bf16 v[80:83], v[164:167], v[180:183], v[80:83]
	v_mfma_f32_16x16x32_bf16 v[88:91], v[172:175], v[180:183], v[88:91]
	v_mfma_f32_16x16x32_bf16 v[108:111], v[164:167], v[188:191], v[108:111]
	v_mfma_f32_16x16x32_bf16 v[116:119], v[172:175], v[188:191], v[116:119]
	v_mfma_f32_16x16x32_bf16 v[112:115], v[164:167], v[216:219], v[112:115]
	v_mfma_f32_16x16x32_bf16 v[104:107], v[172:175], v[216:219], v[104:107]
	v_mfma_f32_16x16x32_bf16 v[68:71], v[164:167], v[238:241], v[68:71]
	v_mfma_f32_16x16x32_bf16 v[64:67], v[172:175], v[238:241], v[64:67]
	s_barrier
; #define PG8_STAGE(bufoff, gbase, voff) do { _Pragma("unroll") for (int _i = 0; _i < 2; ++_i) \
;         __builtin_amdgcn_global_load_lds((const unsigned*)((const char*)(gbase) + (voff)[_i]), (PG8_LAS unsigned*)(lds + (bufoff) + ldsw + _i * 8192), 16, 0, 0); } while (0)
; #define PG8_LDA(dst, b, h) do { _Pragma("unroll") for (int m = 0; m < 4; ++m) _Pragma("unroll") for (int k = 0; k < 2; ++k) dst[m][k] = *(const PG8_LAS bf16x8*)(lds + PG8_SA(b, h) + aoff + m * 2048 + k * 1024); } while (0)
; #define PG8_MMA(ai, bj, At, Bt) do { __builtin_amdgcn_s_setprio(1); _Pragma("unroll") for (int m = 0; m < 4; ++m) _Pragma("unroll") for (int n = 0; n < 2; ++n) _Pragma("unroll") for (int k = 0; k < 2; ++k) \
;         acc[ai][bj][m][n] = __builtin_amdgcn_mfma_f32_16x16x32_bf16(Bt[n][k], At[m][k], acc[ai][bj][m][n], 0, 0, 0); __builtin_amdgcn_s_setprio(0); } while (0)
; #define PG8_WAIT_V(n) asm volatile("s_waitcnt vmcnt(" #n ")" ::: "memory")
; #define PG8_WAIT_L(n) asm volatile("s_waitcnt lgkmcnt(" #n ")" ::: "memory")
; #define PG8_BAR __builtin_amdgcn_s_barrier()
; #define PG8_SCHED __builtin_amdgcn_sched_barrier(0)
; template <class Epi, class Sched, bool ALIGN_EPI = false, bool SP2 = false>
; __device__ __forceinline__ void gemm_phase(PG8_LAS unsigned char* lds, const Gemm g, const Sched& S, const Epi& E, const int tid) {
;     ...
;             PG8_LDA(At, 1, 1); PG8_STAGE(PG8_SB(1, 0), b3, voffB); PG8_STAGE(PG8_SB(1, 1), b3 + hstep, voffB); PG8_STAGE(PG8_SA(1, 0), a3, voffA);
;             PG8_WAIT_V(8); PG8_WAIT_L(0); PG8_BAR; PG8_MMA(1, 0, At, B0); PG8_MMA(1, 1, At, B1); PG8_BAR; PG8_SCHED;
;     ...
;         if (!has_next) break;
; #pragma unroll
;         for (int a = 0; a < 2; ++a)
; #pragma unroll
;             for (int b = 0; b < 2; ++b)
; #pragma unroll
;                 for (int m = 0; m < 4; ++m)
; #pragma unroll
;                     for (int n = 0; n < 2; ++n) acc[a][b][m][n] = (f32x4){0.f, 0.f, 0.f, 0.f};
	s_add_i32 s73, s73, s41
	v_lshl_add_u64 v[194:195], v[194:195], 0, s[36:37]
	s_mov_b32 m0, s73
	ds_read_b128 v[176:179], v143 offset:49152
	ds_read_b128 v[180:183], v143 offset:50176
	ds_read_b128 v[184:187], v143 offset:51200
	ds_read_b128 v[188:191], v143 offset:52224
	ds_read_b128 v[212:215], v143 offset:53248
	ds_read_b128 v[216:219], v143 offset:54272
	ds_read_b128 v[234:237], v143 offset:55296
	ds_read_b128 v[238:241], v143 offset:56320
	global_load_lds_dwordx4 v[194:195], off
	s_add_i32 m0, s73, 0x2000
	s_add_u32 s58, s58, 0x40080
	v_lshl_add_u64 v[194:195], v[196:197], 0, s[36:37]
	s_addc_u32 s59, s59, 0
	s_add_i32 s73, s76, s41
	global_load_lds_dwordx4 v[194:195], off
	v_lshl_add_u64 v[194:195], s[58:59], 0, v[192:193]
	s_mov_b32 m0, s73
	s_nop 0
	global_load_lds_dwordx4 v[194:195], off
	v_lshl_add_u64 v[194:195], s[58:59], 0, v[132:133]
	s_add_i32 m0, s73, 0x2000
	s_nop 0
	global_load_lds_dwordx4 v[194:195], off
	v_lshl_add_u64 v[194:195], v[202:203], 0, s[36:37]
	s_mov_b32 m0, s54
	s_nop 0
	global_load_lds_dwordx4 v[194:195], off
	v_lshl_add_u64 v[194:195], v[204:205], 0, s[36:37]
	s_mov_b32 m0, s55
	s_nop 0
	global_load_lds_dwordx4 v[194:195], off
	s_add_i32 s72, s72, 2
	s_add_u32 s44, s44, 0x100
	s_addc_u32 s45, s45, 0
	s_cmp_gt_u32 s72, 13
	s_waitcnt vmcnt(8)
	s_waitcnt lgkmcnt(0)
	s_barrier
	s_waitcnt lgkmcnt(0)
	v_mfma_f32_16x16x32_bf16 v[60:63], v[144:147], v[176:179], v[60:63]
	v_mfma_f32_16x16x32_bf16 v[56:59], v[152:155], v[176:179], v[56:59]
	v_mfma_f32_16x16x32_bf16 v[44:47], v[144:147], v[184:187], v[44:47]
	v_mfma_f32_16x16x32_bf16 v[40:43], v[152:155], v[184:187], v[40:43]
	v_mfma_f32_16x16x32_bf16 v[28:31], v[144:147], v[212:215], v[28:31]
	v_mfma_f32_16x16x32_bf16 v[24:27], v[152:155], v[212:215], v[24:27]
	v_mfma_f32_16x16x32_bf16 v[12:15], v[144:147], v[234:237], v[12:15]
	v_mfma_f32_16x16x32_bf16 v[8:11], v[152:155], v[234:237], v[8:11]
	v_mfma_f32_16x16x32_bf16 v[60:63], v[148:151], v[180:183], v[60:63]
	v_mfma_f32_16x16x32_bf16 v[56:59], v[156:159], v[180:183], v[56:59]
	v_mfma_f32_16x16x32_bf16 v[44:47], v[148:151], v[188:191], v[44:47]
	v_mfma_f32_16x16x32_bf16 v[40:43], v[156:159], v[188:191], v[40:43]
	v_mfma_f32_16x16x32_bf16 v[28:31], v[148:151], v[216:219], v[28:31]
	v_mfma_f32_16x16x32_bf16 v[24:27], v[156:159], v[216:219], v[24:27]
	v_mfma_f32_16x16x32_bf16 v[12:15], v[148:151], v[238:241], v[12:15]
	v_mfma_f32_16x16x32_bf16 v[8:11], v[156:159], v[238:241], v[8:11]
	v_mfma_f32_16x16x32_bf16 v[52:55], v[160:163], v[176:179], v[52:55]
	v_mfma_f32_16x16x32_bf16 v[48:51], v[168:171], v[176:179], v[48:51]
	v_mfma_f32_16x16x32_bf16 v[36:39], v[160:163], v[184:187], v[36:39]
	v_mfma_f32_16x16x32_bf16 v[32:35], v[168:171], v[184:187], v[32:35]
	v_mfma_f32_16x16x32_bf16 v[20:23], v[160:163], v[212:215], v[20:23]
	v_mfma_f32_16x16x32_bf16 v[16:19], v[168:171], v[212:215], v[16:19]
	v_mfma_f32_16x16x32_bf16 v[4:7], v[160:163], v[234:237], v[4:7]
	v_mfma_f32_16x16x32_bf16 v[0:3], v[168:171], v[234:237], v[0:3]
	v_mfma_f32_16x16x32_bf16 v[52:55], v[164:167], v[180:183], v[52:55]
	v_mfma_f32_16x16x32_bf16 v[48:51], v[172:175], v[180:183], v[48:51]
	v_mfma_f32_16x16x32_bf16 v[36:39], v[164:167], v[188:191], v[36:39]
	v_mfma_f32_16x16x32_bf16 v[32:35], v[172:175], v[188:191], v[32:35]
	v_mfma_f32_16x16x32_bf16 v[20:23], v[164:167], v[216:219], v[20:23]
	v_mfma_f32_16x16x32_bf16 v[16:19], v[172:175], v[216:219], v[16:19]
	v_mfma_f32_16x16x32_bf16 v[4:7], v[164:167], v[238:241], v[4:7]
	v_mfma_f32_16x16x32_bf16 v[0:3], v[172:175], v[238:241], v[0:3]
	s_barrier
	s_cbranch_scc0 .LBB0_239
	s_add_u32 s44, s19, 0xffffff00
	s_addc_u32 s45, s62, -1
	s_andn2_b64 vcc, exec, s[8:9]
	s_cbranch_vccnz .LBB0_242
	v_mov_b32_e32 v0, 0
	s_mov_b32 s22, s12
	s_mov_b32 s20, s14
	s_mov_b64 s[10:11], s[28:29]
	s_mov_b32 s60, s18
	v_mov_b32_e32 v1, v0
	v_mov_b32_e32 v2, v0
	v_mov_b32_e32 v3, v0
	v_mov_b32_e32 v4, v0
	v_mov_b32_e32 v5, v0
	v_mov_b32_e32 v6, v0
	v_mov_b32_e32 v7, v0
	v_mov_b32_e32 v16, v0
	v_mov_b32_e32 v17, v0
	v_mov_b32_e32 v18, v0
	v_mov_b32_e32 v19, v0
	v_mov_b32_e32 v20, v0
	v_mov_b32_e32 v21, v0
	v_mov_b32_e32 v22, v0
	v_mov_b32_e32 v23, v0
	v_mov_b32_e32 v32, v0
	v_mov_b32_e32 v33, v0
	v_mov_b32_e32 v34, v0
	v_mov_b32_e32 v35, v0
	v_mov_b32_e32 v36, v0
	v_mov_b32_e32 v37, v0
	v_mov_b32_e32 v38, v0
	v_mov_b32_e32 v39, v0
	v_mov_b32_e32 v48, v0
	v_mov_b32_e32 v49, v0
	v_mov_b32_e32 v50, v0
	v_mov_b32_e32 v51, v0
	v_mov_b32_e32 v52, v0
	v_mov_b32_e32 v53, v0
	v_mov_b32_e32 v54, v0
	v_mov_b32_e32 v55, v0
	v_mov_b32_e32 v8, v0
	v_mov_b32_e32 v9, v0
	v_mov_b32_e32 v10, v0
	v_mov_b32_e32 v11, v0
	v_mov_b32_e32 v12, v0
	v_mov_b32_e32 v13, v0
	v_mov_b32_e32 v14, v0
	v_mov_b32_e32 v15, v0
	v_mov_b32_e32 v24, v0
	v_mov_b32_e32 v25, v0
	v_mov_b32_e32 v26, v0
	v_mov_b32_e32 v27, v0
	v_mov_b32_e32 v28, v0
	v_mov_b32_e32 v29, v0
	v_mov_b32_e32 v30, v0
	v_mov_b32_e32 v31, v0
	v_mov_b32_e32 v40, v0
	v_mov_b32_e32 v41, v0
	v_mov_b32_e32 v42, v0
	v_mov_b32_e32 v43, v0
	v_mov_b32_e32 v44, v0
	v_mov_b32_e32 v45, v0
	v_mov_b32_e32 v46, v0
	v_mov_b32_e32 v47, v0
	v_mov_b32_e32 v56, v0
	v_mov_b32_e32 v57, v0
	v_mov_b32_e32 v58, v0
	v_mov_b32_e32 v59, v0
	v_mov_b32_e32 v60, v0
	v_mov_b32_e32 v61, v0
	v_mov_b32_e32 v62, v0
	v_mov_b32_e32 v63, v0
	v_mov_b32_e32 v64, v0
	v_mov_b32_e32 v65, v0
	v_mov_b32_e32 v66, v0
	v_mov_b32_e32 v67, v0
	v_mov_b32_e32 v68, v0
	v_mov_b32_e32 v69, v0
	v_mov_b32_e32 v70, v0
	v_mov_b32_e32 v71, v0
	v_mov_b32_e32 v104, v0
	v_mov_b32_e32 v105, v0
	v_mov_b32_e32 v106, v0
	v_mov_b32_e32 v107, v0
	v_mov_b32_e32 v112, v0
	v_mov_b32_e32 v113, v0
	v_mov_b32_e32 v114, v0
	v_mov_b32_e32 v115, v0
	v_mov_b32_e32 v116, v0
	v_mov_b32_e32 v117, v0
	v_mov_b32_e32 v118, v0
	v_mov_b32_e32 v119, v0
	v_mov_b32_e32 v108, v0
	v_mov_b32_e32 v109, v0
	v_mov_b32_e32 v110, v0
	v_mov_b32_e32 v111, v0
	v_mov_b32_e32 v88, v0
	v_mov_b32_e32 v89, v0
	v_mov_b32_e32 v90, v0
	v_mov_b32_e32 v91, v0
	v_mov_b32_e32 v80, v0
	v_mov_b32_e32 v81, v0
	v_mov_b32_e32 v82, v0
	v_mov_b32_e32 v83, v0
	v_mov_b32_e32 v84, v0
	v_mov_b32_e32 v85, v0
	v_mov_b32_e32 v86, v0
	v_mov_b32_e32 v87, v0
	v_mov_b32_e32 v92, v0
	v_mov_b32_e32 v93, v0
	v_mov_b32_e32 v94, v0
	v_mov_b32_e32 v95, v0
	v_mov_b32_e32 v120, v0
	v_mov_b32_e32 v121, v0
	v_mov_b32_e32 v122, v0
	v_mov_b32_e32 v123, v0
	v_mov_b32_e32 v124, v0
	v_mov_b32_e32 v125, v0
	v_mov_b32_e32 v126, v0
	v_mov_b32_e32 v127, v0
	v_mov_b32_e32 v96, v0
	v_mov_b32_e32 v97, v0
	v_mov_b32_e32 v98, v0
	v_mov_b32_e32 v99, v0
	v_mov_b32_e32 v100, v0
	v_mov_b32_e32 v101, v0
	v_mov_b32_e32 v102, v0
	v_mov_b32_e32 v103, v0
	v_mov_b32_e32 v72, v0
	v_mov_b32_e32 v73, v0
	v_mov_b32_e32 v74, v0
	v_mov_b32_e32 v75, v0
	v_mov_b32_e32 v76, v0
	v_mov_b32_e32 v77, v0
	v_mov_b32_e32 v78, v0
	v_mov_b32_e32 v79, v0
	s_load_dword s75, s[96:97], 0x0
	s_mov_b64 s[72:73], 0x20000
	s_andn2_b64 vcc, exec, s[6:7]
	s_cbranch_vccnz .LBB0_243
	s_branch .LBB0_244

; #define PG8_STAGE(bufoff, gbase, voff) do { _Pragma("unroll") for (int _i = 0; _i < 2; ++_i) \
;         __builtin_amdgcn_global_load_lds((const unsigned*)((const char*)(gbase) + (voff)[_i]), (PG8_LAS unsigned*)(lds + (bufoff) + ldsw + _i * 8192), 16, 0, 0); } while (0)
; #define PG8_LDA(dst, b, h) do { _Pragma("unroll") for (int m = 0; m < 4; ++m) _Pragma("unroll") for (int k = 0; k < 2; ++k) dst[m][k] = *(const PG8_LAS bf16x8*)(lds + PG8_SA(b, h) + aoff + m * 2048 + k * 1024); } while (0)
; #define PG8_LDB(dst, b, h) do { _Pragma("unroll") for (int n = 0; n < 2; ++n) _Pragma("unroll") for (int k = 0; k < 2; ++k) dst[n][k] = *(const PG8_LAS bf16x8*)(lds + PG8_SB(b, h) + boff + n * 2048 + k * 1024); } while (0)
; #define PG8_MMA(ai, bj, At, Bt) do { __builtin_amdgcn_s_setprio(1); _Pragma("unroll") for (int m = 0; m < 4; ++m) _Pragma("unroll") for (int n = 0; n < 2; ++n) _Pragma("unroll") for (int k = 0; k < 2; ++k) \
;         acc[ai][bj][m][n] = __builtin_amdgcn_mfma_f32_16x16x32_bf16(Bt[n][k], At[m][k], acc[ai][bj][m][n], 0, 0, 0); __builtin_amdgcn_s_setprio(0); } while (0)
; #define PG8_WAIT_V(n) asm volatile("s_waitcnt vmcnt(" #n ")" ::: "memory")
; #define PG8_WAIT_L(n) asm volatile("s_waitcnt lgkmcnt(" #n ")" ::: "memory")
; #define PG8_BAR __builtin_amdgcn_s_barrier()
; #define PG8_SCHED __builtin_amdgcn_sched_barrier(0)
; template <class Epi, class Sched, bool ALIGN_EPI = false, bool SP2 = false>
; __device__ __forceinline__ void gemm_phase(PG8_LAS unsigned char* lds, const Gemm g, const Sched& S, const Epi& E, const int tid) {
;     ...
;             PG8_LDB(B0, 0, 0); PG8_LDB(B1, 0, 1); PG8_SCHED; PG8_LDA(At, 0, 0); PG8_STAGE(PG8_SA(1, 1), a1 + hstep, voffA);
;             PG8_WAIT_V(8); PG8_WAIT_L(0); PG8_BAR; PG8_MMA(0, 0, At, B0); PG8_MMA(0, 1, At, B1); PG8_BAR; PG8_SCHED;
;             PG8_LDA(At, 0, 1); PG8_STAGE(PG8_SB(0, 0), b2, voffB); PG8_STAGE(PG8_SB(0, 1), b2 + hstep, voffB); PG8_STAGE(PG8_SA(0, 0), a2, voffA);
;             PG8_WAIT_V(8); PG8_WAIT_L(0); PG8_BAR; PG8_MMA(1, 0, At, B0); PG8_MMA(1, 1, At, B1); PG8_BAR; PG8_SCHED;
.LBB0_324:
	v_add_u32_e32 v152, 0x10000, v142
	v_add_u32_e32 v168, 0x14000, v142
	ds_read_b128 v[138:141], v152
	ds_read_b128 v[144:147], v152 offset:1024
	ds_read_b128 v[148:151], v152 offset:2048
	ds_read_b128 v[152:155], v152 offset:3072
	ds_read_b128 v[156:159], v168
	ds_read_b128 v[160:163], v168 offset:1024
	ds_read_b128 v[164:167], v168 offset:2048
	ds_read_b128 v[168:171], v168 offset:3072
	s_add_u32 s28, s22, 0xfffc0080
	s_addc_u32 s29, s23, -1
	s_add_i32 s35, 0, 0x10000
	s_cmp_eq_u32 s34, 12
	s_cselect_b32 s45, s1, s29
	s_cselect_b32 s44, s2, s28
	s_cselect_b32 s29, s13, s26
	s_cselect_b32 s28, s15, s21
	s_add_i32 s38, 0, 0x14000
	v_lshl_add_u64 v[194:195], s[22:23], 0, v[134:135]
	s_add_i32 m0, s80, 0xc000
	ds_read_b128 v[172:175], v143
	ds_read_b128 v[176:179], v143 offset:1024
	ds_read_b128 v[180:183], v143 offset:2048
	ds_read_b128 v[184:187], v143 offset:3072
	ds_read_b128 v[188:191], v143 offset:4096
	ds_read_b128 v[212:215], v143 offset:5120
	ds_read_b128 v[216:219], v143 offset:6144
	ds_read_b128 v[232:235], v143 offset:7168
	global_load_lds_dwordx4 v[194:195], off
	v_lshl_add_u64 v[194:195], s[22:23], 0, v[136:137]
	s_add_i32 m0, s80, 0xe000
	s_nop 0
	global_load_lds_dwordx4 v[194:195], off
	s_waitcnt vmcnt(8)
	s_waitcnt lgkmcnt(0)
	s_barrier
	s_waitcnt lgkmcnt(0)
	v_mfma_f32_16x16x32_bf16 v[124:127], v[138:141], v[172:175], v[124:127]
	v_mfma_f32_16x16x32_bf16 v[120:123], v[148:151], v[172:175], v[120:123]
	v_mfma_f32_16x16x32_bf16 v[108:111], v[138:141], v[180:183], v[108:111]
	v_mfma_f32_16x16x32_bf16 v[104:107], v[148:151], v[180:183], v[104:107]
	v_mfma_f32_16x16x32_bf16 v[92:95], v[138:141], v[188:191], v[92:95]
	v_mfma_f32_16x16x32_bf16 v[88:91], v[148:151], v[188:191], v[88:91]
	v_mfma_f32_16x16x32_bf16 v[76:79], v[138:141], v[216:219], v[76:79]
	v_mfma_f32_16x16x32_bf16 v[72:75], v[148:151], v[216:219], v[72:75]
	v_mfma_f32_16x16x32_bf16 v[124:127], v[144:147], v[176:179], v[124:127]
	v_mfma_f32_16x16x32_bf16 v[120:123], v[152:155], v[176:179], v[120:123]
	v_mfma_f32_16x16x32_bf16 v[108:111], v[144:147], v[184:187], v[108:111]
	v_mfma_f32_16x16x32_bf16 v[104:107], v[152:155], v[184:187], v[104:107]
	v_mfma_f32_16x16x32_bf16 v[92:95], v[144:147], v[212:215], v[92:95]
	v_mfma_f32_16x16x32_bf16 v[88:91], v[152:155], v[212:215], v[88:91]
	v_mfma_f32_16x16x32_bf16 v[76:79], v[144:147], v[232:235], v[76:79]
	v_mfma_f32_16x16x32_bf16 v[72:75], v[152:155], v[232:235], v[72:75]
	v_mfma_f32_16x16x32_bf16 v[116:119], v[156:159], v[172:175], v[116:119]
	v_mfma_f32_16x16x32_bf16 v[112:115], v[164:167], v[172:175], v[112:115]
	v_mfma_f32_16x16x32_bf16 v[100:103], v[156:159], v[180:183], v[100:103]
	v_mfma_f32_16x16x32_bf16 v[96:99], v[164:167], v[180:183], v[96:99]
	v_mfma_f32_16x16x32_bf16 v[84:87], v[156:159], v[188:191], v[84:87]
	v_mfma_f32_16x16x32_bf16 v[80:83], v[164:167], v[188:191], v[80:83]
	v_mfma_f32_16x16x32_bf16 v[68:71], v[156:159], v[216:219], v[68:71]
	v_mfma_f32_16x16x32_bf16 v[64:67], v[164:167], v[216:219], v[64:67]
	v_mfma_f32_16x16x32_bf16 v[116:119], v[160:163], v[176:179], v[116:119]
	v_mfma_f32_16x16x32_bf16 v[112:115], v[168:171], v[176:179], v[112:115]
	v_mfma_f32_16x16x32_bf16 v[100:103], v[160:163], v[184:187], v[100:103]
	v_mfma_f32_16x16x32_bf16 v[96:99], v[168:171], v[184:187], v[96:99]
	v_mfma_f32_16x16x32_bf16 v[84:87], v[160:163], v[212:215], v[84:87]
	v_mfma_f32_16x16x32_bf16 v[80:83], v[168:171], v[212:215], v[80:83]
	v_mfma_f32_16x16x32_bf16 v[68:71], v[160:163], v[232:235], v[68:71]
	v_mfma_f32_16x16x32_bf16 v[64:67], v[168:171], v[232:235], v[64:67]
	s_barrier
	s_add_i32 s35, s35, s79
	v_lshl_add_u64 v[194:195], s[28:29], 0, v[192:193]
	s_mov_b32 m0, s35
	ds_read_b128 v[172:175], v143 offset:16384
	ds_read_b128 v[176:179], v143 offset:17408
	ds_read_b128 v[180:183], v143 offset:18432
	ds_read_b128 v[184:187], v143 offset:19456
	ds_read_b128 v[188:191], v143 offset:20480
	ds_read_b128 v[212:215], v143 offset:21504
	ds_read_b128 v[216:219], v143 offset:22528
	ds_read_b128 v[232:235], v143 offset:23552
	global_load_lds_dwordx4 v[194:195], off
	s_add_i32 m0, s35, 0x2000
	s_add_u32 s40, s28, 0x40000
	v_lshl_add_u64 v[196:197], s[28:29], 0, v[132:133]
	s_addc_u32 s41, s29, 0
	s_add_i32 s35, s38, s79
	global_load_lds_dwordx4 v[196:197], off
	v_lshl_add_u64 v[202:203], s[40:41], 0, v[192:193]
	s_mov_b32 m0, s35
	v_lshl_add_u64 v[204:205], s[44:45], 0, v[130:131]
	global_load_lds_dwordx4 v[202:203], off
	v_lshl_add_u64 v[202:203], s[40:41], 0, v[132:133]
	s_add_i32 m0, s35, 0x2000
	s_nop 0
	global_load_lds_dwordx4 v[202:203], off
	v_lshl_add_u64 v[202:203], s[44:45], 0, v[128:129]
	s_mov_b32 m0, s80
	s_nop 0
	global_load_lds_dwordx4 v[202:203], off
	s_mov_b32 m0, s81
	s_nop 0
	global_load_lds_dwordx4 v[204:205], off
	s_waitcnt vmcnt(8)
	s_waitcnt lgkmcnt(0)
	s_barrier
; #define PG8_STAGE(bufoff, gbase, voff) do { _Pragma("unroll") for (int _i = 0; _i < 2; ++_i) \
;         __builtin_amdgcn_global_load_lds((const unsigned*)((const char*)(gbase) + (voff)[_i]), (PG8_LAS unsigned*)(lds + (bufoff) + ldsw + _i * 8192), 16, 0, 0); } while (0)
; #define PG8_LDA(dst, b, h) do { _Pragma("unroll") for (int m = 0; m < 4; ++m) _Pragma("unroll") for (int k = 0; k < 2; ++k) dst[m][k] = *(const PG8_LAS bf16x8*)(lds + PG8_SA(b, h) + aoff + m * 2048 + k * 1024); } while (0)
; #define PG8_LDB(dst, b, h) do { _Pragma("unroll") for (int n = 0; n < 2; ++n) _Pragma("unroll") for (int k = 0; k < 2; ++k) dst[n][k] = *(const PG8_LAS bf16x8*)(lds + PG8_SB(b, h) + boff + n * 2048 + k * 1024); } while (0)
; #define PG8_MMA(ai, bj, At, Bt) do { __builtin_amdgcn_s_setprio(1); _Pragma("unroll") for (int m = 0; m < 4; ++m) _Pragma("unroll") for (int n = 0; n < 2; ++n) _Pragma("unroll") for (int k = 0; k < 2; ++k) \
;         acc[ai][bj][m][n] = __builtin_amdgcn_mfma_f32_16x16x32_bf16(Bt[n][k], At[m][k], acc[ai][bj][m][n], 0, 0, 0); __builtin_amdgcn_s_setprio(0); } while (0)
; #define PG8_WAIT_V(n) asm volatile("s_waitcnt vmcnt(" #n ")" ::: "memory")
; #define PG8_WAIT_L(n) asm volatile("s_waitcnt lgkmcnt(" #n ")" ::: "memory")
; #define PG8_BAR __builtin_amdgcn_s_barrier()
; #define PG8_SCHED __builtin_amdgcn_sched_barrier(0)
; template <class Epi, class Sched, bool ALIGN_EPI = false, bool SP2 = false>
; __device__ __forceinline__ void gemm_phase(PG8_LAS unsigned char* lds, const Gemm g, const Sched& S, const Epi& E, const int tid) {
;     ...
;             PG8_WAIT_V(8); PG8_WAIT_L(0); PG8_BAR; PG8_MMA(1, 0, At, B0); PG8_MMA(1, 1, At, B1); PG8_BAR; PG8_SCHED;
;             PG8_LDB(B0, 1, 0); PG8_LDB(B1, 1, 1); PG8_SCHED; PG8_LDA(At, 1, 0); PG8_STAGE(PG8_SA(0, 1), a2 + hstep, voffA);
;             PG8_WAIT_V(8); PG8_WAIT_L(0); PG8_BAR; PG8_MMA(0, 0, At, B0); PG8_MMA(0, 1, At, B1); PG8_BAR; PG8_SCHED;
	s_waitcnt lgkmcnt(0)
	v_mfma_f32_16x16x32_bf16 v[60:63], v[138:141], v[172:175], v[60:63]
	v_mfma_f32_16x16x32_bf16 v[56:59], v[148:151], v[172:175], v[56:59]
	v_mfma_f32_16x16x32_bf16 v[44:47], v[138:141], v[180:183], v[44:47]
	v_mfma_f32_16x16x32_bf16 v[40:43], v[148:151], v[180:183], v[40:43]
	v_mfma_f32_16x16x32_bf16 v[28:31], v[138:141], v[188:191], v[28:31]
	v_mfma_f32_16x16x32_bf16 v[24:27], v[148:151], v[188:191], v[24:27]
	v_mfma_f32_16x16x32_bf16 v[12:15], v[138:141], v[216:219], v[12:15]
	v_mfma_f32_16x16x32_bf16 v[8:11], v[148:151], v[216:219], v[8:11]
	v_mfma_f32_16x16x32_bf16 v[60:63], v[144:147], v[176:179], v[60:63]
	v_mfma_f32_16x16x32_bf16 v[56:59], v[152:155], v[176:179], v[56:59]
	v_mfma_f32_16x16x32_bf16 v[44:47], v[144:147], v[184:187], v[44:47]
	v_mfma_f32_16x16x32_bf16 v[40:43], v[152:155], v[184:187], v[40:43]
	v_mfma_f32_16x16x32_bf16 v[28:31], v[144:147], v[212:215], v[28:31]
	v_mfma_f32_16x16x32_bf16 v[24:27], v[152:155], v[212:215], v[24:27]
	v_mfma_f32_16x16x32_bf16 v[12:15], v[144:147], v[232:235], v[12:15]
	v_mfma_f32_16x16x32_bf16 v[8:11], v[152:155], v[232:235], v[8:11]
	v_mfma_f32_16x16x32_bf16 v[52:55], v[156:159], v[172:175], v[52:55]
	v_mfma_f32_16x16x32_bf16 v[48:51], v[164:167], v[172:175], v[48:51]
	v_mfma_f32_16x16x32_bf16 v[36:39], v[156:159], v[180:183], v[36:39]
	v_mfma_f32_16x16x32_bf16 v[32:35], v[164:167], v[180:183], v[32:35]
	v_mfma_f32_16x16x32_bf16 v[20:23], v[156:159], v[188:191], v[20:23]
	v_mfma_f32_16x16x32_bf16 v[16:19], v[164:167], v[188:191], v[16:19]
	v_mfma_f32_16x16x32_bf16 v[4:7], v[156:159], v[216:219], v[4:7]
	v_mfma_f32_16x16x32_bf16 v[0:3], v[164:167], v[216:219], v[0:3]
	v_mfma_f32_16x16x32_bf16 v[52:55], v[160:163], v[176:179], v[52:55]
	v_mfma_f32_16x16x32_bf16 v[48:51], v[168:171], v[176:179], v[48:51]
	v_mfma_f32_16x16x32_bf16 v[36:39], v[160:163], v[184:187], v[36:39]
	v_mfma_f32_16x16x32_bf16 v[32:35], v[168:171], v[184:187], v[32:35]
	v_mfma_f32_16x16x32_bf16 v[20:23], v[160:163], v[212:215], v[20:23]
	v_mfma_f32_16x16x32_bf16 v[16:19], v[168:171], v[212:215], v[16:19]
	v_mfma_f32_16x16x32_bf16 v[4:7], v[160:163], v[232:235], v[4:7]
	v_mfma_f32_16x16x32_bf16 v[0:3], v[168:171], v[232:235], v[0:3]
	s_barrier
	s_add_i32 s35, 0, 0x18000
	s_add_i32 s38, 0, 0x1c000
	v_add_u32_e32 v152, s35, v142
	v_add_u32_e32 v168, s38, v142
	ds_read_b128 v[138:141], v152
	ds_read_b128 v[144:147], v152 offset:1024
	ds_read_b128 v[148:151], v152 offset:2048
	ds_read_b128 v[152:155], v152 offset:3072
	ds_read_b128 v[156:159], v168
	ds_read_b128 v[160:163], v168 offset:1024
	ds_read_b128 v[164:167], v168 offset:2048
	ds_read_b128 v[168:171], v168 offset:3072
	s_add_u32 s40, s44, 0x40000
	s_addc_u32 s41, s45, 0
	s_mov_b32 m0, s82
	v_lshl_add_u64 v[206:207], s[40:41], 0, v[128:129]
	ds_read_b128 v[172:175], v143 offset:32768
	ds_read_b128 v[176:179], v143 offset:33792
	ds_read_b128 v[180:183], v143 offset:34816
	ds_read_b128 v[184:187], v143 offset:35840
	ds_read_b128 v[188:191], v143 offset:36864
	ds_read_b128 v[212:215], v143 offset:37888
	ds_read_b128 v[216:219], v143 offset:38912
	ds_read_b128 v[232:235], v143 offset:39936
	global_load_lds_dwordx4 v[206:207], off
	v_lshl_add_u64 v[206:207], s[40:41], 0, v[130:131]
	s_mov_b32 m0, s83
	s_nop 0
	global_load_lds_dwordx4 v[206:207], off
	s_waitcnt vmcnt(8)
	s_waitcnt lgkmcnt(0)
	s_barrier
	s_waitcnt lgkmcnt(0)
	v_mfma_f32_16x16x32_bf16 v[124:127], v[138:141], v[172:175], v[124:127]
	v_mfma_f32_16x16x32_bf16 v[120:123], v[148:151], v[172:175], v[120:123]
	v_mfma_f32_16x16x32_bf16 v[108:111], v[138:141], v[180:183], v[108:111]
	v_mfma_f32_16x16x32_bf16 v[104:107], v[148:151], v[180:183], v[104:107]
	v_mfma_f32_16x16x32_bf16 v[92:95], v[138:141], v[188:191], v[92:95]
	v_mfma_f32_16x16x32_bf16 v[88:91], v[148:151], v[188:191], v[88:91]
	v_mfma_f32_16x16x32_bf16 v[76:79], v[138:141], v[216:219], v[76:79]
	v_mfma_f32_16x16x32_bf16 v[72:75], v[148:151], v[216:219], v[72:75]
	v_mfma_f32_16x16x32_bf16 v[124:127], v[144:147], v[176:179], v[124:127]
	v_mfma_f32_16x16x32_bf16 v[120:123], v[152:155], v[176:179], v[120:123]
	v_mfma_f32_16x16x32_bf16 v[108:111], v[144:147], v[184:187], v[108:111]
	v_mfma_f32_16x16x32_bf16 v[104:107], v[152:155], v[184:187], v[104:107]
	v_mfma_f32_16x16x32_bf16 v[92:95], v[144:147], v[212:215], v[92:95]
	v_mfma_f32_16x16x32_bf16 v[88:91], v[152:155], v[212:215], v[88:91]
	v_mfma_f32_16x16x32_bf16 v[76:79], v[144:147], v[232:235], v[76:79]
	v_mfma_f32_16x16x32_bf16 v[72:75], v[152:155], v[232:235], v[72:75]
	v_mfma_f32_16x16x32_bf16 v[116:119], v[156:159], v[172:175], v[116:119]
	v_mfma_f32_16x16x32_bf16 v[112:115], v[164:167], v[172:175], v[112:115]
	v_mfma_f32_16x16x32_bf16 v[100:103], v[156:159], v[180:183], v[100:103]
	v_mfma_f32_16x16x32_bf16 v[96:99], v[164:167], v[180:183], v[96:99]
	v_mfma_f32_16x16x32_bf16 v[84:87], v[156:159], v[188:191], v[84:87]
	v_mfma_f32_16x16x32_bf16 v[80:83], v[164:167], v[188:191], v[80:83]
	v_mfma_f32_16x16x32_bf16 v[68:71], v[156:159], v[216:219], v[68:71]
	v_mfma_f32_16x16x32_bf16 v[64:67], v[164:167], v[216:219], v[64:67]
	v_mfma_f32_16x16x32_bf16 v[116:119], v[160:163], v[176:179], v[116:119]
	v_mfma_f32_16x16x32_bf16 v[112:115], v[168:171], v[176:179], v[112:115]
	v_mfma_f32_16x16x32_bf16 v[100:103], v[160:163], v[184:187], v[100:103]
	v_mfma_f32_16x16x32_bf16 v[96:99], v[168:171], v[184:187], v[96:99]
	v_mfma_f32_16x16x32_bf16 v[84:87], v[160:163], v[212:215], v[84:87]
	v_mfma_f32_16x16x32_bf16 v[80:83], v[168:171], v[212:215], v[80:83]
	v_mfma_f32_16x16x32_bf16 v[68:71], v[160:163], v[232:235], v[68:71]
	v_mfma_f32_16x16x32_bf16 v[64:67], v[168:171], v[232:235], v[64:67]
	s_barrier
; #define PG8_STAGE(bufoff, gbase, voff) do { _Pragma("unroll") for (int _i = 0; _i < 2; ++_i) \
;         __builtin_amdgcn_global_load_lds((const unsigned*)((const char*)(gbase) + (voff)[_i]), (PG8_LAS unsigned*)(lds + (bufoff) + ldsw + _i * 8192), 16, 0, 0); } while (0)
; #define PG8_LDA(dst, b, h) do { _Pragma("unroll") for (int m = 0; m < 4; ++m) _Pragma("unroll") for (int k = 0; k < 2; ++k) dst[m][k] = *(const PG8_LAS bf16x8*)(lds + PG8_SA(b, h) + aoff + m * 2048 + k * 1024); } while (0)
; #define PG8_MMA(ai, bj, At, Bt) do { __builtin_amdgcn_s_setprio(1); _Pragma("unroll") for (int m = 0; m < 4; ++m) _Pragma("unroll") for (int n = 0; n < 2; ++n) _Pragma("unroll") for (int k = 0; k < 2; ++k) \
;         acc[ai][bj][m][n] = __builtin_amdgcn_mfma_f32_16x16x32_bf16(Bt[n][k], At[m][k], acc[ai][bj][m][n], 0, 0, 0); __builtin_amdgcn_s_setprio(0); } while (0)
; #define PG8_WAIT_V(n) asm volatile("s_waitcnt vmcnt(" #n ")" ::: "memory")
; #define PG8_WAIT_L(n) asm volatile("s_waitcnt lgkmcnt(" #n ")" ::: "memory")
; #define PG8_BAR __builtin_amdgcn_s_barrier()
; #define PG8_SCHED __builtin_amdgcn_sched_barrier(0)
; template <class Epi, class Sched, bool ALIGN_EPI = false, bool SP2 = false>
; __device__ __forceinline__ void gemm_phase(PG8_LAS unsigned char* lds, const Gemm g, const Sched& S, const Epi& E, const int tid) {
;     ...
;         for (int t = 0; t < nt; t += 2) {
;     ...
;             PG8_LDA(At, 1, 1); PG8_STAGE(PG8_SB(1, 0), b3, voffB); PG8_STAGE(PG8_SB(1, 1), b3 + hstep, voffB); PG8_STAGE(PG8_SA(1, 0), a3, voffA);
;             PG8_WAIT_V(8); PG8_WAIT_L(0); PG8_BAR; PG8_MMA(1, 0, At, B0); PG8_MMA(1, 1, At, B1); PG8_BAR; PG8_SCHED;
;     ...
;         if constexpr (ALIGN_EPI) { if (wr == 0) PG8_BAR; }
	s_add_i32 s35, s35, s79
	v_lshl_add_u64 v[194:195], v[194:195], 0, s[36:37]
	s_mov_b32 m0, s35
	ds_read_b128 v[172:175], v143 offset:49152
	ds_read_b128 v[176:179], v143 offset:50176
	ds_read_b128 v[180:183], v143 offset:51200
	ds_read_b128 v[184:187], v143 offset:52224
	ds_read_b128 v[188:191], v143 offset:53248
	ds_read_b128 v[212:215], v143 offset:54272
	ds_read_b128 v[216:219], v143 offset:55296
	ds_read_b128 v[232:235], v143 offset:56320
	global_load_lds_dwordx4 v[194:195], off
	s_add_i32 m0, s35, 0x2000
	s_add_u32 s28, s28, 0x40080
	v_lshl_add_u64 v[194:195], v[196:197], 0, s[36:37]
	s_addc_u32 s29, s29, 0
	s_add_i32 s35, s38, s79
	global_load_lds_dwordx4 v[194:195], off
	v_lshl_add_u64 v[194:195], s[28:29], 0, v[192:193]
	s_mov_b32 m0, s35
	s_nop 0
	global_load_lds_dwordx4 v[194:195], off
	v_lshl_add_u64 v[194:195], s[28:29], 0, v[132:133]
	s_add_i32 m0, s35, 0x2000
	s_nop 0
	global_load_lds_dwordx4 v[194:195], off
	v_lshl_add_u64 v[194:195], v[202:203], 0, s[36:37]
	s_mov_b32 m0, s84
	s_nop 0
	global_load_lds_dwordx4 v[194:195], off
	v_lshl_add_u64 v[194:195], v[204:205], 0, s[36:37]
	s_mov_b32 m0, s85
	s_nop 0
	global_load_lds_dwordx4 v[194:195], off
	s_add_i32 s34, s34, 2
	s_add_u32 s22, s22, 0x100
	s_addc_u32 s23, s23, 0
	s_add_u32 s21, s21, 0x100
	s_addc_u32 s26, s26, 0
	s_cmp_gt_u32 s34, 13
	s_waitcnt vmcnt(8)
	s_waitcnt lgkmcnt(0)
	s_barrier
	s_waitcnt lgkmcnt(0)
	v_mfma_f32_16x16x32_bf16 v[60:63], v[138:141], v[172:175], v[60:63]
	v_mfma_f32_16x16x32_bf16 v[56:59], v[148:151], v[172:175], v[56:59]
	v_mfma_f32_16x16x32_bf16 v[44:47], v[138:141], v[180:183], v[44:47]
	v_mfma_f32_16x16x32_bf16 v[40:43], v[148:151], v[180:183], v[40:43]
	v_mfma_f32_16x16x32_bf16 v[28:31], v[138:141], v[188:191], v[28:31]
	v_mfma_f32_16x16x32_bf16 v[24:27], v[148:151], v[188:191], v[24:27]
	v_mfma_f32_16x16x32_bf16 v[12:15], v[138:141], v[216:219], v[12:15]
	v_mfma_f32_16x16x32_bf16 v[8:11], v[148:151], v[216:219], v[8:11]
	v_mfma_f32_16x16x32_bf16 v[60:63], v[144:147], v[176:179], v[60:63]
	v_mfma_f32_16x16x32_bf16 v[56:59], v[152:155], v[176:179], v[56:59]
	v_mfma_f32_16x16x32_bf16 v[44:47], v[144:147], v[184:187], v[44:47]
	v_mfma_f32_16x16x32_bf16 v[40:43], v[152:155], v[184:187], v[40:43]
	v_mfma_f32_16x16x32_bf16 v[28:31], v[144:147], v[212:215], v[28:31]
	v_mfma_f32_16x16x32_bf16 v[24:27], v[152:155], v[212:215], v[24:27]
	v_mfma_f32_16x16x32_bf16 v[12:15], v[144:147], v[232:235], v[12:15]
	v_mfma_f32_16x16x32_bf16 v[8:11], v[152:155], v[232:235], v[8:11]
	v_mfma_f32_16x16x32_bf16 v[52:55], v[156:159], v[172:175], v[52:55]
	v_mfma_f32_16x16x32_bf16 v[48:51], v[164:167], v[172:175], v[48:51]
	v_mfma_f32_16x16x32_bf16 v[36:39], v[156:159], v[180:183], v[36:39]
	v_mfma_f32_16x16x32_bf16 v[32:35], v[164:167], v[180:183], v[32:35]
	v_mfma_f32_16x16x32_bf16 v[20:23], v[156:159], v[188:191], v[20:23]
	v_mfma_f32_16x16x32_bf16 v[16:19], v[164:167], v[188:191], v[16:19]
	v_mfma_f32_16x16x32_bf16 v[4:7], v[156:159], v[216:219], v[4:7]
	v_mfma_f32_16x16x32_bf16 v[0:3], v[164:167], v[216:219], v[0:3]
	v_mfma_f32_16x16x32_bf16 v[52:55], v[160:163], v[176:179], v[52:55]
	v_mfma_f32_16x16x32_bf16 v[48:51], v[168:171], v[176:179], v[48:51]
	v_mfma_f32_16x16x32_bf16 v[36:39], v[160:163], v[184:187], v[36:39]
	v_mfma_f32_16x16x32_bf16 v[32:35], v[168:171], v[184:187], v[32:35]
	v_mfma_f32_16x16x32_bf16 v[20:23], v[160:163], v[212:215], v[20:23]
	v_mfma_f32_16x16x32_bf16 v[16:19], v[168:171], v[212:215], v[16:19]
	v_mfma_f32_16x16x32_bf16 v[4:7], v[160:163], v[232:235], v[4:7]
	v_mfma_f32_16x16x32_bf16 v[0:3], v[168:171], v[232:235], v[0:3]
	s_barrier
	s_cbranch_scc0 .LBB0_324
	s_and_b64 vcc, exec, s[10:11]
	s_cbranch_vccz .LBB0_327
	s_barrier

; #define PG8_STAGE(bufoff, gbase, voff) do { _Pragma("unroll") for (int _i = 0; _i < 2; ++_i) \
;         __builtin_amdgcn_global_load_lds((const unsigned*)((const char*)(gbase) + (voff)[_i]), (PG8_LAS unsigned*)(lds + (bufoff) + ldsw + _i * 8192), 16, 0, 0); } while (0)
; #define PG8_LDA(dst, b, h) do { _Pragma("unroll") for (int m = 0; m < 4; ++m) _Pragma("unroll") for (int k = 0; k < 2; ++k) dst[m][k] = *(const PG8_LAS bf16x8*)(lds + PG8_SA(b, h) + aoff + m * 2048 + k * 1024); } while (0)
; #define PG8_LDB(dst, b, h) do { _Pragma("unroll") for (int n = 0; n < 2; ++n) _Pragma("unroll") for (int k = 0; k < 2; ++k) dst[n][k] = *(const PG8_LAS bf16x8*)(lds + PG8_SB(b, h) + boff + n * 2048 + k * 1024); } while (0)
; #define PG8_MMA(ai, bj, At, Bt) do { __builtin_amdgcn_s_setprio(1); _Pragma("unroll") for (int m = 0; m < 4; ++m) _Pragma("unroll") for (int n = 0; n < 2; ++n) _Pragma("unroll") for (int k = 0; k < 2; ++k) \
;         acc[ai][bj][m][n] = __builtin_amdgcn_mfma_f32_16x16x32_bf16(Bt[n][k], At[m][k], acc[ai][bj][m][n], 0, 0, 0); __builtin_amdgcn_s_setprio(0); } while (0)
; #define PG8_WAIT_V(n) asm volatile("s_waitcnt vmcnt(" #n ")" ::: "memory")
; #define PG8_WAIT_L(n) asm volatile("s_waitcnt lgkmcnt(" #n ")" ::: "memory")
; #define PG8_BAR __builtin_amdgcn_s_barrier()
; template <class Epi, class Sched, bool ALIGN_EPI = false, bool SP2 = false>
; __device__ __forceinline__ void gemm_phase(PG8_LAS unsigned char* lds, const Gemm g, const Sched& S, const Epi& E, const int tid) {
;     ...
;         for (int t = 0; t < nt; t += 2) {
;             const bool last = (t == nt - 2);
;             const char* a1 = cA + (size_t)(t + 1) * kstep;
;             const char* a2 = last ? nA : cA + (size_t)(t + 2) * kstep; const char* b2 = last ? nB : cB + (size_t)(t + 2) * kstep;
;             const char* a3 = a2 + kstep; const char* b3 = b2 + kstep;
;             if (last && has_next) S.a_ready(nxt);
;             if constexpr (SP2) {
;             PG8_LDB(B0, 0, 0); PG8_LDB(B1, 0, 1); PG8_SCHED; PG8_LDA(At, 0, 0); PG8_STAGE(PG8_SA(1, 1), a1 + hstep, voffA);
;             PG8_WAIT_V(8); PG8_WAIT_L(0); PG8_BAR; PG8_MMA(0, 0, At, B0); PG8_MMA(0, 1, At, B1); PG8_BAR; PG8_SCHED;
;             PG8_LDA(At, 0, 1); PG8_STAGE(PG8_SB(0, 0), b2, voffB); PG8_STAGE(PG8_SB(0, 1), b2 + hstep, voffB); PG8_STAGE(PG8_SA(0, 0), a2, voffA);
.LBB0_348:
	v_add_u32_e32 v152, 0x10000, v142
	v_add_u32_e32 v168, 0x14000, v142
	ds_read_b128 v[138:141], v152
	ds_read_b128 v[144:147], v152 offset:1024
	ds_read_b128 v[148:151], v152 offset:2048
	ds_read_b128 v[152:155], v152 offset:3072
	ds_read_b128 v[156:159], v168
	ds_read_b128 v[160:163], v168 offset:1024
	ds_read_b128 v[164:167], v168 offset:2048
	ds_read_b128 v[168:171], v168 offset:3072
	s_add_u32 s35, s28, 0xfffe0080
	s_addc_u32 s38, s29, -1
	s_add_i32 s40, 0, 0x10000
	s_cmp_eq_u32 s34, 4
	s_cselect_b32 s59, s1, s38
	s_cselect_b32 s58, s2, s35
	s_cselect_b32 s45, s15, s26
	s_cselect_b32 s44, s17, s23
	s_add_i32 s35, 0, 0x14000
	v_lshl_add_u64 v[194:195], s[28:29], 0, v[134:135]
	s_add_i32 m0, s83, 0xc000
	ds_read_b128 v[172:175], v143
	ds_read_b128 v[176:179], v143 offset:1024
	ds_read_b128 v[180:183], v143 offset:2048
	ds_read_b128 v[184:187], v143 offset:3072
	ds_read_b128 v[188:191], v143 offset:4096
	ds_read_b128 v[212:215], v143 offset:5120
	ds_read_b128 v[216:219], v143 offset:6144
	ds_read_b128 v[232:235], v143 offset:7168
	global_load_lds_dwordx4 v[194:195], off
	v_lshl_add_u64 v[194:195], s[28:29], 0, v[136:137]
	s_add_i32 m0, s83, 0xe000
	s_nop 0
	global_load_lds_dwordx4 v[194:195], off
	s_waitcnt vmcnt(8)
	s_waitcnt lgkmcnt(0)
	s_barrier
	s_waitcnt lgkmcnt(0)
	v_mfma_f32_16x16x32_bf16 v[124:127], v[138:141], v[172:175], v[124:127]
	v_mfma_f32_16x16x32_bf16 v[120:123], v[148:151], v[172:175], v[120:123]
	v_mfma_f32_16x16x32_bf16 v[108:111], v[138:141], v[180:183], v[108:111]
	v_mfma_f32_16x16x32_bf16 v[104:107], v[148:151], v[180:183], v[104:107]
	v_mfma_f32_16x16x32_bf16 v[92:95], v[138:141], v[188:191], v[92:95]
	v_mfma_f32_16x16x32_bf16 v[88:91], v[148:151], v[188:191], v[88:91]
	v_mfma_f32_16x16x32_bf16 v[76:79], v[138:141], v[216:219], v[76:79]
	v_mfma_f32_16x16x32_bf16 v[72:75], v[148:151], v[216:219], v[72:75]
	v_mfma_f32_16x16x32_bf16 v[124:127], v[144:147], v[176:179], v[124:127]
	v_mfma_f32_16x16x32_bf16 v[120:123], v[152:155], v[176:179], v[120:123]
	v_mfma_f32_16x16x32_bf16 v[108:111], v[144:147], v[184:187], v[108:111]
	v_mfma_f32_16x16x32_bf16 v[104:107], v[152:155], v[184:187], v[104:107]
	v_mfma_f32_16x16x32_bf16 v[92:95], v[144:147], v[212:215], v[92:95]
	v_mfma_f32_16x16x32_bf16 v[88:91], v[152:155], v[212:215], v[88:91]
	v_mfma_f32_16x16x32_bf16 v[76:79], v[144:147], v[232:235], v[76:79]
	v_mfma_f32_16x16x32_bf16 v[72:75], v[152:155], v[232:235], v[72:75]
	v_mfma_f32_16x16x32_bf16 v[116:119], v[156:159], v[172:175], v[116:119]
	v_mfma_f32_16x16x32_bf16 v[112:115], v[164:167], v[172:175], v[112:115]
	v_mfma_f32_16x16x32_bf16 v[100:103], v[156:159], v[180:183], v[100:103]
	v_mfma_f32_16x16x32_bf16 v[96:99], v[164:167], v[180:183], v[96:99]
	v_mfma_f32_16x16x32_bf16 v[84:87], v[156:159], v[188:191], v[84:87]
	v_mfma_f32_16x16x32_bf16 v[80:83], v[164:167], v[188:191], v[80:83]
	v_mfma_f32_16x16x32_bf16 v[68:71], v[156:159], v[216:219], v[68:71]
	v_mfma_f32_16x16x32_bf16 v[64:67], v[164:167], v[216:219], v[64:67]
	v_mfma_f32_16x16x32_bf16 v[116:119], v[160:163], v[176:179], v[116:119]
	v_mfma_f32_16x16x32_bf16 v[112:115], v[168:171], v[176:179], v[112:115]
	v_mfma_f32_16x16x32_bf16 v[100:103], v[160:163], v[184:187], v[100:103]
	v_mfma_f32_16x16x32_bf16 v[96:99], v[168:171], v[184:187], v[96:99]
	v_mfma_f32_16x16x32_bf16 v[84:87], v[160:163], v[212:215], v[84:87]
	v_mfma_f32_16x16x32_bf16 v[80:83], v[168:171], v[212:215], v[80:83]
	v_mfma_f32_16x16x32_bf16 v[68:71], v[160:163], v[232:235], v[68:71]
	v_mfma_f32_16x16x32_bf16 v[64:67], v[168:171], v[232:235], v[64:67]
	s_barrier
	s_add_i32 s38, s40, s82
	v_lshl_add_u64 v[194:195], s[44:45], 0, v[192:193]
	s_mov_b32 m0, s38
	ds_read_b128 v[172:175], v143 offset:16384
	ds_read_b128 v[176:179], v143 offset:17408
	ds_read_b128 v[180:183], v143 offset:18432
	ds_read_b128 v[184:187], v143 offset:19456
	ds_read_b128 v[188:191], v143 offset:20480
	ds_read_b128 v[212:215], v143 offset:21504
	ds_read_b128 v[216:219], v143 offset:22528
	ds_read_b128 v[232:235], v143 offset:23552
	global_load_lds_dwordx4 v[194:195], off
	s_add_i32 m0, s38, 0x2000
	s_add_u32 s40, s44, 0x20000
	v_lshl_add_u64 v[196:197], s[44:45], 0, v[132:133]
	s_addc_u32 s41, s45, 0
	s_add_i32 s35, s35, s82
	global_load_lds_dwordx4 v[196:197], off
	v_lshl_add_u64 v[202:203], s[40:41], 0, v[192:193]
	s_mov_b32 m0, s35
	v_lshl_add_u64 v[204:205], s[58:59], 0, v[130:131]
	global_load_lds_dwordx4 v[202:203], off
	v_lshl_add_u64 v[202:203], s[40:41], 0, v[132:133]
	s_add_i32 m0, s35, 0x2000
	s_nop 0
	global_load_lds_dwordx4 v[202:203], off
	v_lshl_add_u64 v[202:203], s[58:59], 0, v[128:129]
	s_mov_b32 m0, s83
	s_nop 0
	global_load_lds_dwordx4 v[202:203], off
	s_mov_b32 m0, s84
	s_nop 0
	global_load_lds_dwordx4 v[204:205], off
	s_waitcnt vmcnt(8)
	s_waitcnt lgkmcnt(0)
	s_barrier
; #define PG8_STAGE(bufoff, gbase, voff) do { _Pragma("unroll") for (int _i = 0; _i < 2; ++_i) \
;         __builtin_amdgcn_global_load_lds((const unsigned*)((const char*)(gbase) + (voff)[_i]), (PG8_LAS unsigned*)(lds + (bufoff) + ldsw + _i * 8192), 16, 0, 0); } while (0)
; #define PG8_LDA(dst, b, h) do { _Pragma("unroll") for (int m = 0; m < 4; ++m) _Pragma("unroll") for (int k = 0; k < 2; ++k) dst[m][k] = *(const PG8_LAS bf16x8*)(lds + PG8_SA(b, h) + aoff + m * 2048 + k * 1024); } while (0)
; #define PG8_LDB(dst, b, h) do { _Pragma("unroll") for (int n = 0; n < 2; ++n) _Pragma("unroll") for (int k = 0; k < 2; ++k) dst[n][k] = *(const PG8_LAS bf16x8*)(lds + PG8_SB(b, h) + boff + n * 2048 + k * 1024); } while (0)
; #define PG8_MMA(ai, bj, At, Bt) do { __builtin_amdgcn_s_setprio(1); _Pragma("unroll") for (int m = 0; m < 4; ++m) _Pragma("unroll") for (int n = 0; n < 2; ++n) _Pragma("unroll") for (int k = 0; k < 2; ++k) \
;         acc[ai][bj][m][n] = __builtin_amdgcn_mfma_f32_16x16x32_bf16(Bt[n][k], At[m][k], acc[ai][bj][m][n], 0, 0, 0); __builtin_amdgcn_s_setprio(0); } while (0)
; #define PG8_WAIT_V(n) asm volatile("s_waitcnt vmcnt(" #n ")" ::: "memory")
; #define PG8_WAIT_L(n) asm volatile("s_waitcnt lgkmcnt(" #n ")" ::: "memory")
; #define PG8_BAR __builtin_amdgcn_s_barrier()
; #define PG8_SCHED __builtin_amdgcn_sched_barrier(0)
; template <class Epi, class Sched, bool ALIGN_EPI = false, bool SP2 = false>
; __device__ __forceinline__ void gemm_phase(PG8_LAS unsigned char* lds, const Gemm g, const Sched& S, const Epi& E, const int tid) {
;     ...
;             PG8_WAIT_V(8); PG8_WAIT_L(0); PG8_BAR; PG8_MMA(1, 0, At, B0); PG8_MMA(1, 1, At, B1); PG8_BAR; PG8_SCHED;
;             PG8_LDB(B0, 1, 0); PG8_LDB(B1, 1, 1); PG8_SCHED; PG8_LDA(At, 1, 0); PG8_STAGE(PG8_SA(0, 1), a2 + hstep, voffA);
;             PG8_WAIT_V(8); PG8_WAIT_L(0); PG8_BAR; PG8_MMA(0, 0, At, B0); PG8_MMA(0, 1, At, B1); PG8_BAR; PG8_SCHED;
	s_waitcnt lgkmcnt(0)
	v_mfma_f32_16x16x32_bf16 v[60:63], v[138:141], v[172:175], v[60:63]
	v_mfma_f32_16x16x32_bf16 v[56:59], v[148:151], v[172:175], v[56:59]
	v_mfma_f32_16x16x32_bf16 v[44:47], v[138:141], v[180:183], v[44:47]
	v_mfma_f32_16x16x32_bf16 v[40:43], v[148:151], v[180:183], v[40:43]
	v_mfma_f32_16x16x32_bf16 v[28:31], v[138:141], v[188:191], v[28:31]
	v_mfma_f32_16x16x32_bf16 v[24:27], v[148:151], v[188:191], v[24:27]
	v_mfma_f32_16x16x32_bf16 v[12:15], v[138:141], v[216:219], v[12:15]
	v_mfma_f32_16x16x32_bf16 v[8:11], v[148:151], v[216:219], v[8:11]
	v_mfma_f32_16x16x32_bf16 v[60:63], v[144:147], v[176:179], v[60:63]
	v_mfma_f32_16x16x32_bf16 v[56:59], v[152:155], v[176:179], v[56:59]
	v_mfma_f32_16x16x32_bf16 v[44:47], v[144:147], v[184:187], v[44:47]
	v_mfma_f32_16x16x32_bf16 v[40:43], v[152:155], v[184:187], v[40:43]
	v_mfma_f32_16x16x32_bf16 v[28:31], v[144:147], v[212:215], v[28:31]
	v_mfma_f32_16x16x32_bf16 v[24:27], v[152:155], v[212:215], v[24:27]
	v_mfma_f32_16x16x32_bf16 v[12:15], v[144:147], v[232:235], v[12:15]
	v_mfma_f32_16x16x32_bf16 v[8:11], v[152:155], v[232:235], v[8:11]
	v_mfma_f32_16x16x32_bf16 v[52:55], v[156:159], v[172:175], v[52:55]
	v_mfma_f32_16x16x32_bf16 v[48:51], v[164:167], v[172:175], v[48:51]
	v_mfma_f32_16x16x32_bf16 v[36:39], v[156:159], v[180:183], v[36:39]
	v_mfma_f32_16x16x32_bf16 v[32:35], v[164:167], v[180:183], v[32:35]
	v_mfma_f32_16x16x32_bf16 v[20:23], v[156:159], v[188:191], v[20:23]
	v_mfma_f32_16x16x32_bf16 v[16:19], v[164:167], v[188:191], v[16:19]
	v_mfma_f32_16x16x32_bf16 v[4:7], v[156:159], v[216:219], v[4:7]
	v_mfma_f32_16x16x32_bf16 v[0:3], v[164:167], v[216:219], v[0:3]
	v_mfma_f32_16x16x32_bf16 v[52:55], v[160:163], v[176:179], v[52:55]
	v_mfma_f32_16x16x32_bf16 v[48:51], v[168:171], v[176:179], v[48:51]
	v_mfma_f32_16x16x32_bf16 v[36:39], v[160:163], v[184:187], v[36:39]
	v_mfma_f32_16x16x32_bf16 v[32:35], v[168:171], v[184:187], v[32:35]
	v_mfma_f32_16x16x32_bf16 v[20:23], v[160:163], v[212:215], v[20:23]
	v_mfma_f32_16x16x32_bf16 v[16:19], v[168:171], v[212:215], v[16:19]
	v_mfma_f32_16x16x32_bf16 v[4:7], v[160:163], v[232:235], v[4:7]
	v_mfma_f32_16x16x32_bf16 v[0:3], v[168:171], v[232:235], v[0:3]
	s_barrier
	s_add_i32 s35, 0, 0x18000
	s_add_i32 s38, 0, 0x1c000
	v_add_u32_e32 v152, s35, v142
	v_add_u32_e32 v168, s38, v142
	ds_read_b128 v[138:141], v152
	ds_read_b128 v[144:147], v152 offset:1024
	ds_read_b128 v[148:151], v152 offset:2048
	ds_read_b128 v[152:155], v152 offset:3072
	ds_read_b128 v[156:159], v168
	ds_read_b128 v[160:163], v168 offset:1024
	ds_read_b128 v[164:167], v168 offset:2048
	ds_read_b128 v[168:171], v168 offset:3072
	s_add_u32 s40, s58, 0x20000
	s_addc_u32 s41, s59, 0
	s_mov_b32 m0, s85
	v_lshl_add_u64 v[206:207], s[40:41], 0, v[128:129]
	ds_read_b128 v[172:175], v143 offset:32768
	ds_read_b128 v[176:179], v143 offset:33792
	ds_read_b128 v[180:183], v143 offset:34816
	ds_read_b128 v[184:187], v143 offset:35840
	ds_read_b128 v[188:191], v143 offset:36864
	ds_read_b128 v[212:215], v143 offset:37888
	ds_read_b128 v[216:219], v143 offset:38912
	ds_read_b128 v[232:235], v143 offset:39936
	global_load_lds_dwordx4 v[206:207], off
	v_lshl_add_u64 v[206:207], s[40:41], 0, v[130:131]
	s_mov_b32 m0, s86
	s_nop 0
	global_load_lds_dwordx4 v[206:207], off
	s_waitcnt vmcnt(8)
	s_waitcnt lgkmcnt(0)
	s_barrier
	s_waitcnt lgkmcnt(0)
	v_mfma_f32_16x16x32_bf16 v[124:127], v[138:141], v[172:175], v[124:127]
	v_mfma_f32_16x16x32_bf16 v[120:123], v[148:151], v[172:175], v[120:123]
	v_mfma_f32_16x16x32_bf16 v[108:111], v[138:141], v[180:183], v[108:111]
	v_mfma_f32_16x16x32_bf16 v[104:107], v[148:151], v[180:183], v[104:107]
	v_mfma_f32_16x16x32_bf16 v[92:95], v[138:141], v[188:191], v[92:95]
	v_mfma_f32_16x16x32_bf16 v[88:91], v[148:151], v[188:191], v[88:91]
	v_mfma_f32_16x16x32_bf16 v[76:79], v[138:141], v[216:219], v[76:79]
	v_mfma_f32_16x16x32_bf16 v[72:75], v[148:151], v[216:219], v[72:75]
	v_mfma_f32_16x16x32_bf16 v[124:127], v[144:147], v[176:179], v[124:127]
	v_mfma_f32_16x16x32_bf16 v[120:123], v[152:155], v[176:179], v[120:123]
	v_mfma_f32_16x16x32_bf16 v[108:111], v[144:147], v[184:187], v[108:111]
	v_mfma_f32_16x16x32_bf16 v[104:107], v[152:155], v[184:187], v[104:107]
	v_mfma_f32_16x16x32_bf16 v[92:95], v[144:147], v[212:215], v[92:95]
	v_mfma_f32_16x16x32_bf16 v[88:91], v[152:155], v[212:215], v[88:91]
	v_mfma_f32_16x16x32_bf16 v[76:79], v[144:147], v[232:235], v[76:79]
	v_mfma_f32_16x16x32_bf16 v[72:75], v[152:155], v[232:235], v[72:75]
	v_mfma_f32_16x16x32_bf16 v[116:119], v[156:159], v[172:175], v[116:119]
	v_mfma_f32_16x16x32_bf16 v[112:115], v[164:167], v[172:175], v[112:115]
	v_mfma_f32_16x16x32_bf16 v[100:103], v[156:159], v[180:183], v[100:103]
	v_mfma_f32_16x16x32_bf16 v[96:99], v[164:167], v[180:183], v[96:99]
	v_mfma_f32_16x16x32_bf16 v[84:87], v[156:159], v[188:191], v[84:87]
	v_mfma_f32_16x16x32_bf16 v[80:83], v[164:167], v[188:191], v[80:83]
	v_mfma_f32_16x16x32_bf16 v[68:71], v[156:159], v[216:219], v[68:71]
	v_mfma_f32_16x16x32_bf16 v[64:67], v[164:167], v[216:219], v[64:67]
	v_mfma_f32_16x16x32_bf16 v[116:119], v[160:163], v[176:179], v[116:119]
	v_mfma_f32_16x16x32_bf16 v[112:115], v[168:171], v[176:179], v[112:115]
	v_mfma_f32_16x16x32_bf16 v[100:103], v[160:163], v[184:187], v[100:103]
	v_mfma_f32_16x16x32_bf16 v[96:99], v[168:171], v[184:187], v[96:99]
	v_mfma_f32_16x16x32_bf16 v[84:87], v[160:163], v[212:215], v[84:87]
	v_mfma_f32_16x16x32_bf16 v[80:83], v[168:171], v[212:215], v[80:83]
	v_mfma_f32_16x16x32_bf16 v[68:71], v[160:163], v[232:235], v[68:71]
	v_mfma_f32_16x16x32_bf16 v[64:67], v[168:171], v[232:235], v[64:67]
	s_barrier
; #define PG8_STAGE(bufoff, gbase, voff) do { _Pragma("unroll") for (int _i = 0; _i < 2; ++_i) \
;         __builtin_amdgcn_global_load_lds((const unsigned*)((const char*)(gbase) + (voff)[_i]), (PG8_LAS unsigned*)(lds + (bufoff) + ldsw + _i * 8192), 16, 0, 0); } while (0)
; #define PG8_LDA(dst, b, h) do { _Pragma("unroll") for (int m = 0; m < 4; ++m) _Pragma("unroll") for (int k = 0; k < 2; ++k) dst[m][k] = *(const PG8_LAS bf16x8*)(lds + PG8_SA(b, h) + aoff + m * 2048 + k * 1024); } while (0)
; #define PG8_MMA(ai, bj, At, Bt) do { __builtin_amdgcn_s_setprio(1); _Pragma("unroll") for (int m = 0; m < 4; ++m) _Pragma("unroll") for (int n = 0; n < 2; ++n) _Pragma("unroll") for (int k = 0; k < 2; ++k) \
;         acc[ai][bj][m][n] = __builtin_amdgcn_mfma_f32_16x16x32_bf16(Bt[n][k], At[m][k], acc[ai][bj][m][n], 0, 0, 0); __builtin_amdgcn_s_setprio(0); } while (0)
; #define PG8_WAIT_V(n) asm volatile("s_waitcnt vmcnt(" #n ")" ::: "memory")
; #define PG8_WAIT_L(n) asm volatile("s_waitcnt lgkmcnt(" #n ")" ::: "memory")
; #define PG8_BAR __builtin_amdgcn_s_barrier()
; #define PG8_SCHED __builtin_amdgcn_sched_barrier(0)
; template <class Epi, class Sched, bool ALIGN_EPI = false, bool SP2 = false>
; __device__ __forceinline__ void gemm_phase(PG8_LAS unsigned char* lds, const Gemm g, const Sched& S, const Epi& E, const int tid) {
;     ...
;         for (int t = 0; t < nt; t += 2) {
;     ...
;             PG8_LDA(At, 1, 1); PG8_STAGE(PG8_SB(1, 0), b3, voffB); PG8_STAGE(PG8_SB(1, 1), b3 + hstep, voffB); PG8_STAGE(PG8_SA(1, 0), a3, voffA);
;             PG8_WAIT_V(8); PG8_WAIT_L(0); PG8_BAR; PG8_MMA(1, 0, At, B0); PG8_MMA(1, 1, At, B1); PG8_BAR; PG8_SCHED;
;     ...
;         if constexpr (ALIGN_EPI) { if (wr == 0) PG8_BAR; }
	s_add_i32 s35, s35, s82
	v_lshl_add_u64 v[194:195], v[194:195], 0, s[36:37]
	s_mov_b32 m0, s35
	ds_read_b128 v[172:175], v143 offset:49152
	ds_read_b128 v[176:179], v143 offset:50176
	ds_read_b128 v[180:183], v143 offset:51200
	ds_read_b128 v[184:187], v143 offset:52224
	ds_read_b128 v[188:191], v143 offset:53248
	ds_read_b128 v[212:215], v143 offset:54272
	ds_read_b128 v[216:219], v143 offset:55296
	ds_read_b128 v[232:235], v143 offset:56320
	global_load_lds_dwordx4 v[194:195], off
	s_add_i32 m0, s35, 0x2000
	s_add_u32 s40, s44, 0x20080
	v_lshl_add_u64 v[194:195], v[196:197], 0, s[36:37]
	s_addc_u32 s41, s45, 0
	s_add_i32 s35, s38, s82
	global_load_lds_dwordx4 v[194:195], off
	v_lshl_add_u64 v[194:195], s[40:41], 0, v[192:193]
	s_mov_b32 m0, s35
	s_nop 0
	global_load_lds_dwordx4 v[194:195], off
	v_lshl_add_u64 v[194:195], s[40:41], 0, v[132:133]
	s_add_i32 m0, s35, 0x2000
	s_nop 0
	global_load_lds_dwordx4 v[194:195], off
	v_lshl_add_u64 v[194:195], v[202:203], 0, s[36:37]
	s_mov_b32 m0, s87
	s_nop 0
	global_load_lds_dwordx4 v[194:195], off
	v_lshl_add_u64 v[194:195], v[204:205], 0, s[36:37]
	s_mov_b32 m0, s88
	s_nop 0
	global_load_lds_dwordx4 v[194:195], off
	s_add_i32 s34, s34, 2
	s_add_u32 s28, s28, 0x100
	s_addc_u32 s29, s29, 0
	s_add_u32 s23, s23, 0x100
	s_addc_u32 s26, s26, 0
	s_cmp_gt_u32 s34, 5
	s_waitcnt vmcnt(8)
	s_waitcnt lgkmcnt(0)
	s_barrier
	s_waitcnt lgkmcnt(0)
	v_mfma_f32_16x16x32_bf16 v[60:63], v[138:141], v[172:175], v[60:63]
	v_mfma_f32_16x16x32_bf16 v[56:59], v[148:151], v[172:175], v[56:59]
	v_mfma_f32_16x16x32_bf16 v[44:47], v[138:141], v[180:183], v[44:47]
	v_mfma_f32_16x16x32_bf16 v[40:43], v[148:151], v[180:183], v[40:43]
	v_mfma_f32_16x16x32_bf16 v[28:31], v[138:141], v[188:191], v[28:31]
	v_mfma_f32_16x16x32_bf16 v[24:27], v[148:151], v[188:191], v[24:27]
	v_mfma_f32_16x16x32_bf16 v[12:15], v[138:141], v[216:219], v[12:15]
	v_mfma_f32_16x16x32_bf16 v[8:11], v[148:151], v[216:219], v[8:11]
	v_mfma_f32_16x16x32_bf16 v[60:63], v[144:147], v[176:179], v[60:63]
	v_mfma_f32_16x16x32_bf16 v[56:59], v[152:155], v[176:179], v[56:59]
	v_mfma_f32_16x16x32_bf16 v[44:47], v[144:147], v[184:187], v[44:47]
	v_mfma_f32_16x16x32_bf16 v[40:43], v[152:155], v[184:187], v[40:43]
	v_mfma_f32_16x16x32_bf16 v[28:31], v[144:147], v[212:215], v[28:31]
	v_mfma_f32_16x16x32_bf16 v[24:27], v[152:155], v[212:215], v[24:27]
	v_mfma_f32_16x16x32_bf16 v[12:15], v[144:147], v[232:235], v[12:15]
	v_mfma_f32_16x16x32_bf16 v[8:11], v[152:155], v[232:235], v[8:11]
	v_mfma_f32_16x16x32_bf16 v[52:55], v[156:159], v[172:175], v[52:55]
	v_mfma_f32_16x16x32_bf16 v[48:51], v[164:167], v[172:175], v[48:51]
	v_mfma_f32_16x16x32_bf16 v[36:39], v[156:159], v[180:183], v[36:39]
	v_mfma_f32_16x16x32_bf16 v[32:35], v[164:167], v[180:183], v[32:35]
	v_mfma_f32_16x16x32_bf16 v[20:23], v[156:159], v[188:191], v[20:23]
	v_mfma_f32_16x16x32_bf16 v[16:19], v[164:167], v[188:191], v[16:19]
	v_mfma_f32_16x16x32_bf16 v[4:7], v[156:159], v[216:219], v[4:7]
	v_mfma_f32_16x16x32_bf16 v[0:3], v[164:167], v[216:219], v[0:3]
	v_mfma_f32_16x16x32_bf16 v[52:55], v[160:163], v[176:179], v[52:55]
	v_mfma_f32_16x16x32_bf16 v[48:51], v[168:171], v[176:179], v[48:51]
	v_mfma_f32_16x16x32_bf16 v[36:39], v[160:163], v[184:187], v[36:39]
	v_mfma_f32_16x16x32_bf16 v[32:35], v[168:171], v[184:187], v[32:35]
	v_mfma_f32_16x16x32_bf16 v[20:23], v[160:163], v[212:215], v[20:23]
	v_mfma_f32_16x16x32_bf16 v[16:19], v[168:171], v[212:215], v[16:19]
	v_mfma_f32_16x16x32_bf16 v[4:7], v[160:163], v[232:235], v[4:7]
	v_mfma_f32_16x16x32_bf16 v[0:3], v[168:171], v[232:235], v[0:3]
	s_barrier
	s_cbranch_scc0 .LBB0_348
	s_and_b64 vcc, exec, s[12:13]
	s_cbranch_vccz .LBB0_351
	s_barrier

; #define PG8_STAGE(bufoff, gbase, voff) do { _Pragma("unroll") for (int _i = 0; _i < 2; ++_i) \
;         __builtin_amdgcn_global_load_lds((const unsigned*)((const char*)(gbase) + (voff)[_i]), (PG8_LAS unsigned*)(lds + (bufoff) + ldsw + _i * 8192), 16, 0, 0); } while (0)
; #define PG8_LDA(dst, b, h) do { _Pragma("unroll") for (int m = 0; m < 4; ++m) _Pragma("unroll") for (int k = 0; k < 2; ++k) dst[m][k] = *(const PG8_LAS bf16x8*)(lds + PG8_SA(b, h) + aoff + m * 2048 + k * 1024); } while (0)
; #define PG8_LDB(dst, b, h) do { _Pragma("unroll") for (int n = 0; n < 2; ++n) _Pragma("unroll") for (int k = 0; k < 2; ++k) dst[n][k] = *(const PG8_LAS bf16x8*)(lds + PG8_SB(b, h) + boff + n * 2048 + k * 1024); } while (0)
; #define PG8_MMA(ai, bj, At, Bt) do { __builtin_amdgcn_s_setprio(1); _Pragma("unroll") for (int m = 0; m < 4; ++m) _Pragma("unroll") for (int n = 0; n < 2; ++n) _Pragma("unroll") for (int k = 0; k < 2; ++k) \
;         acc[ai][bj][m][n] = __builtin_amdgcn_mfma_f32_16x16x32_bf16(Bt[n][k], At[m][k], acc[ai][bj][m][n], 0, 0, 0); __builtin_amdgcn_s_setprio(0); } while (0)
; #define PG8_WAIT_V(n) asm volatile("s_waitcnt vmcnt(" #n ")" ::: "memory")
; #define PG8_WAIT_L(n) asm volatile("s_waitcnt lgkmcnt(" #n ")" ::: "memory")
; #define PG8_BAR __builtin_amdgcn_s_barrier()
; template <class Epi, class Sched, bool ALIGN_EPI = false, bool SP2 = false>
; __device__ __forceinline__ void gemm_phase(PG8_LAS unsigned char* lds, const Gemm g, const Sched& S, const Epi& E, const int tid) {
;     ...
;         for (int t = 0; t < nt; t += 2) {
;             const bool last = (t == nt - 2);
;             const char* a1 = cA + (size_t)(t + 1) * kstep;
;             const char* a2 = last ? nA : cA + (size_t)(t + 2) * kstep; const char* b2 = last ? nB : cB + (size_t)(t + 2) * kstep;
;             const char* a3 = a2 + kstep; const char* b3 = b2 + kstep;
;             if (last && has_next) S.a_ready(nxt);
;             if constexpr (SP2) {
;             PG8_LDB(B0, 0, 0); PG8_LDB(B1, 0, 1); PG8_SCHED; PG8_LDA(At, 0, 0); PG8_STAGE(PG8_SA(1, 1), a1 + hstep, voffA);
;             PG8_WAIT_V(8); PG8_WAIT_L(0); PG8_BAR; PG8_MMA(0, 0, At, B0); PG8_MMA(0, 1, At, B1); PG8_BAR; PG8_SCHED;
;             PG8_LDA(At, 0, 1); PG8_STAGE(PG8_SB(0, 0), b2, voffB); PG8_STAGE(PG8_SB(0, 1), b2 + hstep, voffB); PG8_STAGE(PG8_SA(0, 0), a2, voffA);
.LBB0_485:
	v_add_u32_e32 v140, 0x10000, v184
	v_add_u32_e32 v168, 0x14000, v184
	ds_read_b128 v[128:131], v140
	ds_read_b128 v[132:135], v140 offset:1024
	ds_read_b128 v[136:139], v140 offset:2048
	ds_read_b128 v[140:143], v140 offset:3072
	ds_read_b128 v[144:147], v168
	ds_read_b128 v[148:151], v168 offset:1024
	ds_read_b128 v[164:167], v168 offset:2048
	ds_read_b128 v[168:171], v168 offset:3072
	s_add_u32 s38, s8, 0xfffc0080
	s_addc_u32 s40, s9, -1
	s_add_i32 s41, 0, 0x10000
	s_cmp_eq_u32 s35, 12
	s_cselect_b32 s59, s0, s40
	s_cselect_b32 s58, s1, s38
	s_cselect_b32 s45, s2, s34
	s_cselect_b32 s44, s15, s17
	s_add_i32 s38, 0, 0x14000
	v_lshl_add_u64 v[190:191], s[8:9], 0, v[160:161]
	s_add_i32 m0, s23, 0xc000
	ds_read_b128 v[172:175], v185
	ds_read_b128 v[176:179], v185 offset:1024
	ds_read_b128 v[180:183], v185 offset:2048
	ds_read_b128 v[186:189], v185 offset:3072
	ds_read_b128 v[212:215], v185 offset:4096
	ds_read_b128 v[216:219], v185 offset:5120
	ds_read_b128 v[232:235], v185 offset:6144
	ds_read_b128 v[236:239], v185 offset:7168
	global_load_lds_dwordx4 v[190:191], off
	v_lshl_add_u64 v[190:191], s[8:9], 0, v[162:163]
	s_add_i32 m0, s23, 0xe000
	s_nop 0
	global_load_lds_dwordx4 v[190:191], off
	s_waitcnt vmcnt(8)
	s_waitcnt lgkmcnt(0)
	s_barrier
	s_waitcnt lgkmcnt(0)
	v_mfma_f32_16x16x32_bf16 v[124:127], v[128:131], v[172:175], v[124:127]
	v_mfma_f32_16x16x32_bf16 v[120:123], v[136:139], v[172:175], v[120:123]
	v_mfma_f32_16x16x32_bf16 v[108:111], v[128:131], v[180:183], v[108:111]
	v_mfma_f32_16x16x32_bf16 v[104:107], v[136:139], v[180:183], v[104:107]
	v_mfma_f32_16x16x32_bf16 v[92:95], v[128:131], v[212:215], v[92:95]
	v_mfma_f32_16x16x32_bf16 v[88:91], v[136:139], v[212:215], v[88:91]
	v_mfma_f32_16x16x32_bf16 v[76:79], v[128:131], v[232:235], v[76:79]
	v_mfma_f32_16x16x32_bf16 v[72:75], v[136:139], v[232:235], v[72:75]
	v_mfma_f32_16x16x32_bf16 v[124:127], v[132:135], v[176:179], v[124:127]
	v_mfma_f32_16x16x32_bf16 v[120:123], v[140:143], v[176:179], v[120:123]
	v_mfma_f32_16x16x32_bf16 v[108:111], v[132:135], v[186:189], v[108:111]
	v_mfma_f32_16x16x32_bf16 v[104:107], v[140:143], v[186:189], v[104:107]
	v_mfma_f32_16x16x32_bf16 v[92:95], v[132:135], v[216:219], v[92:95]
	v_mfma_f32_16x16x32_bf16 v[88:91], v[140:143], v[216:219], v[88:91]
	v_mfma_f32_16x16x32_bf16 v[76:79], v[132:135], v[236:239], v[76:79]
	v_mfma_f32_16x16x32_bf16 v[72:75], v[140:143], v[236:239], v[72:75]
	v_mfma_f32_16x16x32_bf16 v[116:119], v[144:147], v[172:175], v[116:119]
	v_mfma_f32_16x16x32_bf16 v[112:115], v[164:167], v[172:175], v[112:115]
	v_mfma_f32_16x16x32_bf16 v[100:103], v[144:147], v[180:183], v[100:103]
	v_mfma_f32_16x16x32_bf16 v[96:99], v[164:167], v[180:183], v[96:99]
	v_mfma_f32_16x16x32_bf16 v[84:87], v[144:147], v[212:215], v[84:87]
	v_mfma_f32_16x16x32_bf16 v[80:83], v[164:167], v[212:215], v[80:83]
	v_mfma_f32_16x16x32_bf16 v[68:71], v[144:147], v[232:235], v[68:71]
	v_mfma_f32_16x16x32_bf16 v[64:67], v[164:167], v[232:235], v[64:67]
	v_mfma_f32_16x16x32_bf16 v[116:119], v[148:151], v[176:179], v[116:119]
	v_mfma_f32_16x16x32_bf16 v[112:115], v[168:171], v[176:179], v[112:115]
	v_mfma_f32_16x16x32_bf16 v[100:103], v[148:151], v[186:189], v[100:103]
	v_mfma_f32_16x16x32_bf16 v[96:99], v[168:171], v[186:189], v[96:99]
	v_mfma_f32_16x16x32_bf16 v[84:87], v[148:151], v[216:219], v[84:87]
	v_mfma_f32_16x16x32_bf16 v[80:83], v[168:171], v[216:219], v[80:83]
	v_mfma_f32_16x16x32_bf16 v[68:71], v[148:151], v[236:239], v[68:71]
	v_mfma_f32_16x16x32_bf16 v[64:67], v[168:171], v[236:239], v[64:67]
	s_barrier
	s_add_i32 s40, s41, s83
	v_lshl_add_u64 v[190:191], s[44:45], 0, v[154:155]
	s_mov_b32 m0, s40
	ds_read_b128 v[172:175], v185 offset:16384
	ds_read_b128 v[176:179], v185 offset:17408
	ds_read_b128 v[180:183], v185 offset:18432
	ds_read_b128 v[186:189], v185 offset:19456
	ds_read_b128 v[212:215], v185 offset:20480
	ds_read_b128 v[216:219], v185 offset:21504
	ds_read_b128 v[232:235], v185 offset:22528
	ds_read_b128 v[236:239], v185 offset:23552
	global_load_lds_dwordx4 v[190:191], off
	s_add_i32 m0, s40, 0x2000
	s_add_u32 s40, s44, 0x40000
	v_lshl_add_u64 v[194:195], s[44:45], 0, v[158:159]
	s_addc_u32 s41, s45, 0
	s_add_i32 s38, s38, s83
	global_load_lds_dwordx4 v[194:195], off
	v_lshl_add_u64 v[196:197], s[40:41], 0, v[154:155]
	s_mov_b32 m0, s38
	v_lshl_add_u64 v[202:203], s[58:59], 0, v[156:157]
	global_load_lds_dwordx4 v[196:197], off
	v_lshl_add_u64 v[196:197], s[40:41], 0, v[158:159]
	s_add_i32 m0, s38, 0x2000
	s_nop 0
	global_load_lds_dwordx4 v[196:197], off
	v_lshl_add_u64 v[196:197], s[58:59], 0, v[152:153]
	s_mov_b32 m0, s23
	s_nop 0
	global_load_lds_dwordx4 v[196:197], off
	s_mov_b32 m0, s29
	s_nop 0
	global_load_lds_dwordx4 v[202:203], off
	s_waitcnt vmcnt(8)
	s_waitcnt lgkmcnt(0)
	s_barrier
; #define PG8_STAGE(bufoff, gbase, voff) do { _Pragma("unroll") for (int _i = 0; _i < 2; ++_i) \
;         __builtin_amdgcn_global_load_lds((const unsigned*)((const char*)(gbase) + (voff)[_i]), (PG8_LAS unsigned*)(lds + (bufoff) + ldsw + _i * 8192), 16, 0, 0); } while (0)
; #define PG8_LDA(dst, b, h) do { _Pragma("unroll") for (int m = 0; m < 4; ++m) _Pragma("unroll") for (int k = 0; k < 2; ++k) dst[m][k] = *(const PG8_LAS bf16x8*)(lds + PG8_SA(b, h) + aoff + m * 2048 + k * 1024); } while (0)
; #define PG8_LDB(dst, b, h) do { _Pragma("unroll") for (int n = 0; n < 2; ++n) _Pragma("unroll") for (int k = 0; k < 2; ++k) dst[n][k] = *(const PG8_LAS bf16x8*)(lds + PG8_SB(b, h) + boff + n * 2048 + k * 1024); } while (0)
; #define PG8_MMA(ai, bj, At, Bt) do { __builtin_amdgcn_s_setprio(1); _Pragma("unroll") for (int m = 0; m < 4; ++m) _Pragma("unroll") for (int n = 0; n < 2; ++n) _Pragma("unroll") for (int k = 0; k < 2; ++k) \
;         acc[ai][bj][m][n] = __builtin_amdgcn_mfma_f32_16x16x32_bf16(Bt[n][k], At[m][k], acc[ai][bj][m][n], 0, 0, 0); __builtin_amdgcn_s_setprio(0); } while (0)
; #define PG8_WAIT_V(n) asm volatile("s_waitcnt vmcnt(" #n ")" ::: "memory")
; #define PG8_WAIT_L(n) asm volatile("s_waitcnt lgkmcnt(" #n ")" ::: "memory")
; #define PG8_BAR __builtin_amdgcn_s_barrier()
; #define PG8_SCHED __builtin_amdgcn_sched_barrier(0)
; template <class Epi, class Sched, bool ALIGN_EPI = false, bool SP2 = false>
; __device__ __forceinline__ void gemm_phase(PG8_LAS unsigned char* lds, const Gemm g, const Sched& S, const Epi& E, const int tid) {
;     ...
;             PG8_WAIT_V(8); PG8_WAIT_L(0); PG8_BAR; PG8_MMA(1, 0, At, B0); PG8_MMA(1, 1, At, B1); PG8_BAR; PG8_SCHED;
;             PG8_LDB(B0, 1, 0); PG8_LDB(B1, 1, 1); PG8_SCHED; PG8_LDA(At, 1, 0); PG8_STAGE(PG8_SA(0, 1), a2 + hstep, voffA);
;             PG8_WAIT_V(8); PG8_WAIT_L(0); PG8_BAR; PG8_MMA(0, 0, At, B0); PG8_MMA(0, 1, At, B1); PG8_BAR; PG8_SCHED;
	s_waitcnt lgkmcnt(0)
	v_mfma_f32_16x16x32_bf16 v[60:63], v[128:131], v[172:175], v[60:63]
	v_mfma_f32_16x16x32_bf16 v[56:59], v[136:139], v[172:175], v[56:59]
	v_mfma_f32_16x16x32_bf16 v[44:47], v[128:131], v[180:183], v[44:47]
	v_mfma_f32_16x16x32_bf16 v[40:43], v[136:139], v[180:183], v[40:43]
	v_mfma_f32_16x16x32_bf16 v[28:31], v[128:131], v[212:215], v[28:31]
	v_mfma_f32_16x16x32_bf16 v[24:27], v[136:139], v[212:215], v[24:27]
	v_mfma_f32_16x16x32_bf16 v[12:15], v[128:131], v[232:235], v[12:15]
	v_mfma_f32_16x16x32_bf16 v[8:11], v[136:139], v[232:235], v[8:11]
	v_mfma_f32_16x16x32_bf16 v[60:63], v[132:135], v[176:179], v[60:63]
	v_mfma_f32_16x16x32_bf16 v[56:59], v[140:143], v[176:179], v[56:59]
	v_mfma_f32_16x16x32_bf16 v[44:47], v[132:135], v[186:189], v[44:47]
	v_mfma_f32_16x16x32_bf16 v[40:43], v[140:143], v[186:189], v[40:43]
	v_mfma_f32_16x16x32_bf16 v[28:31], v[132:135], v[216:219], v[28:31]
	v_mfma_f32_16x16x32_bf16 v[24:27], v[140:143], v[216:219], v[24:27]
	v_mfma_f32_16x16x32_bf16 v[12:15], v[132:135], v[236:239], v[12:15]
	v_mfma_f32_16x16x32_bf16 v[8:11], v[140:143], v[236:239], v[8:11]
	v_mfma_f32_16x16x32_bf16 v[52:55], v[144:147], v[172:175], v[52:55]
	v_mfma_f32_16x16x32_bf16 v[48:51], v[164:167], v[172:175], v[48:51]
	v_mfma_f32_16x16x32_bf16 v[36:39], v[144:147], v[180:183], v[36:39]
	v_mfma_f32_16x16x32_bf16 v[32:35], v[164:167], v[180:183], v[32:35]
	v_mfma_f32_16x16x32_bf16 v[20:23], v[144:147], v[212:215], v[20:23]
	v_mfma_f32_16x16x32_bf16 v[16:19], v[164:167], v[212:215], v[16:19]
	v_mfma_f32_16x16x32_bf16 v[4:7], v[144:147], v[232:235], v[4:7]
	v_mfma_f32_16x16x32_bf16 v[0:3], v[164:167], v[232:235], v[0:3]
	v_mfma_f32_16x16x32_bf16 v[52:55], v[148:151], v[176:179], v[52:55]
	v_mfma_f32_16x16x32_bf16 v[48:51], v[168:171], v[176:179], v[48:51]
	v_mfma_f32_16x16x32_bf16 v[36:39], v[148:151], v[186:189], v[36:39]
	v_mfma_f32_16x16x32_bf16 v[32:35], v[168:171], v[186:189], v[32:35]
	v_mfma_f32_16x16x32_bf16 v[20:23], v[148:151], v[216:219], v[20:23]
	v_mfma_f32_16x16x32_bf16 v[16:19], v[168:171], v[216:219], v[16:19]
	v_mfma_f32_16x16x32_bf16 v[4:7], v[148:151], v[236:239], v[4:7]
	v_mfma_f32_16x16x32_bf16 v[0:3], v[168:171], v[236:239], v[0:3]
	s_barrier
	s_add_i32 s38, 0, 0x18000
	s_add_i32 s46, 0, 0x1c000
	v_add_u32_e32 v140, s38, v184
	v_add_u32_e32 v168, s46, v184
	ds_read_b128 v[128:131], v140
	ds_read_b128 v[132:135], v140 offset:1024
	ds_read_b128 v[136:139], v140 offset:2048
	ds_read_b128 v[140:143], v140 offset:3072
	ds_read_b128 v[144:147], v168
	ds_read_b128 v[148:151], v168 offset:1024
	ds_read_b128 v[164:167], v168 offset:2048
	ds_read_b128 v[168:171], v168 offset:3072
	s_add_u32 s40, s58, 0x40000
	s_addc_u32 s41, s59, 0
	s_mov_b32 m0, s84
	v_lshl_add_u64 v[204:205], s[40:41], 0, v[152:153]
	ds_read_b128 v[172:175], v185 offset:32768
	ds_read_b128 v[176:179], v185 offset:33792
	ds_read_b128 v[180:183], v185 offset:34816
	ds_read_b128 v[186:189], v185 offset:35840
	ds_read_b128 v[212:215], v185 offset:36864
	ds_read_b128 v[216:219], v185 offset:37888
	ds_read_b128 v[232:235], v185 offset:38912
	ds_read_b128 v[236:239], v185 offset:39936
	global_load_lds_dwordx4 v[204:205], off
	v_lshl_add_u64 v[204:205], s[40:41], 0, v[156:157]
	s_mov_b32 m0, s85
	s_nop 0
	global_load_lds_dwordx4 v[204:205], off
	s_waitcnt vmcnt(8)
	s_waitcnt lgkmcnt(0)
	s_barrier
	s_waitcnt lgkmcnt(0)
	v_mfma_f32_16x16x32_bf16 v[124:127], v[128:131], v[172:175], v[124:127]
	v_mfma_f32_16x16x32_bf16 v[120:123], v[136:139], v[172:175], v[120:123]
	v_mfma_f32_16x16x32_bf16 v[108:111], v[128:131], v[180:183], v[108:111]
	v_mfma_f32_16x16x32_bf16 v[104:107], v[136:139], v[180:183], v[104:107]
	v_mfma_f32_16x16x32_bf16 v[92:95], v[128:131], v[212:215], v[92:95]
	v_mfma_f32_16x16x32_bf16 v[88:91], v[136:139], v[212:215], v[88:91]
	v_mfma_f32_16x16x32_bf16 v[76:79], v[128:131], v[232:235], v[76:79]
	v_mfma_f32_16x16x32_bf16 v[72:75], v[136:139], v[232:235], v[72:75]
	v_mfma_f32_16x16x32_bf16 v[124:127], v[132:135], v[176:179], v[124:127]
	v_mfma_f32_16x16x32_bf16 v[120:123], v[140:143], v[176:179], v[120:123]
	v_mfma_f32_16x16x32_bf16 v[108:111], v[132:135], v[186:189], v[108:111]
	v_mfma_f32_16x16x32_bf16 v[104:107], v[140:143], v[186:189], v[104:107]
	v_mfma_f32_16x16x32_bf16 v[92:95], v[132:135], v[216:219], v[92:95]
	v_mfma_f32_16x16x32_bf16 v[88:91], v[140:143], v[216:219], v[88:91]
	v_mfma_f32_16x16x32_bf16 v[76:79], v[132:135], v[236:239], v[76:79]
	v_mfma_f32_16x16x32_bf16 v[72:75], v[140:143], v[236:239], v[72:75]
	v_mfma_f32_16x16x32_bf16 v[116:119], v[144:147], v[172:175], v[116:119]
	v_mfma_f32_16x16x32_bf16 v[112:115], v[164:167], v[172:175], v[112:115]
	v_mfma_f32_16x16x32_bf16 v[100:103], v[144:147], v[180:183], v[100:103]
	v_mfma_f32_16x16x32_bf16 v[96:99], v[164:167], v[180:183], v[96:99]
	v_mfma_f32_16x16x32_bf16 v[84:87], v[144:147], v[212:215], v[84:87]
	v_mfma_f32_16x16x32_bf16 v[80:83], v[164:167], v[212:215], v[80:83]
	v_mfma_f32_16x16x32_bf16 v[68:71], v[144:147], v[232:235], v[68:71]
	v_mfma_f32_16x16x32_bf16 v[64:67], v[164:167], v[232:235], v[64:67]
	v_mfma_f32_16x16x32_bf16 v[116:119], v[148:151], v[176:179], v[116:119]
	v_mfma_f32_16x16x32_bf16 v[112:115], v[168:171], v[176:179], v[112:115]
	v_mfma_f32_16x16x32_bf16 v[100:103], v[148:151], v[186:189], v[100:103]
	v_mfma_f32_16x16x32_bf16 v[96:99], v[168:171], v[186:189], v[96:99]
	v_mfma_f32_16x16x32_bf16 v[84:87], v[148:151], v[216:219], v[84:87]
	v_mfma_f32_16x16x32_bf16 v[80:83], v[168:171], v[216:219], v[80:83]
	v_mfma_f32_16x16x32_bf16 v[68:71], v[148:151], v[236:239], v[68:71]
	v_mfma_f32_16x16x32_bf16 v[64:67], v[168:171], v[236:239], v[64:67]
	s_barrier
; #define PG8_STAGE(bufoff, gbase, voff) do { _Pragma("unroll") for (int _i = 0; _i < 2; ++_i) \
;         __builtin_amdgcn_global_load_lds((const unsigned*)((const char*)(gbase) + (voff)[_i]), (PG8_LAS unsigned*)(lds + (bufoff) + ldsw + _i * 8192), 16, 0, 0); } while (0)
; #define PG8_LDA(dst, b, h) do { _Pragma("unroll") for (int m = 0; m < 4; ++m) _Pragma("unroll") for (int k = 0; k < 2; ++k) dst[m][k] = *(const PG8_LAS bf16x8*)(lds + PG8_SA(b, h) + aoff + m * 2048 + k * 1024); } while (0)
; #define PG8_MMA(ai, bj, At, Bt) do { __builtin_amdgcn_s_setprio(1); _Pragma("unroll") for (int m = 0; m < 4; ++m) _Pragma("unroll") for (int n = 0; n < 2; ++n) _Pragma("unroll") for (int k = 0; k < 2; ++k) \
;         acc[ai][bj][m][n] = __builtin_amdgcn_mfma_f32_16x16x32_bf16(Bt[n][k], At[m][k], acc[ai][bj][m][n], 0, 0, 0); __builtin_amdgcn_s_setprio(0); } while (0)
; #define PG8_WAIT_V(n) asm volatile("s_waitcnt vmcnt(" #n ")" ::: "memory")
; #define PG8_WAIT_L(n) asm volatile("s_waitcnt lgkmcnt(" #n ")" ::: "memory")
; #define PG8_BAR __builtin_amdgcn_s_barrier()
; #define PG8_SCHED __builtin_amdgcn_sched_barrier(0)
; template <class Epi, class Sched, bool ALIGN_EPI = false, bool SP2 = false>
; __device__ __forceinline__ void gemm_phase(PG8_LAS unsigned char* lds, const Gemm g, const Sched& S, const Epi& E, const int tid) {
;     ...
;         for (int t = 0; t < nt; t += 2) {
;     ...
;             PG8_LDA(At, 1, 1); PG8_STAGE(PG8_SB(1, 0), b3, voffB); PG8_STAGE(PG8_SB(1, 1), b3 + hstep, voffB); PG8_STAGE(PG8_SA(1, 0), a3, voffA);
;             PG8_WAIT_V(8); PG8_WAIT_L(0); PG8_BAR; PG8_MMA(1, 0, At, B0); PG8_MMA(1, 1, At, B1); PG8_BAR; PG8_SCHED;
;     ...
;         if constexpr (ALIGN_EPI) { if (wr == 0) PG8_BAR; }
	s_add_i32 s38, s38, s83
	v_lshl_add_u64 v[190:191], v[190:191], 0, s[36:37]
	s_mov_b32 m0, s38
	ds_read_b128 v[172:175], v185 offset:49152
	ds_read_b128 v[176:179], v185 offset:50176
	ds_read_b128 v[180:183], v185 offset:51200
	ds_read_b128 v[186:189], v185 offset:52224
	ds_read_b128 v[212:215], v185 offset:53248
	ds_read_b128 v[216:219], v185 offset:54272
	ds_read_b128 v[232:235], v185 offset:55296
	ds_read_b128 v[236:239], v185 offset:56320
	global_load_lds_dwordx4 v[190:191], off
	s_add_i32 m0, s38, 0x2000
	s_add_u32 s40, s44, 0x40080
	v_lshl_add_u64 v[190:191], v[194:195], 0, s[36:37]
	s_addc_u32 s41, s45, 0
	s_add_i32 s38, s46, s83
	global_load_lds_dwordx4 v[190:191], off
	v_lshl_add_u64 v[190:191], s[40:41], 0, v[154:155]
	s_mov_b32 m0, s38
	s_nop 0
	global_load_lds_dwordx4 v[190:191], off
	v_lshl_add_u64 v[190:191], s[40:41], 0, v[158:159]
	s_add_i32 m0, s38, 0x2000
	s_nop 0
	global_load_lds_dwordx4 v[190:191], off
	v_lshl_add_u64 v[190:191], v[196:197], 0, s[36:37]
	s_mov_b32 m0, s86
	s_nop 0
	global_load_lds_dwordx4 v[190:191], off
	v_lshl_add_u64 v[190:191], v[202:203], 0, s[36:37]
	s_mov_b32 m0, s87
	s_nop 0
	global_load_lds_dwordx4 v[190:191], off
	s_add_i32 s35, s35, 2
	s_add_u32 s8, s8, 0x100
	s_addc_u32 s9, s9, 0
	s_add_u32 s17, s17, 0x100
	s_addc_u32 s34, s34, 0
	s_cmp_gt_u32 s35, 13
	s_waitcnt vmcnt(8)
	s_waitcnt lgkmcnt(0)
	s_barrier
	s_waitcnt lgkmcnt(0)
	v_mfma_f32_16x16x32_bf16 v[60:63], v[128:131], v[172:175], v[60:63]
	v_mfma_f32_16x16x32_bf16 v[56:59], v[136:139], v[172:175], v[56:59]
	v_mfma_f32_16x16x32_bf16 v[44:47], v[128:131], v[180:183], v[44:47]
	v_mfma_f32_16x16x32_bf16 v[40:43], v[136:139], v[180:183], v[40:43]
	v_mfma_f32_16x16x32_bf16 v[28:31], v[128:131], v[212:215], v[28:31]
	v_mfma_f32_16x16x32_bf16 v[24:27], v[136:139], v[212:215], v[24:27]
	v_mfma_f32_16x16x32_bf16 v[12:15], v[128:131], v[232:235], v[12:15]
	v_mfma_f32_16x16x32_bf16 v[8:11], v[136:139], v[232:235], v[8:11]
	v_mfma_f32_16x16x32_bf16 v[60:63], v[132:135], v[176:179], v[60:63]
	v_mfma_f32_16x16x32_bf16 v[56:59], v[140:143], v[176:179], v[56:59]
	v_mfma_f32_16x16x32_bf16 v[44:47], v[132:135], v[186:189], v[44:47]
	v_mfma_f32_16x16x32_bf16 v[40:43], v[140:143], v[186:189], v[40:43]
	v_mfma_f32_16x16x32_bf16 v[28:31], v[132:135], v[216:219], v[28:31]
	v_mfma_f32_16x16x32_bf16 v[24:27], v[140:143], v[216:219], v[24:27]
	v_mfma_f32_16x16x32_bf16 v[12:15], v[132:135], v[236:239], v[12:15]
	v_mfma_f32_16x16x32_bf16 v[8:11], v[140:143], v[236:239], v[8:11]
	v_mfma_f32_16x16x32_bf16 v[52:55], v[144:147], v[172:175], v[52:55]
	v_mfma_f32_16x16x32_bf16 v[48:51], v[164:167], v[172:175], v[48:51]
	v_mfma_f32_16x16x32_bf16 v[36:39], v[144:147], v[180:183], v[36:39]
	v_mfma_f32_16x16x32_bf16 v[32:35], v[164:167], v[180:183], v[32:35]
	v_mfma_f32_16x16x32_bf16 v[20:23], v[144:147], v[212:215], v[20:23]
	v_mfma_f32_16x16x32_bf16 v[16:19], v[164:167], v[212:215], v[16:19]
	v_mfma_f32_16x16x32_bf16 v[4:7], v[144:147], v[232:235], v[4:7]
	v_mfma_f32_16x16x32_bf16 v[0:3], v[164:167], v[232:235], v[0:3]
	v_mfma_f32_16x16x32_bf16 v[52:55], v[148:151], v[176:179], v[52:55]
	v_mfma_f32_16x16x32_bf16 v[48:51], v[168:171], v[176:179], v[48:51]
	v_mfma_f32_16x16x32_bf16 v[36:39], v[148:151], v[186:189], v[36:39]
	v_mfma_f32_16x16x32_bf16 v[32:35], v[168:171], v[186:189], v[32:35]
	v_mfma_f32_16x16x32_bf16 v[20:23], v[148:151], v[216:219], v[20:23]
	v_mfma_f32_16x16x32_bf16 v[16:19], v[168:171], v[216:219], v[16:19]
	v_mfma_f32_16x16x32_bf16 v[4:7], v[148:151], v[236:239], v[4:7]
	v_mfma_f32_16x16x32_bf16 v[0:3], v[168:171], v[236:239], v[0:3]
	s_barrier
	s_cbranch_scc0 .LBB0_485
	s_and_b64 vcc, exec, s[12:13]
	s_cbranch_vccz .LBB0_488
	s_barrier
